# v064 + MFMA blocks of all K-loops run at priority 3 instead of 1
# baseline (speedup 1.0000x reference)
; #define PG8_STAGE(bufoff, gbase, voff) do { _Pragma("unroll") for (int _i = 0; _i < 2; ++_i) \
;         __builtin_amdgcn_global_load_lds((const unsigned*)((const char*)(gbase) + (voff)[_i]), (PG8_LAS unsigned*)(lds + (bufoff) + ldsw + _i * 8192), 16, 0, 0); } while (0)
; #define PG8_LDA(dst, b, h) do { _Pragma("unroll") for (int m = 0; m < 4; ++m) _Pragma("unroll") for (int k = 0; k < 2; ++k) dst[m][k] = *(const PG8_LAS bf16x8*)(lds + PG8_SA(b, h) + aoff + m * 2048 + k * 1024); } while (0)
; #define PG8_LDB(dst, b, h) do { _Pragma("unroll") for (int n = 0; n < 2; ++n) _Pragma("unroll") for (int k = 0; k < 2; ++k) dst[n][k] = *(const PG8_LAS bf16x8*)(lds + PG8_SB(b, h) + boff + n * 2048 + k * 1024); } while (0)
; #define PG8_WAIT_V(n) asm volatile("s_waitcnt vmcnt(" #n ")" ::: "memory")
; #define PG8_WAIT_L(n) asm volatile("s_waitcnt lgkmcnt(" #n ")" ::: "memory")
; #define PG8_BAR __builtin_amdgcn_s_barrier()
; template <class Epi, class Sched, bool ALIGN_EPI = false, bool SP2 = false, bool PAIR_ACC = false>
; __device__ __forceinline__ void gemm_phase(PG8_LAS unsigned char* lds, const Gemm g, const Sched& S, const Epi& E) {
;     ...
;         const bool has_next = S.next(ui + 1, nxt);
;         const char* nA = has_next ? (const char*)g.A + (size_t)nxt.pm * tstep + (size_t)(nxt.pn / g.a_div) * g.a_sel : cA; const char* nB = has_next ? (const char*)g.Bt + (size_t)nxt.pn * tstep : cB;
;         for (int t = 0; t < nt; t += 2) {
;             const bool last = (t == nt - 2);
;             const char* a1 = cA + (size_t)(t + 1) * kstep;
;             const char* a2 = last ? nA : cA + (size_t)(t + 2) * kstep; const char* b2 = last ? nB : cB + (size_t)(t + 2) * kstep;
;             const char* a3 = a2 + kstep; const char* b3 = b2 + kstep;
;             if (last && has_next) S.a_ready(nxt);
;             if constexpr (SP2) {
;             PG8_LDB(B0, 0, 0); PG8_LDB(B1, 0, 1); PG8_SCHED; PG8_LDA(At, 0, 0); PG8_STAGE(PG8_SA(1, 1), a1 + hstep, voffA);
;             PG8_WAIT_V(8); PG8_WAIT_L(0); PG8_BAR; PG8_MMA(0, 0, At, B0); PG8_MMA(0, 1, At, B1); PG8_BAR; PG8_SCHED;
;             PG8_LDA(At, 0, 1); PG8_STAGE(PG8_SB(0, 0), b2, voffB); PG8_STAGE(PG8_SB(0, 1), b2 + hstep, voffB); PG8_STAGE(PG8_SA(0, 0), a2, voffA);
;             PG8_WAIT_V(8); PG8_WAIT_L(0); PG8_BAR; PG8_MMA(1, 0, At, B0); PG8_MMA(1, 1, At, B1); PG8_BAR; PG8_SCHED;
.LBB0_189:
	s_mov_b32 s80, s21
	s_ashr_i32 s81, s21, 31
	s_lshl_b64 s[18:19], s[80:81], 19
	s_add_u32 s84, s23, s18
	s_addc_u32 s85, s61, s19
	s_mov_b32 s78, s17
	s_and_b64 s[18:19], s[82:83], exec
	s_cselect_b32 s13, s85, s11
	s_cselect_b32 s17, s84, s10
	s_ashr_i32 s79, s78, 31
	s_lshl_b64 s[18:19], s[78:79], 19
	s_add_u32 s86, s63, s18
	s_addc_u32 s87, s65, s19
	s_and_b64 s[18:19], s[82:83], exec
	s_cselect_b32 s20, s87, s15
	s_cselect_b32 s21, s86, s14
	s_add_u32 s10, s10, 0x40080
	s_addc_u32 s11, s11, 0
	s_add_u32 s30, s14, 0x100
	s_addc_u32 s38, s15, 0
	s_mov_b32 s39, -2
	s_waitcnt lgkmcnt(0)
	ds_read_b128 v[130:133], v196
	ds_read_b128 v[134:137], v196 offset:1024
	ds_read_b128 v[138:141], v196 offset:2048
	ds_read_b128 v[142:145], v196 offset:3072
	ds_read_b128 v[178:181], v197
	ds_read_b128 v[182:185], v197 offset:1024
	ds_read_b128 v[186:189], v197 offset:2048
	ds_read_b128 v[190:193], v197 offset:3072
	s_add_u32 s14, s10, 0xfffc0080
	s_addc_u32 s15, s11, -1
	s_cmp_eq_u32 s39, 12
	s_cselect_b32 s19, s13, s15
	s_cselect_b32 s18, s17, s14
	s_cselect_b32 s15, s20, s38
	s_cselect_b32 s14, s21, s30
	v_lshl_add_u64 v[194:195], s[10:11], 0, v[170:171]
	s_add_i32 m0, s69, 0xc000
	ds_read_b128 v[206:209], v198
	ds_read_b128 v[210:213], v198 offset:1024
	ds_read_b128 v[214:217], v198 offset:2048
	ds_read_b128 v[218:221], v198 offset:3072
	ds_read_b128 v[222:225], v198 offset:4096
	ds_read_b128 v[226:229], v198 offset:5120
	ds_read_b128 v[230:233], v198 offset:6144
	ds_read_b128 v[234:237], v198 offset:7168
	global_load_lds_dwordx4 v[194:195], off
	v_lshl_add_u64 v[194:195], s[10:11], 0, v[174:175]
	s_add_i32 m0, s69, 0xe000
	s_nop 0
	global_load_lds_dwordx4 v[194:195], off
	s_waitcnt vmcnt(8)
	s_waitcnt lgkmcnt(0)
	s_setprio 3
	s_barrier
	v_mfma_f32_16x16x32_bf16 v[126:129], v[130:133], v[206:209], 0
	v_mfma_f32_16x16x32_bf16 v[122:125], v[138:141], v[206:209], 0
	v_mfma_f32_16x16x32_bf16 v[110:113], v[130:133], v[214:217], 0
	v_mfma_f32_16x16x32_bf16 v[106:109], v[138:141], v[214:217], 0
	v_mfma_f32_16x16x32_bf16 v[94:97], v[130:133], v[222:225], 0
	v_mfma_f32_16x16x32_bf16 v[90:93], v[138:141], v[222:225], 0
	v_mfma_f32_16x16x32_bf16 v[78:81], v[130:133], v[230:233], 0
	v_mfma_f32_16x16x32_bf16 v[74:77], v[138:141], v[230:233], 0
	v_mfma_f32_16x16x32_bf16 v[126:129], v[134:137], v[210:213], v[126:129]
	v_mfma_f32_16x16x32_bf16 v[122:125], v[142:145], v[210:213], v[122:125]
	v_mfma_f32_16x16x32_bf16 v[110:113], v[134:137], v[218:221], v[110:113]
	v_mfma_f32_16x16x32_bf16 v[106:109], v[142:145], v[218:221], v[106:109]
	v_mfma_f32_16x16x32_bf16 v[94:97], v[134:137], v[226:229], v[94:97]
	v_mfma_f32_16x16x32_bf16 v[90:93], v[142:145], v[226:229], v[90:93]
	v_mfma_f32_16x16x32_bf16 v[78:81], v[134:137], v[234:237], v[78:81]
	v_mfma_f32_16x16x32_bf16 v[74:77], v[142:145], v[234:237], v[74:77]
	v_mfma_f32_16x16x32_bf16 v[118:121], v[178:181], v[206:209], 0
	v_mfma_f32_16x16x32_bf16 v[114:117], v[186:189], v[206:209], 0
	v_mfma_f32_16x16x32_bf16 v[102:105], v[178:181], v[214:217], 0
	v_mfma_f32_16x16x32_bf16 v[98:101], v[186:189], v[214:217], 0
	v_mfma_f32_16x16x32_bf16 v[86:89], v[178:181], v[222:225], 0
	v_mfma_f32_16x16x32_bf16 v[82:85], v[186:189], v[222:225], 0
	v_mfma_f32_16x16x32_bf16 v[70:73], v[178:181], v[230:233], 0
	v_mfma_f32_16x16x32_bf16 v[66:69], v[186:189], v[230:233], 0
	v_mfma_f32_16x16x32_bf16 v[118:121], v[182:185], v[210:213], v[118:121]
	v_mfma_f32_16x16x32_bf16 v[114:117], v[190:193], v[210:213], v[114:117]
	v_mfma_f32_16x16x32_bf16 v[102:105], v[182:185], v[218:221], v[102:105]
	v_mfma_f32_16x16x32_bf16 v[98:101], v[190:193], v[218:221], v[98:101]
	v_mfma_f32_16x16x32_bf16 v[86:89], v[182:185], v[226:229], v[86:89]
	v_mfma_f32_16x16x32_bf16 v[82:85], v[190:193], v[226:229], v[82:85]
	v_mfma_f32_16x16x32_bf16 v[70:73], v[182:185], v[234:237], v[70:73]
	v_mfma_f32_16x16x32_bf16 v[66:69], v[190:193], v[234:237], v[66:69]
	s_barrier
	s_setprio 0
	s_add_i32 s40, s25, s67
	v_lshl_add_u64 v[194:195], s[14:15], 0, v[148:149]
	s_mov_b32 m0, s40
	ds_read_b128 v[206:209], v198 offset:16384
	ds_read_b128 v[210:213], v198 offset:17408
	ds_read_b128 v[214:217], v198 offset:18432
	ds_read_b128 v[218:221], v198 offset:19456
	ds_read_b128 v[222:225], v198 offset:20480
	ds_read_b128 v[226:229], v198 offset:21504
	ds_read_b128 v[230:233], v198 offset:22528
	ds_read_b128 v[234:237], v198 offset:23552
	global_load_lds_dwordx4 v[194:195], off
	s_add_i32 m0, s40, 0x2000
	s_add_u32 s40, s14, 0x40000
	v_lshl_add_u64 v[238:239], s[14:15], 0, v[152:153]
	s_addc_u32 s41, s15, 0
	s_add_i32 s79, s35, s67
	global_load_lds_dwordx4 v[238:239], off
	v_lshl_add_u64 v[240:241], s[40:41], 0, v[148:149]
	s_mov_b32 m0, s79
	v_lshl_add_u64 v[242:243], s[18:19], 0, v[150:151]
	global_load_lds_dwordx4 v[240:241], off
	v_lshl_add_u64 v[240:241], s[40:41], 0, v[152:153]
	s_add_i32 m0, s79, 0x2000
	s_nop 0
	global_load_lds_dwordx4 v[240:241], off
	v_lshl_add_u64 v[240:241], s[18:19], 0, v[146:147]
	s_mov_b32 m0, s69
	s_nop 0
	global_load_lds_dwordx4 v[240:241], off
	s_mov_b32 m0, s71
	s_nop 0
	global_load_lds_dwordx4 v[242:243], off
	s_waitcnt vmcnt(8)
	s_waitcnt lgkmcnt(0)
	s_setprio 3
	s_barrier
; #define PG8_STAGE(bufoff, gbase, voff) do { _Pragma("unroll") for (int _i = 0; _i < 2; ++_i) \
;         __builtin_amdgcn_global_load_lds((const unsigned*)((const char*)(gbase) + (voff)[_i]), (PG8_LAS unsigned*)(lds + (bufoff) + ldsw + _i * 8192), 16, 0, 0); } while (0)
; #define PG8_LDA(dst, b, h) do { _Pragma("unroll") for (int m = 0; m < 4; ++m) _Pragma("unroll") for (int k = 0; k < 2; ++k) dst[m][k] = *(const PG8_LAS bf16x8*)(lds + PG8_SA(b, h) + aoff + m * 2048 + k * 1024); } while (0)
; #define PG8_LDB(dst, b, h) do { _Pragma("unroll") for (int n = 0; n < 2; ++n) _Pragma("unroll") for (int k = 0; k < 2; ++k) dst[n][k] = *(const PG8_LAS bf16x8*)(lds + PG8_SB(b, h) + boff + n * 2048 + k * 1024); } while (0)
; #define PG8_MMA(ai, bj, At, Bt) do { __builtin_amdgcn_s_setprio(1); _Pragma("unroll") for (int m = 0; m < 4; ++m) _Pragma("unroll") for (int n = 0; n < 2; ++n) _Pragma("unroll") for (int k = 0; k < 2; ++k) \
;         acc[ai][bj][m][n] = __builtin_amdgcn_mfma_f32_16x16x32_bf16(Bt[n][k], At[m][k], acc[ai][bj][m][n], 0, 0, 0); __builtin_amdgcn_s_setprio(0); } while (0)
; #define PG8_WAIT_V(n) asm volatile("s_waitcnt vmcnt(" #n ")" ::: "memory")
; #define PG8_BAR __builtin_amdgcn_s_barrier()
; template <class Epi, class Sched, bool ALIGN_EPI = false, bool SP2 = false, bool PAIR_ACC = false>
; __device__ __forceinline__ void gemm_phase(PG8_LAS unsigned char* lds, const Gemm g, const Sched& S, const Epi& E) {
;     ...
;         for (int t = 0; t < nt; t += 2) {
;             const bool last = (t == nt - 2);
;             const char* a1 = cA + (size_t)(t + 1) * kstep;
;             const char* a2 = last ? nA : cA + (size_t)(t + 2) * kstep; const char* b2 = last ? nB : cB + (size_t)(t + 2) * kstep;
;             const char* a3 = a2 + kstep; const char* b3 = b2 + kstep;
;             if (last && has_next) S.a_ready(nxt);
;             if constexpr (SP2) {
;             PG8_LDB(B0, 0, 0); PG8_LDB(B1, 0, 1); PG8_SCHED; PG8_LDA(At, 0, 0); PG8_STAGE(PG8_SA(1, 1), a1 + hstep, voffA);
;             PG8_WAIT_V(8); PG8_WAIT_L(0); PG8_BAR; PG8_MMA(0, 0, At, B0); PG8_MMA(0, 1, At, B1); PG8_BAR; PG8_SCHED;
;             PG8_LDA(At, 0, 1); PG8_STAGE(PG8_SB(0, 0), b2, voffB); PG8_STAGE(PG8_SB(0, 1), b2 + hstep, voffB); PG8_STAGE(PG8_SA(0, 0), a2, voffA);
;             PG8_WAIT_V(8); PG8_WAIT_L(0); PG8_BAR; PG8_MMA(1, 0, At, B0); PG8_MMA(1, 1, At, B1); PG8_BAR; PG8_SCHED;
	v_mfma_f32_16x16x32_bf16 v[62:65], v[130:133], v[206:209], 0
	v_mfma_f32_16x16x32_bf16 v[58:61], v[138:141], v[206:209], 0
	v_mfma_f32_16x16x32_bf16 v[46:49], v[130:133], v[214:217], 0
	v_mfma_f32_16x16x32_bf16 v[42:45], v[138:141], v[214:217], 0
	v_mfma_f32_16x16x32_bf16 v[30:33], v[130:133], v[222:225], 0
	v_mfma_f32_16x16x32_bf16 v[26:29], v[138:141], v[222:225], 0
	v_mfma_f32_16x16x32_bf16 v[14:17], v[130:133], v[230:233], 0
	v_mfma_f32_16x16x32_bf16 v[10:13], v[138:141], v[230:233], 0
	v_mfma_f32_16x16x32_bf16 v[62:65], v[134:137], v[210:213], v[62:65]
	v_mfma_f32_16x16x32_bf16 v[58:61], v[142:145], v[210:213], v[58:61]
	v_mfma_f32_16x16x32_bf16 v[46:49], v[134:137], v[218:221], v[46:49]
	v_mfma_f32_16x16x32_bf16 v[42:45], v[142:145], v[218:221], v[42:45]
	v_mfma_f32_16x16x32_bf16 v[30:33], v[134:137], v[226:229], v[30:33]
	v_mfma_f32_16x16x32_bf16 v[26:29], v[142:145], v[226:229], v[26:29]
	v_mfma_f32_16x16x32_bf16 v[14:17], v[134:137], v[234:237], v[14:17]
	v_mfma_f32_16x16x32_bf16 v[10:13], v[142:145], v[234:237], v[10:13]
	v_mfma_f32_16x16x32_bf16 v[54:57], v[178:181], v[206:209], 0
	v_mfma_f32_16x16x32_bf16 v[50:53], v[186:189], v[206:209], 0
	v_mfma_f32_16x16x32_bf16 v[38:41], v[178:181], v[214:217], 0
	v_mfma_f32_16x16x32_bf16 v[34:37], v[186:189], v[214:217], 0
	v_mfma_f32_16x16x32_bf16 v[22:25], v[178:181], v[222:225], 0
	v_mfma_f32_16x16x32_bf16 v[18:21], v[186:189], v[222:225], 0
	v_mfma_f32_16x16x32_bf16 v[6:9], v[178:181], v[230:233], 0
	v_mfma_f32_16x16x32_bf16 v[2:5], v[186:189], v[230:233], 0
	v_mfma_f32_16x16x32_bf16 v[54:57], v[182:185], v[210:213], v[54:57]
	v_mfma_f32_16x16x32_bf16 v[50:53], v[190:193], v[210:213], v[50:53]
	v_mfma_f32_16x16x32_bf16 v[38:41], v[182:185], v[218:221], v[38:41]
	v_mfma_f32_16x16x32_bf16 v[34:37], v[190:193], v[218:221], v[34:37]
	v_mfma_f32_16x16x32_bf16 v[22:25], v[182:185], v[226:229], v[22:25]
	v_mfma_f32_16x16x32_bf16 v[18:21], v[190:193], v[226:229], v[18:21]
	v_mfma_f32_16x16x32_bf16 v[6:9], v[182:185], v[234:237], v[6:9]
	v_mfma_f32_16x16x32_bf16 v[2:5], v[190:193], v[234:237], v[2:5]
	s_barrier
	s_setprio 0
	s_branch .Lpeel_mid_190
.LBB0_190:
	ds_read_b128 v[130:133], v196
	ds_read_b128 v[134:137], v196 offset:1024
	ds_read_b128 v[138:141], v196 offset:2048
	ds_read_b128 v[142:145], v196 offset:3072
	ds_read_b128 v[178:181], v197
	ds_read_b128 v[182:185], v197 offset:1024
	ds_read_b128 v[186:189], v197 offset:2048
	ds_read_b128 v[190:193], v197 offset:3072
	s_add_u32 s14, s10, 0xfffc0080
	s_addc_u32 s15, s11, -1
	s_cmp_eq_u32 s39, 12
	s_cselect_b32 s19, s13, s15
	s_cselect_b32 s18, s17, s14
	s_cselect_b32 s15, s20, s38
	s_cselect_b32 s14, s21, s30
	v_lshl_add_u64 v[194:195], s[10:11], 0, v[170:171]
	s_add_i32 m0, s69, 0xc000
	ds_read_b128 v[206:209], v198
	ds_read_b128 v[210:213], v198 offset:1024
	ds_read_b128 v[214:217], v198 offset:2048
	ds_read_b128 v[218:221], v198 offset:3072
	ds_read_b128 v[222:225], v198 offset:4096
	ds_read_b128 v[226:229], v198 offset:5120
	ds_read_b128 v[230:233], v198 offset:6144
	ds_read_b128 v[234:237], v198 offset:7168
	global_load_lds_dwordx4 v[194:195], off
	v_lshl_add_u64 v[194:195], s[10:11], 0, v[174:175]
	s_add_i32 m0, s69, 0xe000
	s_nop 0
	global_load_lds_dwordx4 v[194:195], off
	s_waitcnt vmcnt(8)
	s_waitcnt lgkmcnt(0)
	s_setprio 3
	s_barrier
	v_mfma_f32_16x16x32_bf16 v[126:129], v[130:133], v[206:209], v[126:129]
	v_mfma_f32_16x16x32_bf16 v[122:125], v[138:141], v[206:209], v[122:125]
	v_mfma_f32_16x16x32_bf16 v[110:113], v[130:133], v[214:217], v[110:113]
	v_mfma_f32_16x16x32_bf16 v[106:109], v[138:141], v[214:217], v[106:109]
	v_mfma_f32_16x16x32_bf16 v[94:97], v[130:133], v[222:225], v[94:97]
	v_mfma_f32_16x16x32_bf16 v[90:93], v[138:141], v[222:225], v[90:93]
	v_mfma_f32_16x16x32_bf16 v[78:81], v[130:133], v[230:233], v[78:81]
	v_mfma_f32_16x16x32_bf16 v[74:77], v[138:141], v[230:233], v[74:77]
	v_mfma_f32_16x16x32_bf16 v[126:129], v[134:137], v[210:213], v[126:129]
	v_mfma_f32_16x16x32_bf16 v[122:125], v[142:145], v[210:213], v[122:125]
	v_mfma_f32_16x16x32_bf16 v[110:113], v[134:137], v[218:221], v[110:113]
	v_mfma_f32_16x16x32_bf16 v[106:109], v[142:145], v[218:221], v[106:109]
	v_mfma_f32_16x16x32_bf16 v[94:97], v[134:137], v[226:229], v[94:97]
	v_mfma_f32_16x16x32_bf16 v[90:93], v[142:145], v[226:229], v[90:93]
	v_mfma_f32_16x16x32_bf16 v[78:81], v[134:137], v[234:237], v[78:81]
	v_mfma_f32_16x16x32_bf16 v[74:77], v[142:145], v[234:237], v[74:77]
	v_mfma_f32_16x16x32_bf16 v[118:121], v[178:181], v[206:209], v[118:121]
	v_mfma_f32_16x16x32_bf16 v[114:117], v[186:189], v[206:209], v[114:117]
	v_mfma_f32_16x16x32_bf16 v[102:105], v[178:181], v[214:217], v[102:105]
	v_mfma_f32_16x16x32_bf16 v[98:101], v[186:189], v[214:217], v[98:101]
	v_mfma_f32_16x16x32_bf16 v[86:89], v[178:181], v[222:225], v[86:89]
	v_mfma_f32_16x16x32_bf16 v[82:85], v[186:189], v[222:225], v[82:85]
	v_mfma_f32_16x16x32_bf16 v[70:73], v[178:181], v[230:233], v[70:73]
	v_mfma_f32_16x16x32_bf16 v[66:69], v[186:189], v[230:233], v[66:69]
	v_mfma_f32_16x16x32_bf16 v[118:121], v[182:185], v[210:213], v[118:121]
	v_mfma_f32_16x16x32_bf16 v[114:117], v[190:193], v[210:213], v[114:117]
	v_mfma_f32_16x16x32_bf16 v[102:105], v[182:185], v[218:221], v[102:105]
	v_mfma_f32_16x16x32_bf16 v[98:101], v[190:193], v[218:221], v[98:101]
	v_mfma_f32_16x16x32_bf16 v[86:89], v[182:185], v[226:229], v[86:89]
	v_mfma_f32_16x16x32_bf16 v[82:85], v[190:193], v[226:229], v[82:85]
	v_mfma_f32_16x16x32_bf16 v[70:73], v[182:185], v[234:237], v[70:73]
	v_mfma_f32_16x16x32_bf16 v[66:69], v[190:193], v[234:237], v[66:69]
	s_barrier
; #define PG8_STAGE(bufoff, gbase, voff) do { _Pragma("unroll") for (int _i = 0; _i < 2; ++_i) \
;         __builtin_amdgcn_global_load_lds((const unsigned*)((const char*)(gbase) + (voff)[_i]), (PG8_LAS unsigned*)(lds + (bufoff) + ldsw + _i * 8192), 16, 0, 0); } while (0)
; #define PG8_LDA(dst, b, h) do { _Pragma("unroll") for (int m = 0; m < 4; ++m) _Pragma("unroll") for (int k = 0; k < 2; ++k) dst[m][k] = *(const PG8_LAS bf16x8*)(lds + PG8_SA(b, h) + aoff + m * 2048 + k * 1024); } while (0)
; #define PG8_LDB(dst, b, h) do { _Pragma("unroll") for (int n = 0; n < 2; ++n) _Pragma("unroll") for (int k = 0; k < 2; ++k) dst[n][k] = *(const PG8_LAS bf16x8*)(lds + PG8_SB(b, h) + boff + n * 2048 + k * 1024); } while (0)
; #define PG8_MMA(ai, bj, At, Bt) do { __builtin_amdgcn_s_setprio(1); _Pragma("unroll") for (int m = 0; m < 4; ++m) _Pragma("unroll") for (int n = 0; n < 2; ++n) _Pragma("unroll") for (int k = 0; k < 2; ++k) \
;         acc[ai][bj][m][n] = __builtin_amdgcn_mfma_f32_16x16x32_bf16(Bt[n][k], At[m][k], acc[ai][bj][m][n], 0, 0, 0); __builtin_amdgcn_s_setprio(0); } while (0)
; #define PG8_WAIT_V(n) asm volatile("s_waitcnt vmcnt(" #n ")" ::: "memory")
; #define PG8_WAIT_L(n) asm volatile("s_waitcnt lgkmcnt(" #n ")" ::: "memory")
; #define PG8_BAR __builtin_amdgcn_s_barrier()
; #define PG8_SCHED __builtin_amdgcn_sched_barrier(0)
; template <class Epi, class Sched, bool ALIGN_EPI = false, bool SP2 = false, bool PAIR_ACC = false>
; __device__ __forceinline__ void gemm_phase(PG8_LAS unsigned char* lds, const Gemm g, const Sched& S, const Epi& E) {
;     ...
;             PG8_LDA(At, 0, 1); PG8_STAGE(PG8_SB(0, 0), b2, voffB); PG8_STAGE(PG8_SB(0, 1), b2 + hstep, voffB); PG8_STAGE(PG8_SA(0, 0), a2, voffA);
;             PG8_WAIT_V(8); PG8_WAIT_L(0); PG8_BAR; PG8_MMA(1, 0, At, B0); PG8_MMA(1, 1, At, B1); PG8_BAR; PG8_SCHED;
;             PG8_LDB(B0, 1, 0); PG8_LDB(B1, 1, 1); PG8_SCHED; PG8_LDA(At, 1, 0); PG8_STAGE(PG8_SA(0, 1), a2 + hstep, voffA);
;             PG8_WAIT_V(8); PG8_WAIT_L(0); PG8_BAR; PG8_MMA(0, 0, At, B0); PG8_MMA(0, 1, At, B1); PG8_BAR; PG8_SCHED;
	s_setprio 0
	s_add_i32 s40, s25, s67
	v_lshl_add_u64 v[194:195], s[14:15], 0, v[148:149]
	s_mov_b32 m0, s40
	ds_read_b128 v[206:209], v198 offset:16384
	ds_read_b128 v[210:213], v198 offset:17408
	ds_read_b128 v[214:217], v198 offset:18432
	ds_read_b128 v[218:221], v198 offset:19456
	ds_read_b128 v[222:225], v198 offset:20480
	ds_read_b128 v[226:229], v198 offset:21504
	ds_read_b128 v[230:233], v198 offset:22528
	ds_read_b128 v[234:237], v198 offset:23552
	global_load_lds_dwordx4 v[194:195], off
	s_add_i32 m0, s40, 0x2000
	s_add_u32 s40, s14, 0x40000
	v_lshl_add_u64 v[238:239], s[14:15], 0, v[152:153]
	s_addc_u32 s41, s15, 0
	s_add_i32 s79, s35, s67
	global_load_lds_dwordx4 v[238:239], off
	v_lshl_add_u64 v[240:241], s[40:41], 0, v[148:149]
	s_mov_b32 m0, s79
	v_lshl_add_u64 v[242:243], s[18:19], 0, v[150:151]
	global_load_lds_dwordx4 v[240:241], off
	v_lshl_add_u64 v[240:241], s[40:41], 0, v[152:153]
	s_add_i32 m0, s79, 0x2000
	s_nop 0
	global_load_lds_dwordx4 v[240:241], off
	v_lshl_add_u64 v[240:241], s[18:19], 0, v[146:147]
	s_mov_b32 m0, s69
	s_nop 0
	global_load_lds_dwordx4 v[240:241], off
	s_mov_b32 m0, s71
	s_nop 0
	global_load_lds_dwordx4 v[242:243], off
	s_waitcnt vmcnt(8)
	s_waitcnt lgkmcnt(0)
	s_setprio 3
	s_barrier
	v_mfma_f32_16x16x32_bf16 v[62:65], v[130:133], v[206:209], v[62:65]
	v_mfma_f32_16x16x32_bf16 v[58:61], v[138:141], v[206:209], v[58:61]
	v_mfma_f32_16x16x32_bf16 v[46:49], v[130:133], v[214:217], v[46:49]
	v_mfma_f32_16x16x32_bf16 v[42:45], v[138:141], v[214:217], v[42:45]
	v_mfma_f32_16x16x32_bf16 v[30:33], v[130:133], v[222:225], v[30:33]
	v_mfma_f32_16x16x32_bf16 v[26:29], v[138:141], v[222:225], v[26:29]
	v_mfma_f32_16x16x32_bf16 v[14:17], v[130:133], v[230:233], v[14:17]
	v_mfma_f32_16x16x32_bf16 v[10:13], v[138:141], v[230:233], v[10:13]
	v_mfma_f32_16x16x32_bf16 v[62:65], v[134:137], v[210:213], v[62:65]
	v_mfma_f32_16x16x32_bf16 v[58:61], v[142:145], v[210:213], v[58:61]
	v_mfma_f32_16x16x32_bf16 v[46:49], v[134:137], v[218:221], v[46:49]
	v_mfma_f32_16x16x32_bf16 v[42:45], v[142:145], v[218:221], v[42:45]
	v_mfma_f32_16x16x32_bf16 v[30:33], v[134:137], v[226:229], v[30:33]
	v_mfma_f32_16x16x32_bf16 v[26:29], v[142:145], v[226:229], v[26:29]
	v_mfma_f32_16x16x32_bf16 v[14:17], v[134:137], v[234:237], v[14:17]
	v_mfma_f32_16x16x32_bf16 v[10:13], v[142:145], v[234:237], v[10:13]
	v_mfma_f32_16x16x32_bf16 v[54:57], v[178:181], v[206:209], v[54:57]
	v_mfma_f32_16x16x32_bf16 v[50:53], v[186:189], v[206:209], v[50:53]
	v_mfma_f32_16x16x32_bf16 v[38:41], v[178:181], v[214:217], v[38:41]
	v_mfma_f32_16x16x32_bf16 v[34:37], v[186:189], v[214:217], v[34:37]
	v_mfma_f32_16x16x32_bf16 v[22:25], v[178:181], v[222:225], v[22:25]
	v_mfma_f32_16x16x32_bf16 v[18:21], v[186:189], v[222:225], v[18:21]
	v_mfma_f32_16x16x32_bf16 v[6:9], v[178:181], v[230:233], v[6:9]
	v_mfma_f32_16x16x32_bf16 v[2:5], v[186:189], v[230:233], v[2:5]
	v_mfma_f32_16x16x32_bf16 v[54:57], v[182:185], v[210:213], v[54:57]
	v_mfma_f32_16x16x32_bf16 v[50:53], v[190:193], v[210:213], v[50:53]
	v_mfma_f32_16x16x32_bf16 v[38:41], v[182:185], v[218:221], v[38:41]
	v_mfma_f32_16x16x32_bf16 v[34:37], v[190:193], v[218:221], v[34:37]
	v_mfma_f32_16x16x32_bf16 v[22:25], v[182:185], v[226:229], v[22:25]
	v_mfma_f32_16x16x32_bf16 v[18:21], v[190:193], v[226:229], v[18:21]
	v_mfma_f32_16x16x32_bf16 v[6:9], v[182:185], v[234:237], v[6:9]
	v_mfma_f32_16x16x32_bf16 v[2:5], v[190:193], v[234:237], v[2:5]
	s_barrier
	s_setprio 0
.Lpeel_mid_190:
	s_add_i32 s40, 0, 0x18000
	s_add_i32 s41, 0, 0x1c000
	v_add_u32_e32 v142, s40, v173
	v_add_u32_e32 v154, s41, v173
	ds_read_b128 v[130:133], v142
	ds_read_b128 v[134:137], v142 offset:1024
	ds_read_b128 v[138:141], v142 offset:2048
	ds_read_b128 v[142:145], v142 offset:3072
	ds_read_b128 v[178:181], v154
	ds_read_b128 v[182:185], v154 offset:1024
	ds_read_b128 v[186:189], v154 offset:2048
	ds_read_b128 v[190:193], v154 offset:3072
	s_add_u32 s18, s18, 0x40000
	s_addc_u32 s19, s19, 0
	s_mov_b32 m0, s73
	v_lshl_add_u64 v[244:245], s[18:19], 0, v[146:147]
	ds_read_b128 v[206:209], v198 offset:32768
	ds_read_b128 v[210:213], v198 offset:33792
	ds_read_b128 v[214:217], v198 offset:34816
	ds_read_b128 v[218:221], v198 offset:35840
	ds_read_b128 v[222:225], v198 offset:36864
	ds_read_b128 v[226:229], v198 offset:37888
	ds_read_b128 v[230:233], v198 offset:38912
	ds_read_b128 v[234:237], v198 offset:39936
	global_load_lds_dwordx4 v[244:245], off
	v_lshl_add_u64 v[244:245], s[18:19], 0, v[150:151]
	s_mov_b32 m0, s36
	s_nop 0
	global_load_lds_dwordx4 v[244:245], off
	s_waitcnt vmcnt(8)
	s_waitcnt lgkmcnt(0)
	s_setprio 3
	s_barrier
; #define PG8_STAGE(bufoff, gbase, voff) do { _Pragma("unroll") for (int _i = 0; _i < 2; ++_i) \
;         __builtin_amdgcn_global_load_lds((const unsigned*)((const char*)(gbase) + (voff)[_i]), (PG8_LAS unsigned*)(lds + (bufoff) + ldsw + _i * 8192), 16, 0, 0); } while (0)
; #define PG8_LDA(dst, b, h) do { _Pragma("unroll") for (int m = 0; m < 4; ++m) _Pragma("unroll") for (int k = 0; k < 2; ++k) dst[m][k] = *(const PG8_LAS bf16x8*)(lds + PG8_SA(b, h) + aoff + m * 2048 + k * 1024); } while (0)
; #define PG8_MMA(ai, bj, At, Bt) do { __builtin_amdgcn_s_setprio(1); _Pragma("unroll") for (int m = 0; m < 4; ++m) _Pragma("unroll") for (int n = 0; n < 2; ++n) _Pragma("unroll") for (int k = 0; k < 2; ++k) \
;         acc[ai][bj][m][n] = __builtin_amdgcn_mfma_f32_16x16x32_bf16(Bt[n][k], At[m][k], acc[ai][bj][m][n], 0, 0, 0); __builtin_amdgcn_s_setprio(0); } while (0)
; #define PG8_WAIT_V(n) asm volatile("s_waitcnt vmcnt(" #n ")" ::: "memory")
; #define PG8_WAIT_L(n) asm volatile("s_waitcnt lgkmcnt(" #n ")" ::: "memory")
; #define PG8_BAR __builtin_amdgcn_s_barrier()
; #define PG8_SCHED __builtin_amdgcn_sched_barrier(0)
; template <class Epi, class Sched, bool ALIGN_EPI = false, bool SP2 = false, bool PAIR_ACC = false>
; __device__ __forceinline__ void gemm_phase(PG8_LAS unsigned char* lds, const Gemm g, const Sched& S, const Epi& E) {
;     ...
;             PG8_WAIT_V(8); PG8_WAIT_L(0); PG8_BAR; PG8_MMA(0, 0, At, B0); PG8_MMA(0, 1, At, B1); PG8_BAR; PG8_SCHED;
;             PG8_LDA(At, 1, 1); PG8_STAGE(PG8_SB(1, 0), b3, voffB); PG8_STAGE(PG8_SB(1, 1), b3 + hstep, voffB); PG8_STAGE(PG8_SA(1, 0), a3, voffA);
;             PG8_WAIT_V(8); PG8_WAIT_L(0); PG8_BAR; PG8_MMA(1, 0, At, B0); PG8_MMA(1, 1, At, B1); PG8_BAR; PG8_SCHED;
	v_mfma_f32_16x16x32_bf16 v[126:129], v[130:133], v[206:209], v[126:129]
	v_mfma_f32_16x16x32_bf16 v[122:125], v[138:141], v[206:209], v[122:125]
	v_mfma_f32_16x16x32_bf16 v[110:113], v[130:133], v[214:217], v[110:113]
	v_mfma_f32_16x16x32_bf16 v[106:109], v[138:141], v[214:217], v[106:109]
	v_mfma_f32_16x16x32_bf16 v[94:97], v[130:133], v[222:225], v[94:97]
	v_mfma_f32_16x16x32_bf16 v[90:93], v[138:141], v[222:225], v[90:93]
	v_mfma_f32_16x16x32_bf16 v[78:81], v[130:133], v[230:233], v[78:81]
	v_mfma_f32_16x16x32_bf16 v[74:77], v[138:141], v[230:233], v[74:77]
	v_mfma_f32_16x16x32_bf16 v[126:129], v[134:137], v[210:213], v[126:129]
	v_mfma_f32_16x16x32_bf16 v[122:125], v[142:145], v[210:213], v[122:125]
	v_mfma_f32_16x16x32_bf16 v[110:113], v[134:137], v[218:221], v[110:113]
	v_mfma_f32_16x16x32_bf16 v[106:109], v[142:145], v[218:221], v[106:109]
	v_mfma_f32_16x16x32_bf16 v[94:97], v[134:137], v[226:229], v[94:97]
	v_mfma_f32_16x16x32_bf16 v[90:93], v[142:145], v[226:229], v[90:93]
	v_mfma_f32_16x16x32_bf16 v[78:81], v[134:137], v[234:237], v[78:81]
	v_mfma_f32_16x16x32_bf16 v[74:77], v[142:145], v[234:237], v[74:77]
	v_mfma_f32_16x16x32_bf16 v[118:121], v[178:181], v[206:209], v[118:121]
	v_mfma_f32_16x16x32_bf16 v[114:117], v[186:189], v[206:209], v[114:117]
	v_mfma_f32_16x16x32_bf16 v[102:105], v[178:181], v[214:217], v[102:105]
	v_mfma_f32_16x16x32_bf16 v[98:101], v[186:189], v[214:217], v[98:101]
	v_mfma_f32_16x16x32_bf16 v[86:89], v[178:181], v[222:225], v[86:89]
	v_mfma_f32_16x16x32_bf16 v[82:85], v[186:189], v[222:225], v[82:85]
	v_mfma_f32_16x16x32_bf16 v[70:73], v[178:181], v[230:233], v[70:73]
	v_mfma_f32_16x16x32_bf16 v[66:69], v[186:189], v[230:233], v[66:69]
	v_mfma_f32_16x16x32_bf16 v[118:121], v[182:185], v[210:213], v[118:121]
	v_mfma_f32_16x16x32_bf16 v[114:117], v[190:193], v[210:213], v[114:117]
	v_mfma_f32_16x16x32_bf16 v[102:105], v[182:185], v[218:221], v[102:105]
	v_mfma_f32_16x16x32_bf16 v[98:101], v[190:193], v[218:221], v[98:101]
	v_mfma_f32_16x16x32_bf16 v[86:89], v[182:185], v[226:229], v[86:89]
	v_mfma_f32_16x16x32_bf16 v[82:85], v[190:193], v[226:229], v[82:85]
	v_mfma_f32_16x16x32_bf16 v[70:73], v[182:185], v[234:237], v[70:73]
	v_mfma_f32_16x16x32_bf16 v[66:69], v[190:193], v[234:237], v[66:69]
	s_barrier
	s_setprio 0
	s_add_i32 s18, s40, s67
	v_lshl_add_u64 v[194:195], v[194:195], 0, s[50:51]
	s_mov_b32 m0, s18
	ds_read_b128 v[206:209], v198 offset:49152
	ds_read_b128 v[210:213], v198 offset:50176
	ds_read_b128 v[214:217], v198 offset:51200
	ds_read_b128 v[218:221], v198 offset:52224
	ds_read_b128 v[222:225], v198 offset:53248
	ds_read_b128 v[226:229], v198 offset:54272
	ds_read_b128 v[230:233], v198 offset:55296
	ds_read_b128 v[234:237], v198 offset:56320
	global_load_lds_dwordx4 v[194:195], off
	s_add_i32 m0, s18, 0x2000
	s_add_u32 s14, s14, 0x40080
	v_lshl_add_u64 v[194:195], v[238:239], 0, s[50:51]
	s_addc_u32 s15, s15, 0
	s_add_i32 s18, s41, s67
	global_load_lds_dwordx4 v[194:195], off
	v_lshl_add_u64 v[194:195], s[14:15], 0, v[148:149]
	s_mov_b32 m0, s18
	s_nop 0
	global_load_lds_dwordx4 v[194:195], off
	v_lshl_add_u64 v[194:195], s[14:15], 0, v[152:153]
	s_add_i32 m0, s18, 0x2000
	s_nop 0
	global_load_lds_dwordx4 v[194:195], off
	v_lshl_add_u64 v[194:195], v[240:241], 0, s[50:51]
	s_mov_b32 m0, s37
	s_nop 0
	global_load_lds_dwordx4 v[194:195], off
	v_lshl_add_u64 v[194:195], v[242:243], 0, s[50:51]
	s_mov_b32 m0, s75
	s_nop 0
	global_load_lds_dwordx4 v[194:195], off
	s_waitcnt vmcnt(8)
	s_waitcnt lgkmcnt(0)
	s_setprio 3
	s_barrier
	v_mfma_f32_16x16x32_bf16 v[62:65], v[130:133], v[206:209], v[62:65]
	v_mfma_f32_16x16x32_bf16 v[58:61], v[138:141], v[206:209], v[58:61]
	v_mfma_f32_16x16x32_bf16 v[46:49], v[130:133], v[214:217], v[46:49]
	v_mfma_f32_16x16x32_bf16 v[42:45], v[138:141], v[214:217], v[42:45]
	v_mfma_f32_16x16x32_bf16 v[30:33], v[130:133], v[222:225], v[30:33]
	v_mfma_f32_16x16x32_bf16 v[26:29], v[138:141], v[222:225], v[26:29]
	v_mfma_f32_16x16x32_bf16 v[14:17], v[130:133], v[230:233], v[14:17]
	v_mfma_f32_16x16x32_bf16 v[10:13], v[138:141], v[230:233], v[10:13]
	v_mfma_f32_16x16x32_bf16 v[62:65], v[134:137], v[210:213], v[62:65]
	v_mfma_f32_16x16x32_bf16 v[58:61], v[142:145], v[210:213], v[58:61]
	v_mfma_f32_16x16x32_bf16 v[46:49], v[134:137], v[218:221], v[46:49]
	v_mfma_f32_16x16x32_bf16 v[42:45], v[142:145], v[218:221], v[42:45]
	v_mfma_f32_16x16x32_bf16 v[30:33], v[134:137], v[226:229], v[30:33]
	v_mfma_f32_16x16x32_bf16 v[26:29], v[142:145], v[226:229], v[26:29]
	v_mfma_f32_16x16x32_bf16 v[14:17], v[134:137], v[234:237], v[14:17]
	v_mfma_f32_16x16x32_bf16 v[10:13], v[142:145], v[234:237], v[10:13]
	v_mfma_f32_16x16x32_bf16 v[54:57], v[178:181], v[206:209], v[54:57]
	v_mfma_f32_16x16x32_bf16 v[50:53], v[186:189], v[206:209], v[50:53]
	v_mfma_f32_16x16x32_bf16 v[38:41], v[178:181], v[214:217], v[38:41]
	v_mfma_f32_16x16x32_bf16 v[34:37], v[186:189], v[214:217], v[34:37]
	v_mfma_f32_16x16x32_bf16 v[22:25], v[178:181], v[222:225], v[22:25]
	v_mfma_f32_16x16x32_bf16 v[18:21], v[186:189], v[222:225], v[18:21]
	v_mfma_f32_16x16x32_bf16 v[6:9], v[178:181], v[230:233], v[6:9]
	v_mfma_f32_16x16x32_bf16 v[2:5], v[186:189], v[230:233], v[2:5]
	v_mfma_f32_16x16x32_bf16 v[54:57], v[182:185], v[210:213], v[54:57]
	v_mfma_f32_16x16x32_bf16 v[50:53], v[190:193], v[210:213], v[50:53]
	v_mfma_f32_16x16x32_bf16 v[38:41], v[182:185], v[218:221], v[38:41]
	v_mfma_f32_16x16x32_bf16 v[34:37], v[190:193], v[218:221], v[34:37]
	v_mfma_f32_16x16x32_bf16 v[22:25], v[182:185], v[226:229], v[22:25]
	v_mfma_f32_16x16x32_bf16 v[18:21], v[190:193], v[226:229], v[18:21]
	v_mfma_f32_16x16x32_bf16 v[6:9], v[182:185], v[234:237], v[6:9]
	v_mfma_f32_16x16x32_bf16 v[2:5], v[190:193], v[234:237], v[2:5]
	s_barrier
	s_setprio 0
	s_add_i32 s39, s39, 2
	s_add_u32 s10, s10, 0x100
	s_addc_u32 s11, s11, 0
	s_add_u32 s30, s30, 0x100
	s_addc_u32 s38, s38, 0
	s_cmp_gt_u32 s39, 13
	s_cbranch_scc0 .LBB0_190
	s_and_b64 vcc, exec, s[52:53]
	s_cbranch_vccz .LBB0_193
	s_barrier

; #define PG8_STAGE(bufoff, gbase, voff) do { _Pragma("unroll") for (int _i = 0; _i < 2; ++_i) \
;         __builtin_amdgcn_global_load_lds((const unsigned*)((const char*)(gbase) + (voff)[_i]), (PG8_LAS unsigned*)(lds + (bufoff) + ldsw + _i * 8192), 16, 0, 0); } while (0)
; #define PG8_LDA(dst, b, h) do { _Pragma("unroll") for (int m = 0; m < 4; ++m) _Pragma("unroll") for (int k = 0; k < 2; ++k) dst[m][k] = *(const PG8_LAS bf16x8*)(lds + PG8_SA(b, h) + aoff + m * 2048 + k * 1024); } while (0)
; #define PG8_LDB(dst, b, h) do { _Pragma("unroll") for (int n = 0; n < 2; ++n) _Pragma("unroll") for (int k = 0; k < 2; ++k) dst[n][k] = *(const PG8_LAS bf16x8*)(lds + PG8_SB(b, h) + boff + n * 2048 + k * 1024); } while (0)
; #define PG8_MMA(ai, bj, At, Bt) do { __builtin_amdgcn_s_setprio(1); _Pragma("unroll") for (int m = 0; m < 4; ++m) _Pragma("unroll") for (int n = 0; n < 2; ++n) _Pragma("unroll") for (int k = 0; k < 2; ++k) \
;         acc[ai][bj][m][n] = __builtin_amdgcn_mfma_f32_16x16x32_bf16(Bt[n][k], At[m][k], acc[ai][bj][m][n], 0, 0, 0); __builtin_amdgcn_s_setprio(0); } while (0)
; #define PG8_WAIT_V(n) asm volatile("s_waitcnt vmcnt(" #n ")" ::: "memory")
; #define PG8_WAIT_L(n) asm volatile("s_waitcnt lgkmcnt(" #n ")" ::: "memory")
; #define PG8_BAR __builtin_amdgcn_s_barrier()
; #define PG8_SCHED __builtin_amdgcn_sched_barrier(0)
; template <class Epi, class Sched, bool ALIGN_EPI = false, bool SP2 = false, bool PAIR_ACC = false>
; __device__ __forceinline__ void gemm_phase(PG8_LAS unsigned char* lds, const Gemm g, const Sched& S, const Epi& E) {
;     ...
;             PG8_LDB(B0, 0, 0); PG8_LDB(B1, 0, 1); PG8_SCHED; PG8_LDA(At, 0, 0); PG8_STAGE(PG8_SA(1, 1), a1 + hstep, voffA);
;             PG8_WAIT_V(8); PG8_WAIT_L(0); PG8_BAR; PG8_MMA(0, 0, At, B0); PG8_MMA(0, 1, At, B1); PG8_BAR; PG8_SCHED;
;             PG8_LDA(At, 0, 1); PG8_STAGE(PG8_SB(0, 0), b2, voffB); PG8_STAGE(PG8_SB(0, 1), b2 + hstep, voffB); PG8_STAGE(PG8_SA(0, 0), a2, voffA);
;             PG8_WAIT_V(8); PG8_WAIT_L(0); PG8_BAR; PG8_MMA(1, 0, At, B0); PG8_MMA(1, 1, At, B1); PG8_BAR; PG8_SCHED;
.LBB0_585:
	v_add_u32_e32 v142, s46, v206
	v_add_u32_e32 v166, s47, v206
	ds_read_b128 v[130:133], v142
	ds_read_b128 v[134:137], v142 offset:1024
	ds_read_b128 v[138:141], v142 offset:2048
	ds_read_b128 v[142:145], v142 offset:3072
	ds_read_b128 v[146:149], v166
	ds_read_b128 v[150:153], v166 offset:1024
	ds_read_b128 v[154:157], v166 offset:2048
	ds_read_b128 v[178:181], v166 offset:3072
	s_add_u32 s38, s8, 0xfffc0080
	s_addc_u32 s39, s9, -1
	s_cmp_eq_u32 s56, 12
	s_cselect_b32 s55, s43, s39
	s_cselect_b32 s54, s42, s38
	s_cselect_b32 s39, s29, s53
	s_cselect_b32 s38, s31, s51
	v_lshl_add_u64 v[198:199], s[8:9], 0, v[168:169]
	s_add_i32 m0, s34, 0xc000
	ds_read_b128 v[182:185], v208
	ds_read_b128 v[186:189], v208 offset:1024
	ds_read_b128 v[190:193], v208 offset:2048
	ds_read_b128 v[194:197], v208 offset:3072
	ds_read_b128 v[210:213], v208 offset:4096
	ds_read_b128 v[214:217], v208 offset:5120
	ds_read_b128 v[218:221], v208 offset:6144
	ds_read_b128 v[222:225], v208 offset:7168
	global_load_lds_dwordx4 v[198:199], off
	v_lshl_add_u64 v[198:199], s[8:9], 0, v[170:171]
	s_add_i32 m0, s34, 0xe000
	s_nop 0
	global_load_lds_dwordx4 v[198:199], off
	s_waitcnt vmcnt(8)
	s_waitcnt lgkmcnt(0)
	s_setprio 3
	s_barrier
	v_mfma_f32_16x16x32_bf16 v[126:129], v[130:133], v[182:185], v[126:129]
	v_mfma_f32_16x16x32_bf16 v[122:125], v[138:141], v[182:185], v[122:125]
	v_mfma_f32_16x16x32_bf16 v[118:121], v[130:133], v[190:193], v[118:121]
	v_mfma_f32_16x16x32_bf16 v[114:117], v[138:141], v[190:193], v[114:117]
	v_mfma_f32_16x16x32_bf16 v[110:113], v[130:133], v[210:213], v[110:113]
	v_mfma_f32_16x16x32_bf16 v[106:109], v[138:141], v[210:213], v[106:109]
	v_mfma_f32_16x16x32_bf16 v[102:105], v[130:133], v[218:221], v[102:105]
	v_mfma_f32_16x16x32_bf16 v[98:101], v[138:141], v[218:221], v[98:101]
	v_mfma_f32_16x16x32_bf16 v[126:129], v[134:137], v[186:189], v[126:129]
	v_mfma_f32_16x16x32_bf16 v[122:125], v[142:145], v[186:189], v[122:125]
	v_mfma_f32_16x16x32_bf16 v[118:121], v[134:137], v[194:197], v[118:121]
	v_mfma_f32_16x16x32_bf16 v[114:117], v[142:145], v[194:197], v[114:117]
	v_mfma_f32_16x16x32_bf16 v[110:113], v[134:137], v[214:217], v[110:113]
	v_mfma_f32_16x16x32_bf16 v[106:109], v[142:145], v[214:217], v[106:109]
	v_mfma_f32_16x16x32_bf16 v[102:105], v[134:137], v[222:225], v[102:105]
	v_mfma_f32_16x16x32_bf16 v[98:101], v[142:145], v[222:225], v[98:101]
	v_mfma_f32_16x16x32_bf16 v[94:97], v[146:149], v[182:185], v[94:97]
	v_mfma_f32_16x16x32_bf16 v[90:93], v[154:157], v[182:185], v[90:93]
	v_mfma_f32_16x16x32_bf16 v[86:89], v[146:149], v[190:193], v[86:89]
	v_mfma_f32_16x16x32_bf16 v[82:85], v[154:157], v[190:193], v[82:85]
	v_mfma_f32_16x16x32_bf16 v[78:81], v[146:149], v[210:213], v[78:81]
	v_mfma_f32_16x16x32_bf16 v[74:77], v[154:157], v[210:213], v[74:77]
	v_mfma_f32_16x16x32_bf16 v[70:73], v[146:149], v[218:221], v[70:73]
	v_mfma_f32_16x16x32_bf16 v[66:69], v[154:157], v[218:221], v[66:69]
	v_mfma_f32_16x16x32_bf16 v[94:97], v[150:153], v[186:189], v[94:97]
	v_mfma_f32_16x16x32_bf16 v[90:93], v[178:181], v[186:189], v[90:93]
	v_mfma_f32_16x16x32_bf16 v[86:89], v[150:153], v[194:197], v[86:89]
	v_mfma_f32_16x16x32_bf16 v[82:85], v[178:181], v[194:197], v[82:85]
	v_mfma_f32_16x16x32_bf16 v[78:81], v[150:153], v[214:217], v[78:81]
	v_mfma_f32_16x16x32_bf16 v[74:77], v[178:181], v[214:217], v[74:77]
	v_mfma_f32_16x16x32_bf16 v[70:73], v[150:153], v[222:225], v[70:73]
	v_mfma_f32_16x16x32_bf16 v[66:69], v[178:181], v[222:225], v[66:69]
	s_barrier
	s_setprio 0
	s_add_i32 s57, s46, s25
	v_lshl_add_u64 v[198:199], s[38:39], 0, v[160:161]
	s_mov_b32 m0, s57
	ds_read_b128 v[182:185], v208 offset:16384
	ds_read_b128 v[186:189], v208 offset:17408
	ds_read_b128 v[190:193], v208 offset:18432
	ds_read_b128 v[194:197], v208 offset:19456
	ds_read_b128 v[210:213], v208 offset:20480
	ds_read_b128 v[214:217], v208 offset:21504
	ds_read_b128 v[218:221], v208 offset:22528
	ds_read_b128 v[222:225], v208 offset:23552
	global_load_lds_dwordx4 v[198:199], off
	s_add_i32 m0, s57, 0x2000
	s_add_u32 s58, s38, 0x40000
	v_lshl_add_u64 v[226:227], s[38:39], 0, v[164:165]
	s_addc_u32 s59, s39, 0
	s_add_i32 s57, s47, s25
	global_load_lds_dwordx4 v[226:227], off
	v_lshl_add_u64 v[228:229], s[58:59], 0, v[160:161]
	s_mov_b32 m0, s57
	v_lshl_add_u64 v[230:231], s[54:55], 0, v[162:163]
	global_load_lds_dwordx4 v[228:229], off
	v_lshl_add_u64 v[228:229], s[58:59], 0, v[164:165]
	s_add_i32 m0, s57, 0x2000
	s_nop 0
	global_load_lds_dwordx4 v[228:229], off
	v_lshl_add_u64 v[228:229], s[54:55], 0, v[158:159]
	s_mov_b32 m0, s34
	s_nop 0
	global_load_lds_dwordx4 v[228:229], off
	s_mov_b32 m0, s35
	s_nop 0
	global_load_lds_dwordx4 v[230:231], off
	s_waitcnt vmcnt(8)
	s_waitcnt lgkmcnt(0)
	s_setprio 3
	s_barrier
; #define PG8_STAGE(bufoff, gbase, voff) do { _Pragma("unroll") for (int _i = 0; _i < 2; ++_i) \
;         __builtin_amdgcn_global_load_lds((const unsigned*)((const char*)(gbase) + (voff)[_i]), (PG8_LAS unsigned*)(lds + (bufoff) + ldsw + _i * 8192), 16, 0, 0); } while (0)
; #define PG8_LDA(dst, b, h) do { _Pragma("unroll") for (int m = 0; m < 4; ++m) _Pragma("unroll") for (int k = 0; k < 2; ++k) dst[m][k] = *(const PG8_LAS bf16x8*)(lds + PG8_SA(b, h) + aoff + m * 2048 + k * 1024); } while (0)
; #define PG8_LDB(dst, b, h) do { _Pragma("unroll") for (int n = 0; n < 2; ++n) _Pragma("unroll") for (int k = 0; k < 2; ++k) dst[n][k] = *(const PG8_LAS bf16x8*)(lds + PG8_SB(b, h) + boff + n * 2048 + k * 1024); } while (0)
; #define PG8_MMA(ai, bj, At, Bt) do { __builtin_amdgcn_s_setprio(1); _Pragma("unroll") for (int m = 0; m < 4; ++m) _Pragma("unroll") for (int n = 0; n < 2; ++n) _Pragma("unroll") for (int k = 0; k < 2; ++k) \
;         acc[ai][bj][m][n] = __builtin_amdgcn_mfma_f32_16x16x32_bf16(Bt[n][k], At[m][k], acc[ai][bj][m][n], 0, 0, 0); __builtin_amdgcn_s_setprio(0); } while (0)
; #define PG8_WAIT_V(n) asm volatile("s_waitcnt vmcnt(" #n ")" ::: "memory")
; #define PG8_WAIT_L(n) asm volatile("s_waitcnt lgkmcnt(" #n ")" ::: "memory")
; #define PG8_BAR __builtin_amdgcn_s_barrier()
; #define PG8_SCHED __builtin_amdgcn_sched_barrier(0)
; template <class Epi, class Sched, bool ALIGN_EPI = false, bool SP2 = false, bool PAIR_ACC = false>
; __device__ __forceinline__ void gemm_phase(PG8_LAS unsigned char* lds, const Gemm g, const Sched& S, const Epi& E) {
;     ...
;             PG8_WAIT_V(8); PG8_WAIT_L(0); PG8_BAR; PG8_MMA(1, 0, At, B0); PG8_MMA(1, 1, At, B1); PG8_BAR; PG8_SCHED;
;             PG8_LDB(B0, 1, 0); PG8_LDB(B1, 1, 1); PG8_SCHED; PG8_LDA(At, 1, 0); PG8_STAGE(PG8_SA(0, 1), a2 + hstep, voffA);
;             PG8_WAIT_V(8); PG8_WAIT_L(0); PG8_BAR; PG8_MMA(0, 0, At, B0); PG8_MMA(0, 1, At, B1); PG8_BAR; PG8_SCHED;
	v_mfma_f32_16x16x32_bf16 v[62:65], v[130:133], v[182:185], v[62:65]
	v_mfma_f32_16x16x32_bf16 v[58:61], v[138:141], v[182:185], v[58:61]
	v_mfma_f32_16x16x32_bf16 v[54:57], v[130:133], v[190:193], v[54:57]
	v_mfma_f32_16x16x32_bf16 v[50:53], v[138:141], v[190:193], v[50:53]
	v_mfma_f32_16x16x32_bf16 v[46:49], v[130:133], v[210:213], v[46:49]
	v_mfma_f32_16x16x32_bf16 v[42:45], v[138:141], v[210:213], v[42:45]
	v_mfma_f32_16x16x32_bf16 v[38:41], v[130:133], v[218:221], v[38:41]
	v_mfma_f32_16x16x32_bf16 v[34:37], v[138:141], v[218:221], v[34:37]
	v_mfma_f32_16x16x32_bf16 v[62:65], v[134:137], v[186:189], v[62:65]
	v_mfma_f32_16x16x32_bf16 v[58:61], v[142:145], v[186:189], v[58:61]
	v_mfma_f32_16x16x32_bf16 v[54:57], v[134:137], v[194:197], v[54:57]
	v_mfma_f32_16x16x32_bf16 v[50:53], v[142:145], v[194:197], v[50:53]
	v_mfma_f32_16x16x32_bf16 v[46:49], v[134:137], v[214:217], v[46:49]
	v_mfma_f32_16x16x32_bf16 v[42:45], v[142:145], v[214:217], v[42:45]
	v_mfma_f32_16x16x32_bf16 v[38:41], v[134:137], v[222:225], v[38:41]
	v_mfma_f32_16x16x32_bf16 v[34:37], v[142:145], v[222:225], v[34:37]
	v_mfma_f32_16x16x32_bf16 v[30:33], v[146:149], v[182:185], v[30:33]
	v_mfma_f32_16x16x32_bf16 v[26:29], v[154:157], v[182:185], v[26:29]
	v_mfma_f32_16x16x32_bf16 v[22:25], v[146:149], v[190:193], v[22:25]
	v_mfma_f32_16x16x32_bf16 v[18:21], v[154:157], v[190:193], v[18:21]
	v_mfma_f32_16x16x32_bf16 v[14:17], v[146:149], v[210:213], v[14:17]
	v_mfma_f32_16x16x32_bf16 v[10:13], v[154:157], v[210:213], v[10:13]
	v_mfma_f32_16x16x32_bf16 v[6:9], v[146:149], v[218:221], v[6:9]
	v_mfma_f32_16x16x32_bf16 v[2:5], v[154:157], v[218:221], v[2:5]
	v_mfma_f32_16x16x32_bf16 v[30:33], v[150:153], v[186:189], v[30:33]
	v_mfma_f32_16x16x32_bf16 v[26:29], v[178:181], v[186:189], v[26:29]
	v_mfma_f32_16x16x32_bf16 v[22:25], v[150:153], v[194:197], v[22:25]
	v_mfma_f32_16x16x32_bf16 v[18:21], v[178:181], v[194:197], v[18:21]
	v_mfma_f32_16x16x32_bf16 v[14:17], v[150:153], v[214:217], v[14:17]
	v_mfma_f32_16x16x32_bf16 v[10:13], v[178:181], v[214:217], v[10:13]
	v_mfma_f32_16x16x32_bf16 v[6:9], v[150:153], v[222:225], v[6:9]
	v_mfma_f32_16x16x32_bf16 v[2:5], v[178:181], v[222:225], v[2:5]
	s_barrier
	s_setprio 0
	s_add_i32 s57, 0, 0x18000
	s_add_i32 s58, 0, 0x1c000
	v_add_u32_e32 v142, s57, v206
	v_add_u32_e32 v166, s58, v206
	ds_read_b128 v[130:133], v142
	ds_read_b128 v[134:137], v142 offset:1024
	ds_read_b128 v[138:141], v142 offset:2048
	ds_read_b128 v[142:145], v142 offset:3072
	ds_read_b128 v[146:149], v166
	ds_read_b128 v[150:153], v166 offset:1024
	ds_read_b128 v[154:157], v166 offset:2048
	ds_read_b128 v[178:181], v166 offset:3072
	s_add_u32 s54, s54, 0x40000
	s_addc_u32 s55, s55, 0
	s_mov_b32 m0, s36
	v_lshl_add_u64 v[232:233], s[54:55], 0, v[158:159]
	ds_read_b128 v[182:185], v208 offset:32768
	ds_read_b128 v[186:189], v208 offset:33792
	ds_read_b128 v[190:193], v208 offset:34816
	ds_read_b128 v[194:197], v208 offset:35840
	ds_read_b128 v[210:213], v208 offset:36864
	ds_read_b128 v[214:217], v208 offset:37888
	ds_read_b128 v[218:221], v208 offset:38912
	ds_read_b128 v[222:225], v208 offset:39936
	global_load_lds_dwordx4 v[232:233], off
	v_lshl_add_u64 v[232:233], s[54:55], 0, v[162:163]
	s_mov_b32 m0, s37
	s_nop 0
	global_load_lds_dwordx4 v[232:233], off
	s_waitcnt vmcnt(8)
	s_waitcnt lgkmcnt(0)
	s_setprio 3
	s_barrier
	v_mfma_f32_16x16x32_bf16 v[126:129], v[130:133], v[182:185], v[126:129]
	v_mfma_f32_16x16x32_bf16 v[122:125], v[138:141], v[182:185], v[122:125]
	v_mfma_f32_16x16x32_bf16 v[118:121], v[130:133], v[190:193], v[118:121]
	v_mfma_f32_16x16x32_bf16 v[114:117], v[138:141], v[190:193], v[114:117]
	v_mfma_f32_16x16x32_bf16 v[110:113], v[130:133], v[210:213], v[110:113]
	v_mfma_f32_16x16x32_bf16 v[106:109], v[138:141], v[210:213], v[106:109]
	v_mfma_f32_16x16x32_bf16 v[102:105], v[130:133], v[218:221], v[102:105]
	v_mfma_f32_16x16x32_bf16 v[98:101], v[138:141], v[218:221], v[98:101]
	v_mfma_f32_16x16x32_bf16 v[126:129], v[134:137], v[186:189], v[126:129]
	v_mfma_f32_16x16x32_bf16 v[122:125], v[142:145], v[186:189], v[122:125]
	v_mfma_f32_16x16x32_bf16 v[118:121], v[134:137], v[194:197], v[118:121]
	v_mfma_f32_16x16x32_bf16 v[114:117], v[142:145], v[194:197], v[114:117]
	v_mfma_f32_16x16x32_bf16 v[110:113], v[134:137], v[214:217], v[110:113]
	v_mfma_f32_16x16x32_bf16 v[106:109], v[142:145], v[214:217], v[106:109]
	v_mfma_f32_16x16x32_bf16 v[102:105], v[134:137], v[222:225], v[102:105]
	v_mfma_f32_16x16x32_bf16 v[98:101], v[142:145], v[222:225], v[98:101]
	v_mfma_f32_16x16x32_bf16 v[94:97], v[146:149], v[182:185], v[94:97]
	v_mfma_f32_16x16x32_bf16 v[90:93], v[154:157], v[182:185], v[90:93]
	v_mfma_f32_16x16x32_bf16 v[86:89], v[146:149], v[190:193], v[86:89]
	v_mfma_f32_16x16x32_bf16 v[82:85], v[154:157], v[190:193], v[82:85]
	v_mfma_f32_16x16x32_bf16 v[78:81], v[146:149], v[210:213], v[78:81]
	v_mfma_f32_16x16x32_bf16 v[74:77], v[154:157], v[210:213], v[74:77]
	v_mfma_f32_16x16x32_bf16 v[70:73], v[146:149], v[218:221], v[70:73]
	v_mfma_f32_16x16x32_bf16 v[66:69], v[154:157], v[218:221], v[66:69]
	v_mfma_f32_16x16x32_bf16 v[94:97], v[150:153], v[186:189], v[94:97]
	v_mfma_f32_16x16x32_bf16 v[90:93], v[178:181], v[186:189], v[90:93]
	v_mfma_f32_16x16x32_bf16 v[86:89], v[150:153], v[194:197], v[86:89]
	v_mfma_f32_16x16x32_bf16 v[82:85], v[178:181], v[194:197], v[82:85]
	v_mfma_f32_16x16x32_bf16 v[78:81], v[150:153], v[214:217], v[78:81]
	v_mfma_f32_16x16x32_bf16 v[74:77], v[178:181], v[214:217], v[74:77]
	v_mfma_f32_16x16x32_bf16 v[70:73], v[150:153], v[222:225], v[70:73]
	v_mfma_f32_16x16x32_bf16 v[66:69], v[178:181], v[222:225], v[66:69]
	s_barrier
; #define PG8_STAGE(bufoff, gbase, voff) do { _Pragma("unroll") for (int _i = 0; _i < 2; ++_i) \
;         __builtin_amdgcn_global_load_lds((const unsigned*)((const char*)(gbase) + (voff)[_i]), (PG8_LAS unsigned*)(lds + (bufoff) + ldsw + _i * 8192), 16, 0, 0); } while (0)
; #define PG8_LDA(dst, b, h) do { _Pragma("unroll") for (int m = 0; m < 4; ++m) _Pragma("unroll") for (int k = 0; k < 2; ++k) dst[m][k] = *(const PG8_LAS bf16x8*)(lds + PG8_SA(b, h) + aoff + m * 2048 + k * 1024); } while (0)
; #define PG8_MMA(ai, bj, At, Bt) do { __builtin_amdgcn_s_setprio(1); _Pragma("unroll") for (int m = 0; m < 4; ++m) _Pragma("unroll") for (int n = 0; n < 2; ++n) _Pragma("unroll") for (int k = 0; k < 2; ++k) \
;         acc[ai][bj][m][n] = __builtin_amdgcn_mfma_f32_16x16x32_bf16(Bt[n][k], At[m][k], acc[ai][bj][m][n], 0, 0, 0); __builtin_amdgcn_s_setprio(0); } while (0)
; #define PG8_WAIT_V(n) asm volatile("s_waitcnt vmcnt(" #n ")" ::: "memory")
; #define PG8_WAIT_L(n) asm volatile("s_waitcnt lgkmcnt(" #n ")" ::: "memory")
; #define PG8_BAR __builtin_amdgcn_s_barrier()
; #define PG8_SCHED __builtin_amdgcn_sched_barrier(0)
; template <class Epi, class Sched, bool ALIGN_EPI = false, bool SP2 = false, bool PAIR_ACC = false>
; __device__ __forceinline__ void gemm_phase(PG8_LAS unsigned char* lds, const Gemm g, const Sched& S, const Epi& E) {
;     ...
;             PG8_LDA(At, 1, 1); PG8_STAGE(PG8_SB(1, 0), b3, voffB); PG8_STAGE(PG8_SB(1, 1), b3 + hstep, voffB); PG8_STAGE(PG8_SA(1, 0), a3, voffA);
;             PG8_WAIT_V(8); PG8_WAIT_L(0); PG8_BAR; PG8_MMA(1, 0, At, B0); PG8_MMA(1, 1, At, B1); PG8_BAR; PG8_SCHED;
	s_setprio 0
	s_add_i32 s54, s57, s25
	v_lshl_add_u64 v[198:199], v[198:199], 0, s[18:19]
	s_mov_b32 m0, s54
	ds_read_b128 v[182:185], v208 offset:49152
	ds_read_b128 v[186:189], v208 offset:50176
	ds_read_b128 v[190:193], v208 offset:51200
	ds_read_b128 v[194:197], v208 offset:52224
	ds_read_b128 v[210:213], v208 offset:53248
	ds_read_b128 v[214:217], v208 offset:54272
	ds_read_b128 v[218:221], v208 offset:55296
	ds_read_b128 v[222:225], v208 offset:56320
	global_load_lds_dwordx4 v[198:199], off
	s_add_i32 m0, s54, 0x2000
	s_add_u32 s38, s38, 0x40080
	v_lshl_add_u64 v[198:199], v[226:227], 0, s[18:19]
	s_addc_u32 s39, s39, 0
	s_add_i32 s54, s58, s25
	global_load_lds_dwordx4 v[198:199], off
	v_lshl_add_u64 v[198:199], s[38:39], 0, v[160:161]
	s_mov_b32 m0, s54
	s_nop 0
	global_load_lds_dwordx4 v[198:199], off
	v_lshl_add_u64 v[198:199], s[38:39], 0, v[164:165]
	s_add_i32 m0, s54, 0x2000
	s_nop 0
	global_load_lds_dwordx4 v[198:199], off
	v_lshl_add_u64 v[198:199], v[228:229], 0, s[18:19]
	s_mov_b32 m0, s41
	s_nop 0
	global_load_lds_dwordx4 v[198:199], off
	v_lshl_add_u64 v[198:199], v[230:231], 0, s[18:19]
	s_mov_b32 m0, s44
	s_nop 0
	global_load_lds_dwordx4 v[198:199], off
	s_waitcnt vmcnt(8)
	s_waitcnt lgkmcnt(0)
	s_setprio 3
	s_barrier
	v_mfma_f32_16x16x32_bf16 v[62:65], v[130:133], v[182:185], v[62:65]
	v_mfma_f32_16x16x32_bf16 v[58:61], v[138:141], v[182:185], v[58:61]
	v_mfma_f32_16x16x32_bf16 v[54:57], v[130:133], v[190:193], v[54:57]
	v_mfma_f32_16x16x32_bf16 v[50:53], v[138:141], v[190:193], v[50:53]
	v_mfma_f32_16x16x32_bf16 v[46:49], v[130:133], v[210:213], v[46:49]
	v_mfma_f32_16x16x32_bf16 v[42:45], v[138:141], v[210:213], v[42:45]
	v_mfma_f32_16x16x32_bf16 v[38:41], v[130:133], v[218:221], v[38:41]
	v_mfma_f32_16x16x32_bf16 v[34:37], v[138:141], v[218:221], v[34:37]
	v_mfma_f32_16x16x32_bf16 v[62:65], v[134:137], v[186:189], v[62:65]
	v_mfma_f32_16x16x32_bf16 v[58:61], v[142:145], v[186:189], v[58:61]
	v_mfma_f32_16x16x32_bf16 v[54:57], v[134:137], v[194:197], v[54:57]
	v_mfma_f32_16x16x32_bf16 v[50:53], v[142:145], v[194:197], v[50:53]
	v_mfma_f32_16x16x32_bf16 v[46:49], v[134:137], v[214:217], v[46:49]
	v_mfma_f32_16x16x32_bf16 v[42:45], v[142:145], v[214:217], v[42:45]
	v_mfma_f32_16x16x32_bf16 v[38:41], v[134:137], v[222:225], v[38:41]
	v_mfma_f32_16x16x32_bf16 v[34:37], v[142:145], v[222:225], v[34:37]
	v_mfma_f32_16x16x32_bf16 v[30:33], v[146:149], v[182:185], v[30:33]
	v_mfma_f32_16x16x32_bf16 v[26:29], v[154:157], v[182:185], v[26:29]
	v_mfma_f32_16x16x32_bf16 v[22:25], v[146:149], v[190:193], v[22:25]
	v_mfma_f32_16x16x32_bf16 v[18:21], v[154:157], v[190:193], v[18:21]
	v_mfma_f32_16x16x32_bf16 v[14:17], v[146:149], v[210:213], v[14:17]
	v_mfma_f32_16x16x32_bf16 v[10:13], v[154:157], v[210:213], v[10:13]
	v_mfma_f32_16x16x32_bf16 v[6:9], v[146:149], v[218:221], v[6:9]
	v_mfma_f32_16x16x32_bf16 v[2:5], v[154:157], v[218:221], v[2:5]
	v_mfma_f32_16x16x32_bf16 v[30:33], v[150:153], v[186:189], v[30:33]
	v_mfma_f32_16x16x32_bf16 v[26:29], v[178:181], v[186:189], v[26:29]
	v_mfma_f32_16x16x32_bf16 v[22:25], v[150:153], v[194:197], v[22:25]
	v_mfma_f32_16x16x32_bf16 v[18:21], v[178:181], v[194:197], v[18:21]
	v_mfma_f32_16x16x32_bf16 v[14:17], v[150:153], v[214:217], v[14:17]
	v_mfma_f32_16x16x32_bf16 v[10:13], v[178:181], v[214:217], v[10:13]
	v_mfma_f32_16x16x32_bf16 v[6:9], v[150:153], v[222:225], v[6:9]
	v_mfma_f32_16x16x32_bf16 v[2:5], v[178:181], v[222:225], v[2:5]
	s_barrier
	s_setprio 0
	s_add_i32 s56, s56, 2
	s_add_u32 s8, s8, 0x100
	s_addc_u32 s9, s9, 0
	s_add_u32 s51, s51, 0x100
	s_addc_u32 s53, s53, 0
	s_cmp_gt_u32 s56, 13
	s_cbranch_scc0 .LBB0_585
	s_and_b64 vcc, exec, s[20:21]
	s_cbranch_vccz .LBB0_588
	s_barrier

; #define PG8_STAGE(bufoff, gbase, voff) do { _Pragma("unroll") for (int _i = 0; _i < 2; ++_i) \
;         __builtin_amdgcn_global_load_lds((const unsigned*)((const char*)(gbase) + (voff)[_i]), (PG8_LAS unsigned*)(lds + (bufoff) + ldsw + _i * 8192), 16, 0, 0); } while (0)
; #define PG8_LDA(dst, b, h) do { _Pragma("unroll") for (int m = 0; m < 4; ++m) _Pragma("unroll") for (int k = 0; k < 2; ++k) dst[m][k] = *(const PG8_LAS bf16x8*)(lds + PG8_SA(b, h) + aoff + m * 2048 + k * 1024); } while (0)
; #define PG8_LDB(dst, b, h) do { _Pragma("unroll") for (int n = 0; n < 2; ++n) _Pragma("unroll") for (int k = 0; k < 2; ++k) dst[n][k] = *(const PG8_LAS bf16x8*)(lds + PG8_SB(b, h) + boff + n * 2048 + k * 1024); } while (0)
; #define PG8_MMA(ai, bj, At, Bt) do { __builtin_amdgcn_s_setprio(1); _Pragma("unroll") for (int m = 0; m < 4; ++m) _Pragma("unroll") for (int n = 0; n < 2; ++n) _Pragma("unroll") for (int k = 0; k < 2; ++k) \
;         acc[ai][bj][m][n] = __builtin_amdgcn_mfma_f32_16x16x32_bf16(Bt[n][k], At[m][k], acc[ai][bj][m][n], 0, 0, 0); __builtin_amdgcn_s_setprio(0); } while (0)
; #define PG8_WAIT_V(n) asm volatile("s_waitcnt vmcnt(" #n ")" ::: "memory")
; #define PG8_WAIT_L(n) asm volatile("s_waitcnt lgkmcnt(" #n ")" ::: "memory")
; #define PG8_BAR __builtin_amdgcn_s_barrier()
; #define PG8_SCHED __builtin_amdgcn_sched_barrier(0)
; template <class Epi, class Sched, bool ALIGN_EPI = false, bool SP2 = false, bool PAIR_ACC = false>
; __device__ __forceinline__ void gemm_phase(PG8_LAS unsigned char* lds, const Gemm g, const Sched& S, const Epi& E) {
;     ...
;             PG8_LDB(B0, 0, 0); PG8_LDB(B1, 0, 1); PG8_SCHED; PG8_LDA(At, 0, 0); PG8_STAGE(PG8_SA(1, 1), a1 + hstep, voffA);
;             PG8_WAIT_V(8); PG8_WAIT_L(0); PG8_BAR; PG8_MMA(0, 0, At, B0); PG8_MMA(0, 1, At, B1); PG8_BAR; PG8_SCHED;
;             PG8_LDA(At, 0, 1); PG8_STAGE(PG8_SB(0, 0), b2, voffB); PG8_STAGE(PG8_SB(0, 1), b2 + hstep, voffB); PG8_STAGE(PG8_SA(0, 0), a2, voffA);
;             PG8_WAIT_V(8); PG8_WAIT_L(0); PG8_BAR; PG8_MMA(1, 0, At, B0); PG8_MMA(1, 1, At, B1); PG8_BAR; PG8_SCHED;
.LBB0_727:
	v_add_u32_e32 v164, s57, v150
	ds_read_b128 v[152:155], v164
	ds_read_b128 v[156:159], v164 offset:1024
	ds_read_b128 v[160:163], v164 offset:2048
	ds_read_b128 v[174:177], v164 offset:3072
	v_add_u32_e32 v164, s58, v150
	s_add_u32 s38, s20, s52
	ds_read_b128 v[178:181], v164
	ds_read_b128 v[182:185], v164 offset:1024
	ds_read_b128 v[186:189], v164 offset:2048
	ds_read_b128 v[190:193], v164 offset:3072
	s_addc_u32 s39, s21, s53
	s_add_u32 s38, s38, 0x100
	s_addc_u32 s39, s39, 0
	s_add_u32 s65, s60, s52
	s_addc_u32 s66, s61, s53
	s_cmpk_eq_i32 s52, 0x700
	s_cselect_b32 s55, s43, s39
	s_cselect_b32 s54, s62, s38
	s_cselect_b32 s39, s31, s66
	s_cselect_b32 s38, s63, s65
	v_lshl_add_u64 v[164:165], v[146:147], 0, s[52:53]
	s_add_i32 m0, s40, 0xc000
	ds_read_b128 v[194:197], v151
	ds_read_b128 v[206:209], v151 offset:1024
	ds_read_b128 v[210:213], v151 offset:2048
	ds_read_b128 v[214:217], v151 offset:3072
	ds_read_b128 v[218:221], v151 offset:4096
	ds_read_b128 v[222:225], v151 offset:5120
	ds_read_b128 v[226:229], v151 offset:6144
	ds_read_b128 v[230:233], v151 offset:7168
	global_load_lds_dwordx4 v[164:165], off
	v_lshl_add_u64 v[164:165], v[148:149], 0, s[52:53]
	s_add_i32 m0, s40, 0xe000
	s_nop 0
	global_load_lds_dwordx4 v[164:165], off
	s_waitcnt vmcnt(8)
	s_waitcnt lgkmcnt(0)
	s_setprio 3
	s_barrier
	v_mfma_f32_16x16x32_bf16 v[122:125], v[152:155], v[194:197], v[122:125]
	v_mfma_f32_16x16x32_bf16 v[126:129], v[160:163], v[194:197], v[126:129]
	v_mfma_f32_16x16x32_bf16 v[110:113], v[152:155], v[210:213], v[110:113]
	v_mfma_f32_16x16x32_bf16 v[106:109], v[160:163], v[210:213], v[106:109]
	v_mfma_f32_16x16x32_bf16 v[102:105], v[152:155], v[218:221], v[102:105]
	v_mfma_f32_16x16x32_bf16 v[98:101], v[160:163], v[218:221], v[98:101]
	v_mfma_f32_16x16x32_bf16 v[94:97], v[152:155], v[226:229], v[94:97]
	v_mfma_f32_16x16x32_bf16 v[90:93], v[160:163], v[226:229], v[90:93]
	v_mfma_f32_16x16x32_bf16 v[122:125], v[156:159], v[206:209], v[122:125]
	v_mfma_f32_16x16x32_bf16 v[126:129], v[174:177], v[206:209], v[126:129]
	v_mfma_f32_16x16x32_bf16 v[110:113], v[156:159], v[214:217], v[110:113]
	v_mfma_f32_16x16x32_bf16 v[106:109], v[174:177], v[214:217], v[106:109]
	v_mfma_f32_16x16x32_bf16 v[102:105], v[156:159], v[222:225], v[102:105]
	v_mfma_f32_16x16x32_bf16 v[98:101], v[174:177], v[222:225], v[98:101]
	v_mfma_f32_16x16x32_bf16 v[94:97], v[156:159], v[230:233], v[94:97]
	v_mfma_f32_16x16x32_bf16 v[90:93], v[174:177], v[230:233], v[90:93]
	v_mfma_f32_16x16x32_bf16 v[118:121], v[178:181], v[194:197], v[118:121]
	v_mfma_f32_16x16x32_bf16 v[114:117], v[186:189], v[194:197], v[114:117]
	v_mfma_f32_16x16x32_bf16 v[70:73], v[178:181], v[210:213], v[70:73]
	v_mfma_f32_16x16x32_bf16 v[66:69], v[186:189], v[210:213], v[66:69]
	v_mfma_f32_16x16x32_bf16 v[62:65], v[178:181], v[218:221], v[62:65]
	v_mfma_f32_16x16x32_bf16 v[58:61], v[186:189], v[218:221], v[58:61]
	v_mfma_f32_16x16x32_bf16 v[54:57], v[178:181], v[226:229], v[54:57]
	v_mfma_f32_16x16x32_bf16 v[50:53], v[186:189], v[226:229], v[50:53]
	v_mfma_f32_16x16x32_bf16 v[118:121], v[182:185], v[206:209], v[118:121]
	v_mfma_f32_16x16x32_bf16 v[114:117], v[190:193], v[206:209], v[114:117]
	v_mfma_f32_16x16x32_bf16 v[70:73], v[182:185], v[214:217], v[70:73]
	v_mfma_f32_16x16x32_bf16 v[66:69], v[190:193], v[214:217], v[66:69]
	v_mfma_f32_16x16x32_bf16 v[62:65], v[182:185], v[222:225], v[62:65]
	v_mfma_f32_16x16x32_bf16 v[58:61], v[190:193], v[222:225], v[58:61]
	v_mfma_f32_16x16x32_bf16 v[54:57], v[182:185], v[230:233], v[54:57]
	v_mfma_f32_16x16x32_bf16 v[50:53], v[190:193], v[230:233], v[50:53]
	s_barrier
	s_setprio 0
	s_add_i32 s65, s57, s37
	v_lshl_add_u64 v[164:165], s[38:39], 0, v[132:133]
	s_mov_b32 m0, s65
	ds_read_b128 v[194:197], v151 offset:16384
	ds_read_b128 v[206:209], v151 offset:17408
	ds_read_b128 v[210:213], v151 offset:18432
	ds_read_b128 v[214:217], v151 offset:19456
	ds_read_b128 v[218:221], v151 offset:20480
	ds_read_b128 v[222:225], v151 offset:21504
	ds_read_b128 v[226:229], v151 offset:22528
	ds_read_b128 v[230:233], v151 offset:23552
	global_load_lds_dwordx4 v[164:165], off
	s_add_i32 m0, s65, 0x2000
	s_add_u32 s66, s38, 0x40000
	v_lshl_add_u64 v[168:169], s[38:39], 0, v[136:137]
	s_addc_u32 s67, s39, 0
	s_add_i32 s65, s58, s37
	global_load_lds_dwordx4 v[168:169], off
	v_lshl_add_u64 v[198:199], s[66:67], 0, v[132:133]
	s_mov_b32 m0, s65
	v_lshl_add_u64 v[234:235], s[54:55], 0, v[134:135]
	global_load_lds_dwordx4 v[198:199], off
	v_lshl_add_u64 v[198:199], s[66:67], 0, v[136:137]
	s_add_i32 m0, s65, 0x2000
	s_nop 0
	global_load_lds_dwordx4 v[198:199], off
	v_lshl_add_u64 v[198:199], s[54:55], 0, v[130:131]
	s_mov_b32 m0, s40
	s_nop 0
	global_load_lds_dwordx4 v[198:199], off
	s_mov_b32 m0, s41
	s_nop 0
	global_load_lds_dwordx4 v[234:235], off
	s_waitcnt vmcnt(8)
	s_waitcnt lgkmcnt(0)
	s_setprio 3
	s_barrier
; #define PG8_STAGE(bufoff, gbase, voff) do { _Pragma("unroll") for (int _i = 0; _i < 2; ++_i) \
;         __builtin_amdgcn_global_load_lds((const unsigned*)((const char*)(gbase) + (voff)[_i]), (PG8_LAS unsigned*)(lds + (bufoff) + ldsw + _i * 8192), 16, 0, 0); } while (0)
; #define PG8_LDA(dst, b, h) do { _Pragma("unroll") for (int m = 0; m < 4; ++m) _Pragma("unroll") for (int k = 0; k < 2; ++k) dst[m][k] = *(const PG8_LAS bf16x8*)(lds + PG8_SA(b, h) + aoff + m * 2048 + k * 1024); } while (0)
; #define PG8_LDB(dst, b, h) do { _Pragma("unroll") for (int n = 0; n < 2; ++n) _Pragma("unroll") for (int k = 0; k < 2; ++k) dst[n][k] = *(const PG8_LAS bf16x8*)(lds + PG8_SB(b, h) + boff + n * 2048 + k * 1024); } while (0)
; #define PG8_MMA(ai, bj, At, Bt) do { __builtin_amdgcn_s_setprio(1); _Pragma("unroll") for (int m = 0; m < 4; ++m) _Pragma("unroll") for (int n = 0; n < 2; ++n) _Pragma("unroll") for (int k = 0; k < 2; ++k) \
;         acc[ai][bj][m][n] = __builtin_amdgcn_mfma_f32_16x16x32_bf16(Bt[n][k], At[m][k], acc[ai][bj][m][n], 0, 0, 0); __builtin_amdgcn_s_setprio(0); } while (0)
; #define PG8_WAIT_V(n) asm volatile("s_waitcnt vmcnt(" #n ")" ::: "memory")
; #define PG8_WAIT_L(n) asm volatile("s_waitcnt lgkmcnt(" #n ")" ::: "memory")
; #define PG8_BAR __builtin_amdgcn_s_barrier()
; #define PG8_SCHED __builtin_amdgcn_sched_barrier(0)
; template <class Epi, class Sched, bool ALIGN_EPI = false, bool SP2 = false, bool PAIR_ACC = false>
; __device__ __forceinline__ void gemm_phase(PG8_LAS unsigned char* lds, const Gemm g, const Sched& S, const Epi& E) {
;     ...
;             PG8_WAIT_V(8); PG8_WAIT_L(0); PG8_BAR; PG8_MMA(1, 0, At, B0); PG8_MMA(1, 1, At, B1); PG8_BAR; PG8_SCHED;
;             PG8_LDB(B0, 1, 0); PG8_LDB(B1, 1, 1); PG8_SCHED; PG8_LDA(At, 1, 0); PG8_STAGE(PG8_SA(0, 1), a2 + hstep, voffA);
;             PG8_WAIT_V(8); PG8_WAIT_L(0); PG8_BAR; PG8_MMA(0, 0, At, B0); PG8_MMA(0, 1, At, B1); PG8_BAR; PG8_SCHED;
	v_mfma_f32_16x16x32_bf16 v[86:89], v[152:155], v[194:197], v[86:89]
	v_mfma_f32_16x16x32_bf16 v[82:85], v[160:163], v[194:197], v[82:85]
	v_mfma_f32_16x16x32_bf16 v[78:81], v[152:155], v[210:213], v[78:81]
	v_mfma_f32_16x16x32_bf16 v[74:77], v[160:163], v[210:213], v[74:77]
	v_mfma_f32_16x16x32_bf16 v[30:33], v[152:155], v[218:221], v[30:33]
	v_mfma_f32_16x16x32_bf16 v[26:29], v[160:163], v[218:221], v[26:29]
	v_mfma_f32_16x16x32_bf16 v[14:17], v[152:155], v[226:229], v[14:17]
	v_mfma_f32_16x16x32_bf16 v[10:13], v[160:163], v[226:229], v[10:13]
	v_mfma_f32_16x16x32_bf16 v[86:89], v[156:159], v[206:209], v[86:89]
	v_mfma_f32_16x16x32_bf16 v[82:85], v[174:177], v[206:209], v[82:85]
	v_mfma_f32_16x16x32_bf16 v[78:81], v[156:159], v[214:217], v[78:81]
	v_mfma_f32_16x16x32_bf16 v[74:77], v[174:177], v[214:217], v[74:77]
	v_mfma_f32_16x16x32_bf16 v[30:33], v[156:159], v[222:225], v[30:33]
	v_mfma_f32_16x16x32_bf16 v[26:29], v[174:177], v[222:225], v[26:29]
	v_mfma_f32_16x16x32_bf16 v[14:17], v[156:159], v[230:233], v[14:17]
	v_mfma_f32_16x16x32_bf16 v[10:13], v[174:177], v[230:233], v[10:13]
	v_mfma_f32_16x16x32_bf16 v[46:49], v[178:181], v[194:197], v[46:49]
	v_mfma_f32_16x16x32_bf16 v[42:45], v[186:189], v[194:197], v[42:45]
	v_mfma_f32_16x16x32_bf16 v[38:41], v[178:181], v[210:213], v[38:41]
	v_mfma_f32_16x16x32_bf16 v[34:37], v[186:189], v[210:213], v[34:37]
	v_mfma_f32_16x16x32_bf16 v[22:25], v[178:181], v[218:221], v[22:25]
	v_mfma_f32_16x16x32_bf16 v[18:21], v[186:189], v[218:221], v[18:21]
	v_mfma_f32_16x16x32_bf16 v[6:9], v[178:181], v[226:229], v[6:9]
	v_mfma_f32_16x16x32_bf16 v[2:5], v[186:189], v[226:229], v[2:5]
	v_mfma_f32_16x16x32_bf16 v[46:49], v[182:185], v[206:209], v[46:49]
	v_mfma_f32_16x16x32_bf16 v[42:45], v[190:193], v[206:209], v[42:45]
	v_mfma_f32_16x16x32_bf16 v[38:41], v[182:185], v[214:217], v[38:41]
	v_mfma_f32_16x16x32_bf16 v[34:37], v[190:193], v[214:217], v[34:37]
	v_mfma_f32_16x16x32_bf16 v[22:25], v[182:185], v[222:225], v[22:25]
	v_mfma_f32_16x16x32_bf16 v[18:21], v[190:193], v[222:225], v[18:21]
	v_mfma_f32_16x16x32_bf16 v[6:9], v[182:185], v[230:233], v[6:9]
	v_mfma_f32_16x16x32_bf16 v[2:5], v[190:193], v[230:233], v[2:5]
	s_barrier
	s_setprio 0
	s_add_i32 s65, 0, 0x18000
	v_add_u32_e32 v167, s65, v150
	s_add_i32 s66, 0, 0x1c000
	ds_read_b128 v[152:155], v167
	ds_read_b128 v[156:159], v167 offset:1024
	ds_read_b128 v[160:163], v167 offset:2048
	ds_read_b128 v[174:177], v167 offset:3072
	v_add_u32_e32 v167, s66, v150
	ds_read_b128 v[178:181], v167
	ds_read_b128 v[182:185], v167 offset:1024
	ds_read_b128 v[186:189], v167 offset:2048
	ds_read_b128 v[190:193], v167 offset:3072
	s_add_u32 s54, s54, 0x40000
	s_addc_u32 s55, s55, 0
	s_mov_b32 m0, s44
	v_lshl_add_u64 v[236:237], s[54:55], 0, v[130:131]
	ds_read_b128 v[194:197], v151 offset:32768
	ds_read_b128 v[206:209], v151 offset:33792
	ds_read_b128 v[210:213], v151 offset:34816
	ds_read_b128 v[214:217], v151 offset:35840
	ds_read_b128 v[218:221], v151 offset:36864
	ds_read_b128 v[222:225], v151 offset:37888
	ds_read_b128 v[226:229], v151 offset:38912
	ds_read_b128 v[230:233], v151 offset:39936
	global_load_lds_dwordx4 v[236:237], off
	v_lshl_add_u64 v[236:237], s[54:55], 0, v[134:135]
	s_mov_b32 m0, s45
	s_nop 0
	global_load_lds_dwordx4 v[236:237], off
	s_waitcnt vmcnt(8)
	s_waitcnt lgkmcnt(0)
	s_setprio 3
	s_barrier
	v_mfma_f32_16x16x32_bf16 v[122:125], v[152:155], v[194:197], v[122:125]
	v_mfma_f32_16x16x32_bf16 v[126:129], v[160:163], v[194:197], v[126:129]
	v_mfma_f32_16x16x32_bf16 v[110:113], v[152:155], v[210:213], v[110:113]
	v_mfma_f32_16x16x32_bf16 v[106:109], v[160:163], v[210:213], v[106:109]
	v_mfma_f32_16x16x32_bf16 v[102:105], v[152:155], v[218:221], v[102:105]
	v_mfma_f32_16x16x32_bf16 v[98:101], v[160:163], v[218:221], v[98:101]
	v_mfma_f32_16x16x32_bf16 v[94:97], v[152:155], v[226:229], v[94:97]
	v_mfma_f32_16x16x32_bf16 v[90:93], v[160:163], v[226:229], v[90:93]
	v_mfma_f32_16x16x32_bf16 v[122:125], v[156:159], v[206:209], v[122:125]
	v_mfma_f32_16x16x32_bf16 v[126:129], v[174:177], v[206:209], v[126:129]
	v_mfma_f32_16x16x32_bf16 v[110:113], v[156:159], v[214:217], v[110:113]
	v_mfma_f32_16x16x32_bf16 v[106:109], v[174:177], v[214:217], v[106:109]
	v_mfma_f32_16x16x32_bf16 v[102:105], v[156:159], v[222:225], v[102:105]
	v_mfma_f32_16x16x32_bf16 v[98:101], v[174:177], v[222:225], v[98:101]
	v_mfma_f32_16x16x32_bf16 v[94:97], v[156:159], v[230:233], v[94:97]
	v_mfma_f32_16x16x32_bf16 v[90:93], v[174:177], v[230:233], v[90:93]
	v_mfma_f32_16x16x32_bf16 v[118:121], v[178:181], v[194:197], v[118:121]
	v_mfma_f32_16x16x32_bf16 v[114:117], v[186:189], v[194:197], v[114:117]
	v_mfma_f32_16x16x32_bf16 v[70:73], v[178:181], v[210:213], v[70:73]
	v_mfma_f32_16x16x32_bf16 v[66:69], v[186:189], v[210:213], v[66:69]
	v_mfma_f32_16x16x32_bf16 v[62:65], v[178:181], v[218:221], v[62:65]
	v_mfma_f32_16x16x32_bf16 v[58:61], v[186:189], v[218:221], v[58:61]
	v_mfma_f32_16x16x32_bf16 v[54:57], v[178:181], v[226:229], v[54:57]
	v_mfma_f32_16x16x32_bf16 v[50:53], v[186:189], v[226:229], v[50:53]
	v_mfma_f32_16x16x32_bf16 v[118:121], v[182:185], v[206:209], v[118:121]
	v_mfma_f32_16x16x32_bf16 v[114:117], v[190:193], v[206:209], v[114:117]
	v_mfma_f32_16x16x32_bf16 v[70:73], v[182:185], v[214:217], v[70:73]
	v_mfma_f32_16x16x32_bf16 v[66:69], v[190:193], v[214:217], v[66:69]
	v_mfma_f32_16x16x32_bf16 v[62:65], v[182:185], v[222:225], v[62:65]
	v_mfma_f32_16x16x32_bf16 v[58:61], v[190:193], v[222:225], v[58:61]
	v_mfma_f32_16x16x32_bf16 v[54:57], v[182:185], v[230:233], v[54:57]
	v_mfma_f32_16x16x32_bf16 v[50:53], v[190:193], v[230:233], v[50:53]
	s_barrier
; #define PG8_STAGE(bufoff, gbase, voff) do { _Pragma("unroll") for (int _i = 0; _i < 2; ++_i) \
;         __builtin_amdgcn_global_load_lds((const unsigned*)((const char*)(gbase) + (voff)[_i]), (PG8_LAS unsigned*)(lds + (bufoff) + ldsw + _i * 8192), 16, 0, 0); } while (0)
; #define PG8_LDA(dst, b, h) do { _Pragma("unroll") for (int m = 0; m < 4; ++m) _Pragma("unroll") for (int k = 0; k < 2; ++k) dst[m][k] = *(const PG8_LAS bf16x8*)(lds + PG8_SA(b, h) + aoff + m * 2048 + k * 1024); } while (0)
; #define PG8_MMA(ai, bj, At, Bt) do { __builtin_amdgcn_s_setprio(1); _Pragma("unroll") for (int m = 0; m < 4; ++m) _Pragma("unroll") for (int n = 0; n < 2; ++n) _Pragma("unroll") for (int k = 0; k < 2; ++k) \
;         acc[ai][bj][m][n] = __builtin_amdgcn_mfma_f32_16x16x32_bf16(Bt[n][k], At[m][k], acc[ai][bj][m][n], 0, 0, 0); __builtin_amdgcn_s_setprio(0); } while (0)
; #define PG8_WAIT_V(n) asm volatile("s_waitcnt vmcnt(" #n ")" ::: "memory")
; #define PG8_WAIT_L(n) asm volatile("s_waitcnt lgkmcnt(" #n ")" ::: "memory")
; #define PG8_BAR __builtin_amdgcn_s_barrier()
; #define PG8_SCHED __builtin_amdgcn_sched_barrier(0)
; template <class Epi, class Sched, bool ALIGN_EPI = false, bool SP2 = false, bool PAIR_ACC = false>
; __device__ __forceinline__ void gemm_phase(PG8_LAS unsigned char* lds, const Gemm g, const Sched& S, const Epi& E) {
;     ...
;             PG8_LDA(At, 1, 1); PG8_STAGE(PG8_SB(1, 0), b3, voffB); PG8_STAGE(PG8_SB(1, 1), b3 + hstep, voffB); PG8_STAGE(PG8_SA(1, 0), a3, voffA);
;             PG8_WAIT_V(8); PG8_WAIT_L(0); PG8_BAR; PG8_MMA(1, 0, At, B0); PG8_MMA(1, 1, At, B1); PG8_BAR; PG8_SCHED;
;     ...
;         if (!(PAIR_ACC && cur.pn < 4)) {
; #pragma unroll
;         for (int a = 0; a < 2; ++a)
; #pragma unroll
;             for (int b = 0; b < 2; ++b)
; #pragma unroll
;                 for (int m = 0; m < 4; ++m)
; #pragma unroll
;                     for (int n = 0; n < 2; ++n) acc[a][b][m][n] = (f32x4){0.f, 0.f, 0.f, 0.f};
	s_setprio 0
	s_add_i32 s54, s65, s37
	v_lshl_add_u64 v[164:165], v[164:165], 0, s[28:29]
	s_mov_b32 m0, s54
	ds_read_b128 v[194:197], v151 offset:49152
	ds_read_b128 v[206:209], v151 offset:50176
	ds_read_b128 v[210:213], v151 offset:51200
	ds_read_b128 v[214:217], v151 offset:52224
	ds_read_b128 v[218:221], v151 offset:53248
	ds_read_b128 v[222:225], v151 offset:54272
	ds_read_b128 v[226:229], v151 offset:55296
	ds_read_b128 v[230:233], v151 offset:56320
	global_load_lds_dwordx4 v[164:165], off
	s_add_i32 m0, s54, 0x2000
	s_add_u32 s38, s38, 0x40080
	v_lshl_add_u64 v[164:165], v[168:169], 0, s[28:29]
	s_addc_u32 s39, s39, 0
	s_add_i32 s54, s66, s37
	global_load_lds_dwordx4 v[164:165], off
	v_lshl_add_u64 v[164:165], s[38:39], 0, v[132:133]
	s_mov_b32 m0, s54
	s_nop 0
	global_load_lds_dwordx4 v[164:165], off
	v_lshl_add_u64 v[164:165], s[38:39], 0, v[136:137]
	s_add_i32 m0, s54, 0x2000
	s_nop 0
	global_load_lds_dwordx4 v[164:165], off
	v_lshl_add_u64 v[164:165], v[198:199], 0, s[28:29]
	s_mov_b32 m0, s47
	s_nop 0
	global_load_lds_dwordx4 v[164:165], off
	v_lshl_add_u64 v[164:165], v[234:235], 0, s[28:29]
	s_mov_b32 m0, s56
	s_nop 0
	global_load_lds_dwordx4 v[164:165], off
	s_waitcnt vmcnt(8)
	s_waitcnt lgkmcnt(0)
	s_setprio 3
	s_barrier
	v_mfma_f32_16x16x32_bf16 v[86:89], v[152:155], v[194:197], v[86:89]
	v_mfma_f32_16x16x32_bf16 v[82:85], v[160:163], v[194:197], v[82:85]
	v_mfma_f32_16x16x32_bf16 v[78:81], v[152:155], v[210:213], v[78:81]
	v_mfma_f32_16x16x32_bf16 v[74:77], v[160:163], v[210:213], v[74:77]
	v_mfma_f32_16x16x32_bf16 v[30:33], v[152:155], v[218:221], v[30:33]
	v_mfma_f32_16x16x32_bf16 v[26:29], v[160:163], v[218:221], v[26:29]
	v_mfma_f32_16x16x32_bf16 v[14:17], v[152:155], v[226:229], v[14:17]
	v_mfma_f32_16x16x32_bf16 v[10:13], v[160:163], v[226:229], v[10:13]
	v_mfma_f32_16x16x32_bf16 v[86:89], v[156:159], v[206:209], v[86:89]
	v_mfma_f32_16x16x32_bf16 v[82:85], v[174:177], v[206:209], v[82:85]
	v_mfma_f32_16x16x32_bf16 v[78:81], v[156:159], v[214:217], v[78:81]
	v_mfma_f32_16x16x32_bf16 v[74:77], v[174:177], v[214:217], v[74:77]
	v_mfma_f32_16x16x32_bf16 v[30:33], v[156:159], v[222:225], v[30:33]
	v_mfma_f32_16x16x32_bf16 v[26:29], v[174:177], v[222:225], v[26:29]
	v_mfma_f32_16x16x32_bf16 v[14:17], v[156:159], v[230:233], v[14:17]
	v_mfma_f32_16x16x32_bf16 v[10:13], v[174:177], v[230:233], v[10:13]
	v_mfma_f32_16x16x32_bf16 v[46:49], v[178:181], v[194:197], v[46:49]
	v_mfma_f32_16x16x32_bf16 v[42:45], v[186:189], v[194:197], v[42:45]
	v_mfma_f32_16x16x32_bf16 v[38:41], v[178:181], v[210:213], v[38:41]
	v_mfma_f32_16x16x32_bf16 v[34:37], v[186:189], v[210:213], v[34:37]
	v_mfma_f32_16x16x32_bf16 v[22:25], v[178:181], v[218:221], v[22:25]
	v_mfma_f32_16x16x32_bf16 v[18:21], v[186:189], v[218:221], v[18:21]
	v_mfma_f32_16x16x32_bf16 v[6:9], v[178:181], v[226:229], v[6:9]
	v_mfma_f32_16x16x32_bf16 v[2:5], v[186:189], v[226:229], v[2:5]
	v_mfma_f32_16x16x32_bf16 v[46:49], v[182:185], v[206:209], v[46:49]
	v_mfma_f32_16x16x32_bf16 v[42:45], v[190:193], v[206:209], v[42:45]
	v_mfma_f32_16x16x32_bf16 v[38:41], v[182:185], v[214:217], v[38:41]
	v_mfma_f32_16x16x32_bf16 v[34:37], v[190:193], v[214:217], v[34:37]
	v_mfma_f32_16x16x32_bf16 v[22:25], v[182:185], v[222:225], v[22:25]
	v_mfma_f32_16x16x32_bf16 v[18:21], v[190:193], v[222:225], v[18:21]
	v_mfma_f32_16x16x32_bf16 v[6:9], v[182:185], v[230:233], v[6:9]
	v_mfma_f32_16x16x32_bf16 v[2:5], v[190:193], v[230:233], v[2:5]
	s_barrier
	s_setprio 0
	s_add_i32 s64, s64, 2
	s_add_u32 s52, s52, 0x100
	s_addc_u32 s53, s53, 0
	s_cmp_gt_u32 s64, 13
	s_cbranch_scc0 .LBB0_727
	s_add_u32 s38, s60, 0xffffff00
	s_addc_u32 s39, s61, -1
	s_andn2_b64 vcc, exec, s[8:9]
	s_cbranch_vccnz .LBB0_718
	v_mov_b32_e32 v2, 0
	s_mov_b32 s10, s30
	s_mov_b32 s16, s42
	s_mov_b64 s[20:21], s[50:51]
	s_mov_b32 s46, s59
	v_mov_b32_e32 v3, v2
	v_mov_b32_e32 v4, v2
	v_mov_b32_e32 v5, v2
	v_mov_b32_e32 v6, v2
	v_mov_b32_e32 v7, v2
	v_mov_b32_e32 v8, v2
	v_mov_b32_e32 v9, v2
	v_mov_b32_e32 v18, v2
	v_mov_b32_e32 v19, v2
	v_mov_b32_e32 v20, v2
	v_mov_b32_e32 v21, v2
	v_mov_b32_e32 v22, v2
	v_mov_b32_e32 v23, v2
	v_mov_b32_e32 v24, v2
	v_mov_b32_e32 v25, v2
	v_mov_b32_e32 v34, v2
	v_mov_b32_e32 v35, v2
	v_mov_b32_e32 v36, v2
	v_mov_b32_e32 v37, v2
	v_mov_b32_e32 v38, v2
	v_mov_b32_e32 v39, v2
	v_mov_b32_e32 v40, v2
	v_mov_b32_e32 v41, v2
	v_mov_b32_e32 v42, v2
	v_mov_b32_e32 v43, v2
	v_mov_b32_e32 v44, v2
	v_mov_b32_e32 v45, v2
	v_mov_b32_e32 v46, v2
	v_mov_b32_e32 v47, v2
	v_mov_b32_e32 v48, v2
	v_mov_b32_e32 v49, v2
	v_mov_b32_e32 v10, v2
	v_mov_b32_e32 v11, v2
	v_mov_b32_e32 v12, v2
	v_mov_b32_e32 v13, v2
	v_mov_b32_e32 v14, v2
	v_mov_b32_e32 v15, v2
	v_mov_b32_e32 v16, v2
	v_mov_b32_e32 v17, v2
	v_mov_b32_e32 v26, v2
	v_mov_b32_e32 v27, v2
	v_mov_b32_e32 v28, v2
	v_mov_b32_e32 v29, v2
	v_mov_b32_e32 v30, v2
	v_mov_b32_e32 v31, v2
	v_mov_b32_e32 v32, v2
	v_mov_b32_e32 v33, v2
	v_mov_b32_e32 v74, v2
	v_mov_b32_e32 v75, v2
	v_mov_b32_e32 v76, v2
	v_mov_b32_e32 v77, v2
	v_mov_b32_e32 v78, v2
	v_mov_b32_e32 v79, v2
	v_mov_b32_e32 v80, v2
	v_mov_b32_e32 v81, v2
	v_mov_b32_e32 v82, v2
	v_mov_b32_e32 v83, v2
	v_mov_b32_e32 v84, v2
	v_mov_b32_e32 v85, v2
	v_mov_b32_e32 v86, v2
	v_mov_b32_e32 v87, v2
	v_mov_b32_e32 v88, v2
	v_mov_b32_e32 v89, v2
	v_mov_b32_e32 v50, v2
	v_mov_b32_e32 v51, v2
	v_mov_b32_e32 v52, v2
	v_mov_b32_e32 v53, v2
	v_mov_b32_e32 v54, v2
	v_mov_b32_e32 v55, v2
	v_mov_b32_e32 v56, v2
	v_mov_b32_e32 v57, v2
	v_mov_b32_e32 v58, v2
	v_mov_b32_e32 v59, v2
	v_mov_b32_e32 v60, v2
	v_mov_b32_e32 v61, v2
	v_mov_b32_e32 v62, v2
	v_mov_b32_e32 v63, v2
	v_mov_b32_e32 v64, v2
	v_mov_b32_e32 v65, v2
	v_mov_b32_e32 v66, v2
	v_mov_b32_e32 v67, v2
	v_mov_b32_e32 v68, v2
	v_mov_b32_e32 v69, v2
	v_mov_b32_e32 v70, v2
	v_mov_b32_e32 v71, v2
	v_mov_b32_e32 v72, v2
	v_mov_b32_e32 v73, v2
	v_mov_b32_e32 v114, v2
	v_mov_b32_e32 v115, v2
	v_mov_b32_e32 v116, v2
	v_mov_b32_e32 v117, v2
	v_mov_b32_e32 v118, v2
	v_mov_b32_e32 v119, v2
	v_mov_b32_e32 v120, v2
	v_mov_b32_e32 v121, v2
	v_mov_b32_e32 v90, v2
	v_mov_b32_e32 v91, v2
	v_mov_b32_e32 v92, v2
	v_mov_b32_e32 v93, v2
	v_mov_b32_e32 v94, v2
	v_mov_b32_e32 v95, v2
	v_mov_b32_e32 v96, v2
	v_mov_b32_e32 v97, v2
	v_mov_b32_e32 v98, v2
	v_mov_b32_e32 v99, v2
	v_mov_b32_e32 v100, v2
	v_mov_b32_e32 v101, v2
	v_mov_b32_e32 v102, v2
	v_mov_b32_e32 v103, v2
	v_mov_b32_e32 v104, v2
	v_mov_b32_e32 v105, v2
	v_mov_b32_e32 v106, v2
	v_mov_b32_e32 v107, v2
	v_mov_b32_e32 v108, v2
	v_mov_b32_e32 v109, v2
	v_mov_b32_e32 v110, v2
	v_mov_b32_e32 v111, v2
	v_mov_b32_e32 v112, v2
	v_mov_b32_e32 v113, v2
	v_mov_b32_e32 v126, v2
	v_mov_b32_e32 v127, v2
	v_mov_b32_e32 v128, v2
	v_mov_b32_e32 v129, v2
	v_mov_b32_e32 v122, v2
	v_mov_b32_e32 v123, v2
	v_mov_b32_e32 v124, v2
	v_mov_b32_e32 v125, v2
	s_andn2_b64 vcc, exec, s[6:7]
	s_cbranch_vccnz .LBB0_719

; #define PG8_STAGE(bufoff, gbase, voff) do { _Pragma("unroll") for (int _i = 0; _i < 2; ++_i) \
;         __builtin_amdgcn_global_load_lds((const unsigned*)((const char*)(gbase) + (voff)[_i]), (PG8_LAS unsigned*)(lds + (bufoff) + ldsw + _i * 8192), 16, 0, 0); } while (0)
; #define PG8_LDA(dst, b, h) do { _Pragma("unroll") for (int m = 0; m < 4; ++m) _Pragma("unroll") for (int k = 0; k < 2; ++k) dst[m][k] = *(const PG8_LAS bf16x8*)(lds + PG8_SA(b, h) + aoff + m * 2048 + k * 1024); } while (0)
; #define PG8_LDB(dst, b, h) do { _Pragma("unroll") for (int n = 0; n < 2; ++n) _Pragma("unroll") for (int k = 0; k < 2; ++k) dst[n][k] = *(const PG8_LAS bf16x8*)(lds + PG8_SB(b, h) + boff + n * 2048 + k * 1024); } while (0)
; #define PG8_WAIT_V(n) asm volatile("s_waitcnt vmcnt(" #n ")" ::: "memory")
; #define PG8_WAIT_L(n) asm volatile("s_waitcnt lgkmcnt(" #n ")" ::: "memory")
; #define PG8_BAR __builtin_amdgcn_s_barrier()
; template <class Epi, class Sched, bool ALIGN_EPI = false, bool SP2 = false, bool PAIR_ACC = false>
; __device__ __forceinline__ void gemm_phase(PG8_LAS unsigned char* lds, const Gemm g, const Sched& S, const Epi& E) {
;     ...
;         const bool has_next = S.next(ui + 1, nxt);
;         const char* nA = has_next ? (const char*)g.A + (size_t)nxt.pm * tstep + (size_t)(nxt.pn / g.a_div) * g.a_sel : cA; const char* nB = has_next ? (const char*)g.Bt + (size_t)nxt.pn * tstep : cB;
;         for (int t = 0; t < nt; t += 2) {
;             const bool last = (t == nt - 2);
;             const char* a1 = cA + (size_t)(t + 1) * kstep;
;             const char* a2 = last ? nA : cA + (size_t)(t + 2) * kstep; const char* b2 = last ? nB : cB + (size_t)(t + 2) * kstep;
;             const char* a3 = a2 + kstep; const char* b3 = b2 + kstep;
;             if (last && has_next) S.a_ready(nxt);
;             if constexpr (SP2) {
;             PG8_LDB(B0, 0, 0); PG8_LDB(B1, 0, 1); PG8_SCHED; PG8_LDA(At, 0, 0); PG8_STAGE(PG8_SA(1, 1), a1 + hstep, voffA);
;             PG8_WAIT_V(8); PG8_WAIT_L(0); PG8_BAR; PG8_MMA(0, 0, At, B0); PG8_MMA(0, 1, At, B1); PG8_BAR; PG8_SCHED;
;             PG8_LDA(At, 0, 1); PG8_STAGE(PG8_SB(0, 0), b2, voffB); PG8_STAGE(PG8_SB(0, 1), b2 + hstep, voffB); PG8_STAGE(PG8_SA(0, 0), a2, voffA);
;             PG8_WAIT_V(8); PG8_WAIT_L(0); PG8_BAR; PG8_MMA(1, 0, At, B0); PG8_MMA(1, 1, At, B1); PG8_BAR; PG8_SCHED;
.LBB0_833:
	s_ashr_i32 s65, s64, 31
	s_lshl_b64 s[40:41], s[64:65], 19
	s_add_u32 s66, s4, s40
	s_addc_u32 s67, s5, s41
	s_and_b64 s[40:41], s[8:9], exec
	s_cselect_b32 s40, s67, s11
	s_cselect_b32 s41, s66, s10
	s_ashr_i32 s63, s62, 31
	s_lshl_b64 s[68:69], s[62:63], 19
	s_add_u32 s68, s23, s68
	s_addc_u32 s69, s24, s69
	s_and_b64 s[72:73], s[8:9], exec
	s_cselect_b32 s63, s69, s39
	s_cselect_b32 s65, s68, s38
	s_add_u32 s10, s10, 0x40080
	s_addc_u32 s11, s11, 0
	s_add_u32 s78, s38, 0x100
	s_addc_u32 s79, s39, 0
	s_mov_b32 s80, -2
	ds_read_b128 v[74:77], v197
	ds_read_b128 v[78:81], v197 offset:1024
	ds_read_b128 v[82:85], v197 offset:2048
	ds_read_b128 v[86:89], v197 offset:3072
	ds_read_b128 v[90:93], v198
	ds_read_b128 v[94:97], v198 offset:1024
	ds_read_b128 v[98:101], v198 offset:2048
	ds_read_b128 v[106:109], v198 offset:3072
	s_add_u32 s38, s10, 0xfffc0080
	s_addc_u32 s39, s11, -1
	s_cmp_eq_u32 s80, 12
	s_cselect_b32 s73, s40, s39
	s_cselect_b32 s72, s41, s38
	s_cselect_b32 s39, s63, s79
	s_cselect_b32 s38, s65, s78
	v_lshl_add_u64 v[170:171], s[10:11], 0, v[186:187]
	s_add_i32 m0, s36, 0xc000
	ds_read_b128 v[162:165], v199
	ds_read_b128 v[166:169], v199 offset:1024
	ds_read_b128 v[210:213], v199 offset:2048
	ds_read_b128 v[214:217], v199 offset:3072
	ds_read_b128 v[218:221], v199 offset:4096
	ds_read_b128 v[222:225], v199 offset:5120
	ds_read_b128 v[226:229], v199 offset:6144
	ds_read_b128 v[230:233], v199 offset:7168
	global_load_lds_dwordx4 v[170:171], off
	v_lshl_add_u64 v[170:171], s[10:11], 0, v[188:189]
	s_add_i32 m0, s36, 0xe000
	s_nop 0
	global_load_lds_dwordx4 v[170:171], off
	s_waitcnt vmcnt(8)
	s_waitcnt lgkmcnt(0)
	s_setprio 3
	s_barrier
	v_mfma_f32_16x16x32_bf16 v[150:153], v[74:77], v[162:165], 0
	v_mfma_f32_16x16x32_bf16 v[146:149], v[82:85], v[162:165], 0
	v_mfma_f32_16x16x32_bf16 v[134:137], v[74:77], v[210:213], 0
	v_mfma_f32_16x16x32_bf16 v[130:133], v[82:85], v[210:213], 0
	v_mfma_f32_16x16x32_bf16 v[118:121], v[74:77], v[218:221], 0
	v_mfma_f32_16x16x32_bf16 v[110:113], v[82:85], v[218:221], 0
	v_mfma_f32_16x16x32_bf16 v[114:117], v[74:77], v[226:229], 0
	v_mfma_f32_16x16x32_bf16 v[102:105], v[82:85], v[226:229], 0
	v_mfma_f32_16x16x32_bf16 v[150:153], v[78:81], v[166:169], v[150:153]
	v_mfma_f32_16x16x32_bf16 v[146:149], v[86:89], v[166:169], v[146:149]
	v_mfma_f32_16x16x32_bf16 v[134:137], v[78:81], v[214:217], v[134:137]
	v_mfma_f32_16x16x32_bf16 v[130:133], v[86:89], v[214:217], v[130:133]
	v_mfma_f32_16x16x32_bf16 v[118:121], v[78:81], v[222:225], v[118:121]
	v_mfma_f32_16x16x32_bf16 v[110:113], v[86:89], v[222:225], v[110:113]
	v_mfma_f32_16x16x32_bf16 v[114:117], v[78:81], v[230:233], v[114:117]
	v_mfma_f32_16x16x32_bf16 v[102:105], v[86:89], v[230:233], v[102:105]
	v_mfma_f32_16x16x32_bf16 v[158:161], v[90:93], v[162:165], 0
	v_mfma_f32_16x16x32_bf16 v[154:157], v[98:101], v[162:165], 0
	v_mfma_f32_16x16x32_bf16 v[142:145], v[90:93], v[210:213], 0
	v_mfma_f32_16x16x32_bf16 v[138:141], v[98:101], v[210:213], 0
	v_mfma_f32_16x16x32_bf16 v[126:129], v[90:93], v[218:221], 0
	v_mfma_f32_16x16x32_bf16 v[122:125], v[98:101], v[218:221], 0
	v_mfma_f32_16x16x32_bf16 v[70:73], v[90:93], v[226:229], 0
	v_mfma_f32_16x16x32_bf16 v[66:69], v[98:101], v[226:229], 0
	v_mfma_f32_16x16x32_bf16 v[158:161], v[94:97], v[166:169], v[158:161]
	v_mfma_f32_16x16x32_bf16 v[154:157], v[106:109], v[166:169], v[154:157]
	v_mfma_f32_16x16x32_bf16 v[142:145], v[94:97], v[214:217], v[142:145]
	v_mfma_f32_16x16x32_bf16 v[138:141], v[106:109], v[214:217], v[138:141]
	v_mfma_f32_16x16x32_bf16 v[126:129], v[94:97], v[222:225], v[126:129]
	v_mfma_f32_16x16x32_bf16 v[122:125], v[106:109], v[222:225], v[122:125]
	v_mfma_f32_16x16x32_bf16 v[70:73], v[94:97], v[230:233], v[70:73]
	v_mfma_f32_16x16x32_bf16 v[66:69], v[106:109], v[230:233], v[66:69]
	s_barrier
	s_setprio 0
	s_add_i32 s81, s61, s25
	v_lshl_add_u64 v[170:171], s[38:39], 0, v[178:179]
	s_mov_b32 m0, s81
	ds_read_b128 v[162:165], v199 offset:16384
	ds_read_b128 v[166:169], v199 offset:17408
	ds_read_b128 v[210:213], v199 offset:18432
	ds_read_b128 v[214:217], v199 offset:19456
	ds_read_b128 v[218:221], v199 offset:20480
	ds_read_b128 v[222:225], v199 offset:21504
	ds_read_b128 v[226:229], v199 offset:22528
	ds_read_b128 v[230:233], v199 offset:23552
	global_load_lds_dwordx4 v[170:171], off
	s_add_i32 m0, s81, 0x2000
	s_add_u32 s82, s38, 0x40000
	v_lshl_add_u64 v[194:195], s[38:39], 0, v[174:175]
	s_addc_u32 s83, s39, 0
	s_add_i32 s81, s74, s25
	global_load_lds_dwordx4 v[194:195], off
	v_lshl_add_u64 v[234:235], s[82:83], 0, v[178:179]
	s_mov_b32 m0, s81
	v_lshl_add_u64 v[236:237], s[72:73], 0, v[176:177]
	global_load_lds_dwordx4 v[234:235], off
	v_lshl_add_u64 v[234:235], s[82:83], 0, v[174:175]
	s_add_i32 m0, s81, 0x2000
	s_nop 0
	global_load_lds_dwordx4 v[234:235], off
	v_lshl_add_u64 v[234:235], s[72:73], 0, v[180:181]
	s_mov_b32 m0, s36
	s_nop 0
	global_load_lds_dwordx4 v[234:235], off
	s_mov_b32 m0, s37
	s_nop 0
	global_load_lds_dwordx4 v[236:237], off
	s_waitcnt vmcnt(8)
	s_waitcnt lgkmcnt(0)
	s_setprio 3
	s_barrier
; #define PG8_STAGE(bufoff, gbase, voff) do { _Pragma("unroll") for (int _i = 0; _i < 2; ++_i) \
;         __builtin_amdgcn_global_load_lds((const unsigned*)((const char*)(gbase) + (voff)[_i]), (PG8_LAS unsigned*)(lds + (bufoff) + ldsw + _i * 8192), 16, 0, 0); } while (0)
; #define PG8_LDA(dst, b, h) do { _Pragma("unroll") for (int m = 0; m < 4; ++m) _Pragma("unroll") for (int k = 0; k < 2; ++k) dst[m][k] = *(const PG8_LAS bf16x8*)(lds + PG8_SA(b, h) + aoff + m * 2048 + k * 1024); } while (0)
; #define PG8_LDB(dst, b, h) do { _Pragma("unroll") for (int n = 0; n < 2; ++n) _Pragma("unroll") for (int k = 0; k < 2; ++k) dst[n][k] = *(const PG8_LAS bf16x8*)(lds + PG8_SB(b, h) + boff + n * 2048 + k * 1024); } while (0)
; #define PG8_MMA(ai, bj, At, Bt) do { __builtin_amdgcn_s_setprio(1); _Pragma("unroll") for (int m = 0; m < 4; ++m) _Pragma("unroll") for (int n = 0; n < 2; ++n) _Pragma("unroll") for (int k = 0; k < 2; ++k) \
;         acc[ai][bj][m][n] = __builtin_amdgcn_mfma_f32_16x16x32_bf16(Bt[n][k], At[m][k], acc[ai][bj][m][n], 0, 0, 0); __builtin_amdgcn_s_setprio(0); } while (0)
; #define PG8_WAIT_V(n) asm volatile("s_waitcnt vmcnt(" #n ")" ::: "memory")
; #define PG8_BAR __builtin_amdgcn_s_barrier()
; template <class Epi, class Sched, bool ALIGN_EPI = false, bool SP2 = false, bool PAIR_ACC = false>
; __device__ __forceinline__ void gemm_phase(PG8_LAS unsigned char* lds, const Gemm g, const Sched& S, const Epi& E) {
;     ...
;         for (int t = 0; t < nt; t += 2) {
;             const bool last = (t == nt - 2);
;             const char* a1 = cA + (size_t)(t + 1) * kstep;
;             const char* a2 = last ? nA : cA + (size_t)(t + 2) * kstep; const char* b2 = last ? nB : cB + (size_t)(t + 2) * kstep;
;             const char* a3 = a2 + kstep; const char* b3 = b2 + kstep;
;             if (last && has_next) S.a_ready(nxt);
;             if constexpr (SP2) {
;             PG8_LDB(B0, 0, 0); PG8_LDB(B1, 0, 1); PG8_SCHED; PG8_LDA(At, 0, 0); PG8_STAGE(PG8_SA(1, 1), a1 + hstep, voffA);
;             PG8_WAIT_V(8); PG8_WAIT_L(0); PG8_BAR; PG8_MMA(0, 0, At, B0); PG8_MMA(0, 1, At, B1); PG8_BAR; PG8_SCHED;
;             PG8_LDA(At, 0, 1); PG8_STAGE(PG8_SB(0, 0), b2, voffB); PG8_STAGE(PG8_SB(0, 1), b2 + hstep, voffB); PG8_STAGE(PG8_SA(0, 0), a2, voffA);
;             PG8_WAIT_V(8); PG8_WAIT_L(0); PG8_BAR; PG8_MMA(1, 0, At, B0); PG8_MMA(1, 1, At, B1); PG8_BAR; PG8_SCHED;
	v_mfma_f32_16x16x32_bf16 v[54:57], v[74:77], v[162:165], 0
	v_mfma_f32_16x16x32_bf16 v[50:53], v[82:85], v[162:165], 0
	v_mfma_f32_16x16x32_bf16 v[38:41], v[74:77], v[210:213], 0
	v_mfma_f32_16x16x32_bf16 v[34:37], v[82:85], v[210:213], 0
	v_mfma_f32_16x16x32_bf16 v[22:25], v[74:77], v[218:221], 0
	v_mfma_f32_16x16x32_bf16 v[14:17], v[82:85], v[218:221], 0
	v_mfma_f32_16x16x32_bf16 v[18:21], v[74:77], v[226:229], 0
	v_mfma_f32_16x16x32_bf16 v[10:13], v[82:85], v[226:229], 0
	v_mfma_f32_16x16x32_bf16 v[54:57], v[78:81], v[166:169], v[54:57]
	v_mfma_f32_16x16x32_bf16 v[50:53], v[86:89], v[166:169], v[50:53]
	v_mfma_f32_16x16x32_bf16 v[38:41], v[78:81], v[214:217], v[38:41]
	v_mfma_f32_16x16x32_bf16 v[34:37], v[86:89], v[214:217], v[34:37]
	v_mfma_f32_16x16x32_bf16 v[22:25], v[78:81], v[222:225], v[22:25]
	v_mfma_f32_16x16x32_bf16 v[14:17], v[86:89], v[222:225], v[14:17]
	v_mfma_f32_16x16x32_bf16 v[18:21], v[78:81], v[230:233], v[18:21]
	v_mfma_f32_16x16x32_bf16 v[10:13], v[86:89], v[230:233], v[10:13]
	v_mfma_f32_16x16x32_bf16 v[62:65], v[90:93], v[162:165], 0
	v_mfma_f32_16x16x32_bf16 v[58:61], v[98:101], v[162:165], 0
	v_mfma_f32_16x16x32_bf16 v[46:49], v[90:93], v[210:213], 0
	v_mfma_f32_16x16x32_bf16 v[42:45], v[98:101], v[210:213], 0
	v_mfma_f32_16x16x32_bf16 v[30:33], v[90:93], v[218:221], 0
	v_mfma_f32_16x16x32_bf16 v[26:29], v[98:101], v[218:221], 0
	v_mfma_f32_16x16x32_bf16 v[6:9], v[90:93], v[226:229], 0
	v_mfma_f32_16x16x32_bf16 v[2:5], v[98:101], v[226:229], 0
	v_mfma_f32_16x16x32_bf16 v[62:65], v[94:97], v[166:169], v[62:65]
	v_mfma_f32_16x16x32_bf16 v[58:61], v[106:109], v[166:169], v[58:61]
	v_mfma_f32_16x16x32_bf16 v[46:49], v[94:97], v[214:217], v[46:49]
	v_mfma_f32_16x16x32_bf16 v[42:45], v[106:109], v[214:217], v[42:45]
	v_mfma_f32_16x16x32_bf16 v[30:33], v[94:97], v[222:225], v[30:33]
	v_mfma_f32_16x16x32_bf16 v[26:29], v[106:109], v[222:225], v[26:29]
	v_mfma_f32_16x16x32_bf16 v[6:9], v[94:97], v[230:233], v[6:9]
	v_mfma_f32_16x16x32_bf16 v[2:5], v[106:109], v[230:233], v[2:5]
	s_barrier
	s_setprio 0
	s_branch .Lpeel_mid_834
.LBB0_834:
	ds_read_b128 v[74:77], v197
	ds_read_b128 v[78:81], v197 offset:1024
	ds_read_b128 v[82:85], v197 offset:2048
	ds_read_b128 v[86:89], v197 offset:3072
	ds_read_b128 v[90:93], v198
	ds_read_b128 v[94:97], v198 offset:1024
	ds_read_b128 v[98:101], v198 offset:2048
	ds_read_b128 v[106:109], v198 offset:3072
	s_add_u32 s38, s10, 0xfffc0080
	s_addc_u32 s39, s11, -1
	s_cmp_eq_u32 s80, 12
	s_cselect_b32 s73, s40, s39
	s_cselect_b32 s72, s41, s38
	s_cselect_b32 s39, s63, s79
	s_cselect_b32 s38, s65, s78
	v_lshl_add_u64 v[170:171], s[10:11], 0, v[186:187]
	s_add_i32 m0, s36, 0xc000
	ds_read_b128 v[162:165], v199
	ds_read_b128 v[166:169], v199 offset:1024
	ds_read_b128 v[210:213], v199 offset:2048
	ds_read_b128 v[214:217], v199 offset:3072
	ds_read_b128 v[218:221], v199 offset:4096
	ds_read_b128 v[222:225], v199 offset:5120
	ds_read_b128 v[226:229], v199 offset:6144
	ds_read_b128 v[230:233], v199 offset:7168
	global_load_lds_dwordx4 v[170:171], off
	v_lshl_add_u64 v[170:171], s[10:11], 0, v[188:189]
	s_add_i32 m0, s36, 0xe000
	s_nop 0
	global_load_lds_dwordx4 v[170:171], off
	s_waitcnt vmcnt(8)
	s_waitcnt lgkmcnt(0)
	s_setprio 3
	s_barrier
	v_mfma_f32_16x16x32_bf16 v[150:153], v[74:77], v[162:165], v[150:153]
	v_mfma_f32_16x16x32_bf16 v[146:149], v[82:85], v[162:165], v[146:149]
	v_mfma_f32_16x16x32_bf16 v[134:137], v[74:77], v[210:213], v[134:137]
	v_mfma_f32_16x16x32_bf16 v[130:133], v[82:85], v[210:213], v[130:133]
	v_mfma_f32_16x16x32_bf16 v[118:121], v[74:77], v[218:221], v[118:121]
	v_mfma_f32_16x16x32_bf16 v[110:113], v[82:85], v[218:221], v[110:113]
	v_mfma_f32_16x16x32_bf16 v[114:117], v[74:77], v[226:229], v[114:117]
	v_mfma_f32_16x16x32_bf16 v[102:105], v[82:85], v[226:229], v[102:105]
	v_mfma_f32_16x16x32_bf16 v[150:153], v[78:81], v[166:169], v[150:153]
	v_mfma_f32_16x16x32_bf16 v[146:149], v[86:89], v[166:169], v[146:149]
	v_mfma_f32_16x16x32_bf16 v[134:137], v[78:81], v[214:217], v[134:137]
	v_mfma_f32_16x16x32_bf16 v[130:133], v[86:89], v[214:217], v[130:133]
	v_mfma_f32_16x16x32_bf16 v[118:121], v[78:81], v[222:225], v[118:121]
	v_mfma_f32_16x16x32_bf16 v[110:113], v[86:89], v[222:225], v[110:113]
	v_mfma_f32_16x16x32_bf16 v[114:117], v[78:81], v[230:233], v[114:117]
	v_mfma_f32_16x16x32_bf16 v[102:105], v[86:89], v[230:233], v[102:105]
	v_mfma_f32_16x16x32_bf16 v[158:161], v[90:93], v[162:165], v[158:161]
	v_mfma_f32_16x16x32_bf16 v[154:157], v[98:101], v[162:165], v[154:157]
	v_mfma_f32_16x16x32_bf16 v[142:145], v[90:93], v[210:213], v[142:145]
	v_mfma_f32_16x16x32_bf16 v[138:141], v[98:101], v[210:213], v[138:141]
	v_mfma_f32_16x16x32_bf16 v[126:129], v[90:93], v[218:221], v[126:129]
	v_mfma_f32_16x16x32_bf16 v[122:125], v[98:101], v[218:221], v[122:125]
	v_mfma_f32_16x16x32_bf16 v[70:73], v[90:93], v[226:229], v[70:73]
	v_mfma_f32_16x16x32_bf16 v[66:69], v[98:101], v[226:229], v[66:69]
	v_mfma_f32_16x16x32_bf16 v[158:161], v[94:97], v[166:169], v[158:161]
	v_mfma_f32_16x16x32_bf16 v[154:157], v[106:109], v[166:169], v[154:157]
	v_mfma_f32_16x16x32_bf16 v[142:145], v[94:97], v[214:217], v[142:145]
	v_mfma_f32_16x16x32_bf16 v[138:141], v[106:109], v[214:217], v[138:141]
	v_mfma_f32_16x16x32_bf16 v[126:129], v[94:97], v[222:225], v[126:129]
	v_mfma_f32_16x16x32_bf16 v[122:125], v[106:109], v[222:225], v[122:125]
	v_mfma_f32_16x16x32_bf16 v[70:73], v[94:97], v[230:233], v[70:73]
	v_mfma_f32_16x16x32_bf16 v[66:69], v[106:109], v[230:233], v[66:69]
	s_barrier
; #define PG8_STAGE(bufoff, gbase, voff) do { _Pragma("unroll") for (int _i = 0; _i < 2; ++_i) \
;         __builtin_amdgcn_global_load_lds((const unsigned*)((const char*)(gbase) + (voff)[_i]), (PG8_LAS unsigned*)(lds + (bufoff) + ldsw + _i * 8192), 16, 0, 0); } while (0)
; #define PG8_LDA(dst, b, h) do { _Pragma("unroll") for (int m = 0; m < 4; ++m) _Pragma("unroll") for (int k = 0; k < 2; ++k) dst[m][k] = *(const PG8_LAS bf16x8*)(lds + PG8_SA(b, h) + aoff + m * 2048 + k * 1024); } while (0)
; #define PG8_LDB(dst, b, h) do { _Pragma("unroll") for (int n = 0; n < 2; ++n) _Pragma("unroll") for (int k = 0; k < 2; ++k) dst[n][k] = *(const PG8_LAS bf16x8*)(lds + PG8_SB(b, h) + boff + n * 2048 + k * 1024); } while (0)
; #define PG8_MMA(ai, bj, At, Bt) do { __builtin_amdgcn_s_setprio(1); _Pragma("unroll") for (int m = 0; m < 4; ++m) _Pragma("unroll") for (int n = 0; n < 2; ++n) _Pragma("unroll") for (int k = 0; k < 2; ++k) \
;         acc[ai][bj][m][n] = __builtin_amdgcn_mfma_f32_16x16x32_bf16(Bt[n][k], At[m][k], acc[ai][bj][m][n], 0, 0, 0); __builtin_amdgcn_s_setprio(0); } while (0)
; #define PG8_WAIT_V(n) asm volatile("s_waitcnt vmcnt(" #n ")" ::: "memory")
; #define PG8_WAIT_L(n) asm volatile("s_waitcnt lgkmcnt(" #n ")" ::: "memory")
; #define PG8_BAR __builtin_amdgcn_s_barrier()
; #define PG8_SCHED __builtin_amdgcn_sched_barrier(0)
; template <class Epi, class Sched, bool ALIGN_EPI = false, bool SP2 = false, bool PAIR_ACC = false>
; __device__ __forceinline__ void gemm_phase(PG8_LAS unsigned char* lds, const Gemm g, const Sched& S, const Epi& E) {
;     ...
;             PG8_LDA(At, 0, 1); PG8_STAGE(PG8_SB(0, 0), b2, voffB); PG8_STAGE(PG8_SB(0, 1), b2 + hstep, voffB); PG8_STAGE(PG8_SA(0, 0), a2, voffA);
;             PG8_WAIT_V(8); PG8_WAIT_L(0); PG8_BAR; PG8_MMA(1, 0, At, B0); PG8_MMA(1, 1, At, B1); PG8_BAR; PG8_SCHED;
;             PG8_LDB(B0, 1, 0); PG8_LDB(B1, 1, 1); PG8_SCHED; PG8_LDA(At, 1, 0); PG8_STAGE(PG8_SA(0, 1), a2 + hstep, voffA);
;             PG8_WAIT_V(8); PG8_WAIT_L(0); PG8_BAR; PG8_MMA(0, 0, At, B0); PG8_MMA(0, 1, At, B1); PG8_BAR; PG8_SCHED;
	s_setprio 0
	s_add_i32 s81, s61, s25
	v_lshl_add_u64 v[170:171], s[38:39], 0, v[178:179]
	s_mov_b32 m0, s81
	ds_read_b128 v[162:165], v199 offset:16384
	ds_read_b128 v[166:169], v199 offset:17408
	ds_read_b128 v[210:213], v199 offset:18432
	ds_read_b128 v[214:217], v199 offset:19456
	ds_read_b128 v[218:221], v199 offset:20480
	ds_read_b128 v[222:225], v199 offset:21504
	ds_read_b128 v[226:229], v199 offset:22528
	ds_read_b128 v[230:233], v199 offset:23552
	global_load_lds_dwordx4 v[170:171], off
	s_add_i32 m0, s81, 0x2000
	s_add_u32 s82, s38, 0x40000
	v_lshl_add_u64 v[194:195], s[38:39], 0, v[174:175]
	s_addc_u32 s83, s39, 0
	s_add_i32 s81, s74, s25
	global_load_lds_dwordx4 v[194:195], off
	v_lshl_add_u64 v[234:235], s[82:83], 0, v[178:179]
	s_mov_b32 m0, s81
	v_lshl_add_u64 v[236:237], s[72:73], 0, v[176:177]
	global_load_lds_dwordx4 v[234:235], off
	v_lshl_add_u64 v[234:235], s[82:83], 0, v[174:175]
	s_add_i32 m0, s81, 0x2000
	s_nop 0
	global_load_lds_dwordx4 v[234:235], off
	v_lshl_add_u64 v[234:235], s[72:73], 0, v[180:181]
	s_mov_b32 m0, s36
	s_nop 0
	global_load_lds_dwordx4 v[234:235], off
	s_mov_b32 m0, s37
	s_nop 0
	global_load_lds_dwordx4 v[236:237], off
	s_waitcnt vmcnt(8)
	s_waitcnt lgkmcnt(0)
	s_setprio 3
	s_barrier
	v_mfma_f32_16x16x32_bf16 v[54:57], v[74:77], v[162:165], v[54:57]
	v_mfma_f32_16x16x32_bf16 v[50:53], v[82:85], v[162:165], v[50:53]
	v_mfma_f32_16x16x32_bf16 v[38:41], v[74:77], v[210:213], v[38:41]
	v_mfma_f32_16x16x32_bf16 v[34:37], v[82:85], v[210:213], v[34:37]
	v_mfma_f32_16x16x32_bf16 v[22:25], v[74:77], v[218:221], v[22:25]
	v_mfma_f32_16x16x32_bf16 v[14:17], v[82:85], v[218:221], v[14:17]
	v_mfma_f32_16x16x32_bf16 v[18:21], v[74:77], v[226:229], v[18:21]
	v_mfma_f32_16x16x32_bf16 v[10:13], v[82:85], v[226:229], v[10:13]
	v_mfma_f32_16x16x32_bf16 v[54:57], v[78:81], v[166:169], v[54:57]
	v_mfma_f32_16x16x32_bf16 v[50:53], v[86:89], v[166:169], v[50:53]
	v_mfma_f32_16x16x32_bf16 v[38:41], v[78:81], v[214:217], v[38:41]
	v_mfma_f32_16x16x32_bf16 v[34:37], v[86:89], v[214:217], v[34:37]
	v_mfma_f32_16x16x32_bf16 v[22:25], v[78:81], v[222:225], v[22:25]
	v_mfma_f32_16x16x32_bf16 v[14:17], v[86:89], v[222:225], v[14:17]
	v_mfma_f32_16x16x32_bf16 v[18:21], v[78:81], v[230:233], v[18:21]
	v_mfma_f32_16x16x32_bf16 v[10:13], v[86:89], v[230:233], v[10:13]
	v_mfma_f32_16x16x32_bf16 v[62:65], v[90:93], v[162:165], v[62:65]
	v_mfma_f32_16x16x32_bf16 v[58:61], v[98:101], v[162:165], v[58:61]
	v_mfma_f32_16x16x32_bf16 v[46:49], v[90:93], v[210:213], v[46:49]
	v_mfma_f32_16x16x32_bf16 v[42:45], v[98:101], v[210:213], v[42:45]
	v_mfma_f32_16x16x32_bf16 v[30:33], v[90:93], v[218:221], v[30:33]
	v_mfma_f32_16x16x32_bf16 v[26:29], v[98:101], v[218:221], v[26:29]
	v_mfma_f32_16x16x32_bf16 v[6:9], v[90:93], v[226:229], v[6:9]
	v_mfma_f32_16x16x32_bf16 v[2:5], v[98:101], v[226:229], v[2:5]
	v_mfma_f32_16x16x32_bf16 v[62:65], v[94:97], v[166:169], v[62:65]
	v_mfma_f32_16x16x32_bf16 v[58:61], v[106:109], v[166:169], v[58:61]
	v_mfma_f32_16x16x32_bf16 v[46:49], v[94:97], v[214:217], v[46:49]
	v_mfma_f32_16x16x32_bf16 v[42:45], v[106:109], v[214:217], v[42:45]
	v_mfma_f32_16x16x32_bf16 v[30:33], v[94:97], v[222:225], v[30:33]
	v_mfma_f32_16x16x32_bf16 v[26:29], v[106:109], v[222:225], v[26:29]
	v_mfma_f32_16x16x32_bf16 v[6:9], v[94:97], v[230:233], v[6:9]
	v_mfma_f32_16x16x32_bf16 v[2:5], v[106:109], v[230:233], v[2:5]
	s_barrier
	s_setprio 0
.Lpeel_mid_834:
	s_add_i32 s81, 0, 0x18000
	s_add_i32 s82, 0, 0x1c000
	v_add_u32_e32 v86, s81, v183
	v_add_u32_e32 v106, s82, v183
	ds_read_b128 v[74:77], v86
	ds_read_b128 v[78:81], v86 offset:1024
	ds_read_b128 v[82:85], v86 offset:2048
	ds_read_b128 v[86:89], v86 offset:3072
	ds_read_b128 v[90:93], v106
	ds_read_b128 v[94:97], v106 offset:1024
	ds_read_b128 v[98:101], v106 offset:2048
	ds_read_b128 v[106:109], v106 offset:3072
	s_add_u32 s72, s72, 0x40000
	s_addc_u32 s73, s73, 0
	s_mov_b32 m0, s42
	v_lshl_add_u64 v[238:239], s[72:73], 0, v[180:181]
	ds_read_b128 v[162:165], v199 offset:32768
	ds_read_b128 v[166:169], v199 offset:33792
	ds_read_b128 v[210:213], v199 offset:34816
	ds_read_b128 v[214:217], v199 offset:35840
	ds_read_b128 v[218:221], v199 offset:36864
	ds_read_b128 v[222:225], v199 offset:37888
	ds_read_b128 v[226:229], v199 offset:38912
	ds_read_b128 v[230:233], v199 offset:39936
	global_load_lds_dwordx4 v[238:239], off
	v_lshl_add_u64 v[238:239], s[72:73], 0, v[176:177]
	s_mov_b32 m0, s43
	s_nop 0
	global_load_lds_dwordx4 v[238:239], off
	s_waitcnt vmcnt(8)
	s_waitcnt lgkmcnt(0)
	s_setprio 3
	s_barrier
; #define PG8_STAGE(bufoff, gbase, voff) do { _Pragma("unroll") for (int _i = 0; _i < 2; ++_i) \
;         __builtin_amdgcn_global_load_lds((const unsigned*)((const char*)(gbase) + (voff)[_i]), (PG8_LAS unsigned*)(lds + (bufoff) + ldsw + _i * 8192), 16, 0, 0); } while (0)
; #define PG8_LDA(dst, b, h) do { _Pragma("unroll") for (int m = 0; m < 4; ++m) _Pragma("unroll") for (int k = 0; k < 2; ++k) dst[m][k] = *(const PG8_LAS bf16x8*)(lds + PG8_SA(b, h) + aoff + m * 2048 + k * 1024); } while (0)
; #define PG8_MMA(ai, bj, At, Bt) do { __builtin_amdgcn_s_setprio(1); _Pragma("unroll") for (int m = 0; m < 4; ++m) _Pragma("unroll") for (int n = 0; n < 2; ++n) _Pragma("unroll") for (int k = 0; k < 2; ++k) \
;         acc[ai][bj][m][n] = __builtin_amdgcn_mfma_f32_16x16x32_bf16(Bt[n][k], At[m][k], acc[ai][bj][m][n], 0, 0, 0); __builtin_amdgcn_s_setprio(0); } while (0)
; #define PG8_WAIT_V(n) asm volatile("s_waitcnt vmcnt(" #n ")" ::: "memory")
; #define PG8_WAIT_L(n) asm volatile("s_waitcnt lgkmcnt(" #n ")" ::: "memory")
; #define PG8_BAR __builtin_amdgcn_s_barrier()
; #define PG8_SCHED __builtin_amdgcn_sched_barrier(0)
; template <class Epi, class Sched, bool ALIGN_EPI = false, bool SP2 = false, bool PAIR_ACC = false>
; __device__ __forceinline__ void gemm_phase(PG8_LAS unsigned char* lds, const Gemm g, const Sched& S, const Epi& E) {
;     ...
;             PG8_WAIT_V(8); PG8_WAIT_L(0); PG8_BAR; PG8_MMA(0, 0, At, B0); PG8_MMA(0, 1, At, B1); PG8_BAR; PG8_SCHED;
;             PG8_LDA(At, 1, 1); PG8_STAGE(PG8_SB(1, 0), b3, voffB); PG8_STAGE(PG8_SB(1, 1), b3 + hstep, voffB); PG8_STAGE(PG8_SA(1, 0), a3, voffA);
;             PG8_WAIT_V(8); PG8_WAIT_L(0); PG8_BAR; PG8_MMA(1, 0, At, B0); PG8_MMA(1, 1, At, B1); PG8_BAR; PG8_SCHED;
	v_mfma_f32_16x16x32_bf16 v[150:153], v[74:77], v[162:165], v[150:153]
	v_mfma_f32_16x16x32_bf16 v[146:149], v[82:85], v[162:165], v[146:149]
	v_mfma_f32_16x16x32_bf16 v[134:137], v[74:77], v[210:213], v[134:137]
	v_mfma_f32_16x16x32_bf16 v[130:133], v[82:85], v[210:213], v[130:133]
	v_mfma_f32_16x16x32_bf16 v[118:121], v[74:77], v[218:221], v[118:121]
	v_mfma_f32_16x16x32_bf16 v[110:113], v[82:85], v[218:221], v[110:113]
	v_mfma_f32_16x16x32_bf16 v[114:117], v[74:77], v[226:229], v[114:117]
	v_mfma_f32_16x16x32_bf16 v[102:105], v[82:85], v[226:229], v[102:105]
	v_mfma_f32_16x16x32_bf16 v[150:153], v[78:81], v[166:169], v[150:153]
	v_mfma_f32_16x16x32_bf16 v[146:149], v[86:89], v[166:169], v[146:149]
	v_mfma_f32_16x16x32_bf16 v[134:137], v[78:81], v[214:217], v[134:137]
	v_mfma_f32_16x16x32_bf16 v[130:133], v[86:89], v[214:217], v[130:133]
	v_mfma_f32_16x16x32_bf16 v[118:121], v[78:81], v[222:225], v[118:121]
	v_mfma_f32_16x16x32_bf16 v[110:113], v[86:89], v[222:225], v[110:113]
	v_mfma_f32_16x16x32_bf16 v[114:117], v[78:81], v[230:233], v[114:117]
	v_mfma_f32_16x16x32_bf16 v[102:105], v[86:89], v[230:233], v[102:105]
	v_mfma_f32_16x16x32_bf16 v[158:161], v[90:93], v[162:165], v[158:161]
	v_mfma_f32_16x16x32_bf16 v[154:157], v[98:101], v[162:165], v[154:157]
	v_mfma_f32_16x16x32_bf16 v[142:145], v[90:93], v[210:213], v[142:145]
	v_mfma_f32_16x16x32_bf16 v[138:141], v[98:101], v[210:213], v[138:141]
	v_mfma_f32_16x16x32_bf16 v[126:129], v[90:93], v[218:221], v[126:129]
	v_mfma_f32_16x16x32_bf16 v[122:125], v[98:101], v[218:221], v[122:125]
	v_mfma_f32_16x16x32_bf16 v[70:73], v[90:93], v[226:229], v[70:73]
	v_mfma_f32_16x16x32_bf16 v[66:69], v[98:101], v[226:229], v[66:69]
	v_mfma_f32_16x16x32_bf16 v[158:161], v[94:97], v[166:169], v[158:161]
	v_mfma_f32_16x16x32_bf16 v[154:157], v[106:109], v[166:169], v[154:157]
	v_mfma_f32_16x16x32_bf16 v[142:145], v[94:97], v[214:217], v[142:145]
	v_mfma_f32_16x16x32_bf16 v[138:141], v[106:109], v[214:217], v[138:141]
	v_mfma_f32_16x16x32_bf16 v[126:129], v[94:97], v[222:225], v[126:129]
	v_mfma_f32_16x16x32_bf16 v[122:125], v[106:109], v[222:225], v[122:125]
	v_mfma_f32_16x16x32_bf16 v[70:73], v[94:97], v[230:233], v[70:73]
	v_mfma_f32_16x16x32_bf16 v[66:69], v[106:109], v[230:233], v[66:69]
	s_barrier
	s_setprio 0
	s_add_i32 s72, s81, s25
	v_lshl_add_u64 v[170:171], v[170:171], 0, s[48:49]
	s_mov_b32 m0, s72
	ds_read_b128 v[162:165], v199 offset:49152
	ds_read_b128 v[166:169], v199 offset:50176
	ds_read_b128 v[210:213], v199 offset:51200
	ds_read_b128 v[214:217], v199 offset:52224
	ds_read_b128 v[218:221], v199 offset:53248
	ds_read_b128 v[222:225], v199 offset:54272
	ds_read_b128 v[226:229], v199 offset:55296
	ds_read_b128 v[230:233], v199 offset:56320
	global_load_lds_dwordx4 v[170:171], off
	s_add_i32 m0, s72, 0x2000
	s_add_u32 s38, s38, 0x40080
	v_lshl_add_u64 v[170:171], v[194:195], 0, s[48:49]
	s_addc_u32 s39, s39, 0
	s_add_i32 s72, s82, s25
	global_load_lds_dwordx4 v[170:171], off
	v_lshl_add_u64 v[170:171], s[38:39], 0, v[178:179]
	s_mov_b32 m0, s72
	s_nop 0
	global_load_lds_dwordx4 v[170:171], off
	v_lshl_add_u64 v[170:171], s[38:39], 0, v[174:175]
	s_add_i32 m0, s72, 0x2000
	s_nop 0
	global_load_lds_dwordx4 v[170:171], off
	v_lshl_add_u64 v[170:171], v[234:235], 0, s[48:49]
	s_mov_b32 m0, s45
	s_nop 0
	global_load_lds_dwordx4 v[170:171], off
	v_lshl_add_u64 v[170:171], v[236:237], 0, s[48:49]
	s_mov_b32 m0, s46
	s_nop 0
	global_load_lds_dwordx4 v[170:171], off
	s_waitcnt vmcnt(8)
	s_waitcnt lgkmcnt(0)
	s_setprio 3
	s_barrier
	v_mfma_f32_16x16x32_bf16 v[54:57], v[74:77], v[162:165], v[54:57]
	v_mfma_f32_16x16x32_bf16 v[50:53], v[82:85], v[162:165], v[50:53]
	v_mfma_f32_16x16x32_bf16 v[38:41], v[74:77], v[210:213], v[38:41]
	v_mfma_f32_16x16x32_bf16 v[34:37], v[82:85], v[210:213], v[34:37]
	v_mfma_f32_16x16x32_bf16 v[22:25], v[74:77], v[218:221], v[22:25]
	v_mfma_f32_16x16x32_bf16 v[14:17], v[82:85], v[218:221], v[14:17]
	v_mfma_f32_16x16x32_bf16 v[18:21], v[74:77], v[226:229], v[18:21]
	v_mfma_f32_16x16x32_bf16 v[10:13], v[82:85], v[226:229], v[10:13]
	v_mfma_f32_16x16x32_bf16 v[54:57], v[78:81], v[166:169], v[54:57]
	v_mfma_f32_16x16x32_bf16 v[50:53], v[86:89], v[166:169], v[50:53]
	v_mfma_f32_16x16x32_bf16 v[38:41], v[78:81], v[214:217], v[38:41]
	v_mfma_f32_16x16x32_bf16 v[34:37], v[86:89], v[214:217], v[34:37]
	v_mfma_f32_16x16x32_bf16 v[22:25], v[78:81], v[222:225], v[22:25]
	v_mfma_f32_16x16x32_bf16 v[14:17], v[86:89], v[222:225], v[14:17]
	v_mfma_f32_16x16x32_bf16 v[18:21], v[78:81], v[230:233], v[18:21]
	v_mfma_f32_16x16x32_bf16 v[10:13], v[86:89], v[230:233], v[10:13]
	v_mfma_f32_16x16x32_bf16 v[62:65], v[90:93], v[162:165], v[62:65]
	v_mfma_f32_16x16x32_bf16 v[58:61], v[98:101], v[162:165], v[58:61]
	v_mfma_f32_16x16x32_bf16 v[46:49], v[90:93], v[210:213], v[46:49]
	v_mfma_f32_16x16x32_bf16 v[42:45], v[98:101], v[210:213], v[42:45]
	v_mfma_f32_16x16x32_bf16 v[30:33], v[90:93], v[218:221], v[30:33]
	v_mfma_f32_16x16x32_bf16 v[26:29], v[98:101], v[218:221], v[26:29]
	v_mfma_f32_16x16x32_bf16 v[6:9], v[90:93], v[226:229], v[6:9]
	v_mfma_f32_16x16x32_bf16 v[2:5], v[98:101], v[226:229], v[2:5]
	v_mfma_f32_16x16x32_bf16 v[62:65], v[94:97], v[166:169], v[62:65]
	v_mfma_f32_16x16x32_bf16 v[58:61], v[106:109], v[166:169], v[58:61]
	v_mfma_f32_16x16x32_bf16 v[46:49], v[94:97], v[214:217], v[46:49]
	v_mfma_f32_16x16x32_bf16 v[42:45], v[106:109], v[214:217], v[42:45]
	v_mfma_f32_16x16x32_bf16 v[30:33], v[94:97], v[222:225], v[30:33]
	v_mfma_f32_16x16x32_bf16 v[26:29], v[106:109], v[222:225], v[26:29]
	v_mfma_f32_16x16x32_bf16 v[6:9], v[94:97], v[230:233], v[6:9]
	v_mfma_f32_16x16x32_bf16 v[2:5], v[106:109], v[230:233], v[2:5]
	s_barrier
	s_setprio 0
	s_add_i32 s80, s80, 2
	s_add_u32 s10, s10, 0x100
	s_addc_u32 s11, s11, 0
	s_add_u32 s78, s78, 0x100
	s_addc_u32 s79, s79, 0
	s_cmp_gt_u32 s80, 13
	s_cbranch_scc0 .LBB0_834
	s_and_b64 vcc, exec, s[50:51]
	s_cbranch_vccz .LBB0_837
	s_barrier

; #define PG8_STAGE(bufoff, gbase, voff) do { _Pragma("unroll") for (int _i = 0; _i < 2; ++_i) \
;         __builtin_amdgcn_global_load_lds((const unsigned*)((const char*)(gbase) + (voff)[_i]), (PG8_LAS unsigned*)(lds + (bufoff) + ldsw + _i * 8192), 16, 0, 0); } while (0)
; #define PG8_LDA(dst, b, h) do { _Pragma("unroll") for (int m = 0; m < 4; ++m) _Pragma("unroll") for (int k = 0; k < 2; ++k) dst[m][k] = *(const PG8_LAS bf16x8*)(lds + PG8_SA(b, h) + aoff + m * 2048 + k * 1024); } while (0)
; #define PG8_LDB(dst, b, h) do { _Pragma("unroll") for (int n = 0; n < 2; ++n) _Pragma("unroll") for (int k = 0; k < 2; ++k) dst[n][k] = *(const PG8_LAS bf16x8*)(lds + PG8_SB(b, h) + boff + n * 2048 + k * 1024); } while (0)
; #define PG8_MMA(ai, bj, At, Bt) do { __builtin_amdgcn_s_setprio(1); _Pragma("unroll") for (int m = 0; m < 4; ++m) _Pragma("unroll") for (int n = 0; n < 2; ++n) _Pragma("unroll") for (int k = 0; k < 2; ++k) \
;         acc[ai][bj][m][n] = __builtin_amdgcn_mfma_f32_16x16x32_bf16(Bt[n][k], At[m][k], acc[ai][bj][m][n], 0, 0, 0); __builtin_amdgcn_s_setprio(0); } while (0)
; #define PG8_WAIT_V(n) asm volatile("s_waitcnt vmcnt(" #n ")" ::: "memory")
; #define PG8_WAIT_L(n) asm volatile("s_waitcnt lgkmcnt(" #n ")" ::: "memory")
; #define PG8_BAR __builtin_amdgcn_s_barrier()
; #define PG8_SCHED __builtin_amdgcn_sched_barrier(0)
; template <class Epi, class Sched, bool ALIGN_EPI = false, bool SP2 = false, bool PAIR_ACC = false>
; __device__ __forceinline__ void gemm_phase(PG8_LAS unsigned char* lds, const Gemm g, const Sched& S, const Epi& E) {
;     ...
;             PG8_LDB(B0, 0, 0); PG8_LDB(B1, 0, 1); PG8_SCHED; PG8_LDA(At, 0, 0); PG8_STAGE(PG8_SA(1, 1), a1 + hstep, voffA);
;             PG8_WAIT_V(8); PG8_WAIT_L(0); PG8_BAR; PG8_MMA(0, 0, At, B0); PG8_MMA(0, 1, At, B1); PG8_BAR; PG8_SCHED;
;             PG8_LDA(At, 0, 1); PG8_STAGE(PG8_SB(0, 0), b2, voffB); PG8_STAGE(PG8_SB(0, 1), b2 + hstep, voffB); PG8_STAGE(PG8_SA(0, 0), a2, voffA);
;             PG8_WAIT_V(8); PG8_WAIT_L(0); PG8_BAR; PG8_MMA(1, 0, At, B0); PG8_MMA(1, 1, At, B1); PG8_BAR; PG8_SCHED;
.LBB0_937:
	v_add_u32_e32 v164, s46, v150
	ds_read_b128 v[152:155], v164
	ds_read_b128 v[156:159], v164 offset:1024
	ds_read_b128 v[160:163], v164 offset:2048
	ds_read_b128 v[174:177], v164 offset:3072
	v_add_u32_e32 v164, s47, v150
	s_add_u32 s38, s28, s50
	ds_read_b128 v[178:181], v164
	ds_read_b128 v[182:185], v164 offset:1024
	ds_read_b128 v[186:189], v164 offset:2048
	ds_read_b128 v[190:193], v164 offset:3072
	s_addc_u32 s39, s29, s51
	s_add_u32 s38, s38, 0x100
	s_addc_u32 s39, s39, 0
	s_add_u32 s60, s57, s50
	s_addc_u32 s61, s58, s51
	s_cmpk_eq_i32 s50, 0x1500
	s_cselect_b32 s53, s49, s39
	s_cselect_b32 s52, s48, s38
	s_cselect_b32 s39, s11, s61
	s_cselect_b32 s38, s10, s60
	v_lshl_add_u64 v[164:165], v[146:147], 0, s[50:51]
	s_add_i32 m0, s37, 0xc000
	ds_read_b128 v[194:197], v151
	ds_read_b128 v[206:209], v151 offset:1024
	ds_read_b128 v[210:213], v151 offset:2048
	ds_read_b128 v[214:217], v151 offset:3072
	ds_read_b128 v[218:221], v151 offset:4096
	ds_read_b128 v[222:225], v151 offset:5120
	ds_read_b128 v[226:229], v151 offset:6144
	ds_read_b128 v[230:233], v151 offset:7168
	global_load_lds_dwordx4 v[164:165], off
	v_lshl_add_u64 v[164:165], v[148:149], 0, s[50:51]
	s_add_i32 m0, s37, 0xe000
	s_nop 0
	global_load_lds_dwordx4 v[164:165], off
	s_waitcnt vmcnt(8)
	s_waitcnt lgkmcnt(0)
	s_setprio 3
	s_barrier
	v_mfma_f32_16x16x32_bf16 v[58:61], v[152:155], v[194:197], v[58:61]
	v_mfma_f32_16x16x32_bf16 v[62:65], v[160:163], v[194:197], v[62:65]
	v_mfma_f32_16x16x32_bf16 v[82:85], v[152:155], v[210:213], v[82:85]
	v_mfma_f32_16x16x32_bf16 v[74:77], v[160:163], v[210:213], v[74:77]
	v_mfma_f32_16x16x32_bf16 v[98:101], v[152:155], v[218:221], v[98:101]
	v_mfma_f32_16x16x32_bf16 v[90:93], v[160:163], v[218:221], v[90:93]
	v_mfma_f32_16x16x32_bf16 v[114:117], v[152:155], v[226:229], v[114:117]
	v_mfma_f32_16x16x32_bf16 v[110:113], v[160:163], v[226:229], v[110:113]
	v_mfma_f32_16x16x32_bf16 v[58:61], v[156:159], v[206:209], v[58:61]
	v_mfma_f32_16x16x32_bf16 v[62:65], v[174:177], v[206:209], v[62:65]
	v_mfma_f32_16x16x32_bf16 v[82:85], v[156:159], v[214:217], v[82:85]
	v_mfma_f32_16x16x32_bf16 v[74:77], v[174:177], v[214:217], v[74:77]
	v_mfma_f32_16x16x32_bf16 v[98:101], v[156:159], v[222:225], v[98:101]
	v_mfma_f32_16x16x32_bf16 v[90:93], v[174:177], v[222:225], v[90:93]
	v_mfma_f32_16x16x32_bf16 v[114:117], v[156:159], v[230:233], v[114:117]
	v_mfma_f32_16x16x32_bf16 v[110:113], v[174:177], v[230:233], v[110:113]
	v_mfma_f32_16x16x32_bf16 v[54:57], v[178:181], v[194:197], v[54:57]
	v_mfma_f32_16x16x32_bf16 v[46:49], v[186:189], v[194:197], v[46:49]
	v_mfma_f32_16x16x32_bf16 v[50:53], v[178:181], v[210:213], v[50:53]
	v_mfma_f32_16x16x32_bf16 v[42:45], v[186:189], v[210:213], v[42:45]
	v_mfma_f32_16x16x32_bf16 v[78:81], v[178:181], v[218:221], v[78:81]
	v_mfma_f32_16x16x32_bf16 v[70:73], v[186:189], v[218:221], v[70:73]
	v_mfma_f32_16x16x32_bf16 v[102:105], v[178:181], v[226:229], v[102:105]
	v_mfma_f32_16x16x32_bf16 v[94:97], v[186:189], v[226:229], v[94:97]
	v_mfma_f32_16x16x32_bf16 v[54:57], v[182:185], v[206:209], v[54:57]
	v_mfma_f32_16x16x32_bf16 v[46:49], v[190:193], v[206:209], v[46:49]
	v_mfma_f32_16x16x32_bf16 v[50:53], v[182:185], v[214:217], v[50:53]
	v_mfma_f32_16x16x32_bf16 v[42:45], v[190:193], v[214:217], v[42:45]
	v_mfma_f32_16x16x32_bf16 v[78:81], v[182:185], v[222:225], v[78:81]
	v_mfma_f32_16x16x32_bf16 v[70:73], v[190:193], v[222:225], v[70:73]
	v_mfma_f32_16x16x32_bf16 v[102:105], v[182:185], v[230:233], v[102:105]
	v_mfma_f32_16x16x32_bf16 v[94:97], v[190:193], v[230:233], v[94:97]
	s_barrier
	s_setprio 0
	s_add_i32 s60, s46, s36
	v_lshl_add_u64 v[164:165], s[38:39], 0, v[132:133]
	s_mov_b32 m0, s60
	ds_read_b128 v[194:197], v151 offset:16384
	ds_read_b128 v[206:209], v151 offset:17408
	ds_read_b128 v[210:213], v151 offset:18432
	ds_read_b128 v[214:217], v151 offset:19456
	ds_read_b128 v[218:221], v151 offset:20480
	ds_read_b128 v[222:225], v151 offset:21504
	ds_read_b128 v[226:229], v151 offset:22528
	ds_read_b128 v[230:233], v151 offset:23552
	global_load_lds_dwordx4 v[164:165], off
	s_add_i32 m0, s60, 0x2000
	s_add_u32 s60, s38, 0xb0000
	v_lshl_add_u64 v[170:171], s[38:39], 0, v[136:137]
	s_addc_u32 s61, s39, 0
	s_add_i32 s62, s47, s36
	global_load_lds_dwordx4 v[170:171], off
	v_lshl_add_u64 v[198:199], s[60:61], 0, v[132:133]
	s_mov_b32 m0, s62
	v_lshl_add_u64 v[234:235], s[52:53], 0, v[134:135]
	global_load_lds_dwordx4 v[198:199], off
	v_lshl_add_u64 v[198:199], s[60:61], 0, v[136:137]
	s_add_i32 m0, s62, 0x2000
	s_nop 0
	global_load_lds_dwordx4 v[198:199], off
	v_lshl_add_u64 v[198:199], s[52:53], 0, v[130:131]
	s_mov_b32 m0, s37
	s_nop 0
	global_load_lds_dwordx4 v[198:199], off
	s_mov_b32 m0, s40
	s_nop 0
	global_load_lds_dwordx4 v[234:235], off
	s_waitcnt vmcnt(8)
	s_waitcnt lgkmcnt(0)
	s_setprio 3
	s_barrier
; #define PG8_STAGE(bufoff, gbase, voff) do { _Pragma("unroll") for (int _i = 0; _i < 2; ++_i) \
;         __builtin_amdgcn_global_load_lds((const unsigned*)((const char*)(gbase) + (voff)[_i]), (PG8_LAS unsigned*)(lds + (bufoff) + ldsw + _i * 8192), 16, 0, 0); } while (0)
; #define PG8_LDA(dst, b, h) do { _Pragma("unroll") for (int m = 0; m < 4; ++m) _Pragma("unroll") for (int k = 0; k < 2; ++k) dst[m][k] = *(const PG8_LAS bf16x8*)(lds + PG8_SA(b, h) + aoff + m * 2048 + k * 1024); } while (0)
; #define PG8_LDB(dst, b, h) do { _Pragma("unroll") for (int n = 0; n < 2; ++n) _Pragma("unroll") for (int k = 0; k < 2; ++k) dst[n][k] = *(const PG8_LAS bf16x8*)(lds + PG8_SB(b, h) + boff + n * 2048 + k * 1024); } while (0)
; #define PG8_MMA(ai, bj, At, Bt) do { __builtin_amdgcn_s_setprio(1); _Pragma("unroll") for (int m = 0; m < 4; ++m) _Pragma("unroll") for (int n = 0; n < 2; ++n) _Pragma("unroll") for (int k = 0; k < 2; ++k) \
;         acc[ai][bj][m][n] = __builtin_amdgcn_mfma_f32_16x16x32_bf16(Bt[n][k], At[m][k], acc[ai][bj][m][n], 0, 0, 0); __builtin_amdgcn_s_setprio(0); } while (0)
; #define PG8_WAIT_V(n) asm volatile("s_waitcnt vmcnt(" #n ")" ::: "memory")
; #define PG8_WAIT_L(n) asm volatile("s_waitcnt lgkmcnt(" #n ")" ::: "memory")
; #define PG8_BAR __builtin_amdgcn_s_barrier()
; #define PG8_SCHED __builtin_amdgcn_sched_barrier(0)
; template <class Epi, class Sched, bool ALIGN_EPI = false, bool SP2 = false, bool PAIR_ACC = false>
; __device__ __forceinline__ void gemm_phase(PG8_LAS unsigned char* lds, const Gemm g, const Sched& S, const Epi& E) {
;     ...
;             PG8_WAIT_V(8); PG8_WAIT_L(0); PG8_BAR; PG8_MMA(1, 0, At, B0); PG8_MMA(1, 1, At, B1); PG8_BAR; PG8_SCHED;
;             PG8_LDB(B0, 1, 0); PG8_LDB(B1, 1, 1); PG8_SCHED; PG8_LDA(At, 1, 0); PG8_STAGE(PG8_SA(0, 1), a2 + hstep, voffA);
;             PG8_WAIT_V(8); PG8_WAIT_L(0); PG8_BAR; PG8_MMA(0, 0, At, B0); PG8_MMA(0, 1, At, B1); PG8_BAR; PG8_SCHED;
	v_mfma_f32_16x16x32_bf16 v[126:129], v[152:155], v[194:197], v[126:129]
	v_mfma_f32_16x16x32_bf16 v[122:125], v[160:163], v[194:197], v[122:125]
	v_mfma_f32_16x16x32_bf16 v[86:89], v[152:155], v[210:213], v[86:89]
	v_mfma_f32_16x16x32_bf16 v[66:69], v[160:163], v[210:213], v[66:69]
	v_mfma_f32_16x16x32_bf16 v[30:33], v[152:155], v[218:221], v[30:33]
	v_mfma_f32_16x16x32_bf16 v[26:29], v[160:163], v[218:221], v[26:29]
	v_mfma_f32_16x16x32_bf16 v[14:17], v[152:155], v[226:229], v[14:17]
	v_mfma_f32_16x16x32_bf16 v[10:13], v[160:163], v[226:229], v[10:13]
	v_mfma_f32_16x16x32_bf16 v[126:129], v[156:159], v[206:209], v[126:129]
	v_mfma_f32_16x16x32_bf16 v[122:125], v[174:177], v[206:209], v[122:125]
	v_mfma_f32_16x16x32_bf16 v[86:89], v[156:159], v[214:217], v[86:89]
	v_mfma_f32_16x16x32_bf16 v[66:69], v[174:177], v[214:217], v[66:69]
	v_mfma_f32_16x16x32_bf16 v[30:33], v[156:159], v[222:225], v[30:33]
	v_mfma_f32_16x16x32_bf16 v[26:29], v[174:177], v[222:225], v[26:29]
	v_mfma_f32_16x16x32_bf16 v[14:17], v[156:159], v[230:233], v[14:17]
	v_mfma_f32_16x16x32_bf16 v[10:13], v[174:177], v[230:233], v[10:13]
	v_mfma_f32_16x16x32_bf16 v[118:121], v[178:181], v[194:197], v[118:121]
	v_mfma_f32_16x16x32_bf16 v[106:109], v[186:189], v[194:197], v[106:109]
	v_mfma_f32_16x16x32_bf16 v[38:41], v[178:181], v[210:213], v[38:41]
	v_mfma_f32_16x16x32_bf16 v[34:37], v[186:189], v[210:213], v[34:37]
	v_mfma_f32_16x16x32_bf16 v[22:25], v[178:181], v[218:221], v[22:25]
	v_mfma_f32_16x16x32_bf16 v[18:21], v[186:189], v[218:221], v[18:21]
	v_mfma_f32_16x16x32_bf16 v[6:9], v[178:181], v[226:229], v[6:9]
	v_mfma_f32_16x16x32_bf16 v[2:5], v[186:189], v[226:229], v[2:5]
	v_mfma_f32_16x16x32_bf16 v[118:121], v[182:185], v[206:209], v[118:121]
	v_mfma_f32_16x16x32_bf16 v[106:109], v[190:193], v[206:209], v[106:109]
	v_mfma_f32_16x16x32_bf16 v[38:41], v[182:185], v[214:217], v[38:41]
	v_mfma_f32_16x16x32_bf16 v[34:37], v[190:193], v[214:217], v[34:37]
	v_mfma_f32_16x16x32_bf16 v[22:25], v[182:185], v[222:225], v[22:25]
	v_mfma_f32_16x16x32_bf16 v[18:21], v[190:193], v[222:225], v[18:21]
	v_mfma_f32_16x16x32_bf16 v[6:9], v[182:185], v[230:233], v[6:9]
	v_mfma_f32_16x16x32_bf16 v[2:5], v[190:193], v[230:233], v[2:5]
	s_barrier
	s_setprio 0
	s_add_i32 s60, 0, 0x18000
	v_add_u32_e32 v169, s60, v150
	s_add_i32 s61, 0, 0x1c000
	ds_read_b128 v[152:155], v169
	ds_read_b128 v[156:159], v169 offset:1024
	ds_read_b128 v[160:163], v169 offset:2048
	ds_read_b128 v[174:177], v169 offset:3072
	v_add_u32_e32 v169, s61, v150
	ds_read_b128 v[178:181], v169
	ds_read_b128 v[182:185], v169 offset:1024
	ds_read_b128 v[186:189], v169 offset:2048
	ds_read_b128 v[190:193], v169 offset:3072
	s_add_u32 s52, s52, 0xb0000
	s_addc_u32 s53, s53, 0
	s_mov_b32 m0, s41
	v_lshl_add_u64 v[236:237], s[52:53], 0, v[130:131]
	ds_read_b128 v[194:197], v151 offset:32768
	ds_read_b128 v[206:209], v151 offset:33792
	ds_read_b128 v[210:213], v151 offset:34816
	ds_read_b128 v[214:217], v151 offset:35840
	ds_read_b128 v[218:221], v151 offset:36864
	ds_read_b128 v[222:225], v151 offset:37888
	ds_read_b128 v[226:229], v151 offset:38912
	ds_read_b128 v[230:233], v151 offset:39936
	global_load_lds_dwordx4 v[236:237], off
	v_lshl_add_u64 v[236:237], s[52:53], 0, v[134:135]
	s_mov_b32 m0, s42
	s_nop 0
	global_load_lds_dwordx4 v[236:237], off
	s_waitcnt vmcnt(8)
	s_waitcnt lgkmcnt(0)
	s_setprio 3
	s_barrier
	v_mfma_f32_16x16x32_bf16 v[58:61], v[152:155], v[194:197], v[58:61]
	v_mfma_f32_16x16x32_bf16 v[62:65], v[160:163], v[194:197], v[62:65]
	v_mfma_f32_16x16x32_bf16 v[82:85], v[152:155], v[210:213], v[82:85]
	v_mfma_f32_16x16x32_bf16 v[74:77], v[160:163], v[210:213], v[74:77]
	v_mfma_f32_16x16x32_bf16 v[98:101], v[152:155], v[218:221], v[98:101]
	v_mfma_f32_16x16x32_bf16 v[90:93], v[160:163], v[218:221], v[90:93]
	v_mfma_f32_16x16x32_bf16 v[114:117], v[152:155], v[226:229], v[114:117]
	v_mfma_f32_16x16x32_bf16 v[110:113], v[160:163], v[226:229], v[110:113]
	v_mfma_f32_16x16x32_bf16 v[58:61], v[156:159], v[206:209], v[58:61]
	v_mfma_f32_16x16x32_bf16 v[62:65], v[174:177], v[206:209], v[62:65]
	v_mfma_f32_16x16x32_bf16 v[82:85], v[156:159], v[214:217], v[82:85]
	v_mfma_f32_16x16x32_bf16 v[74:77], v[174:177], v[214:217], v[74:77]
	v_mfma_f32_16x16x32_bf16 v[98:101], v[156:159], v[222:225], v[98:101]
	v_mfma_f32_16x16x32_bf16 v[90:93], v[174:177], v[222:225], v[90:93]
	v_mfma_f32_16x16x32_bf16 v[114:117], v[156:159], v[230:233], v[114:117]
	v_mfma_f32_16x16x32_bf16 v[110:113], v[174:177], v[230:233], v[110:113]
	v_mfma_f32_16x16x32_bf16 v[54:57], v[178:181], v[194:197], v[54:57]
	v_mfma_f32_16x16x32_bf16 v[46:49], v[186:189], v[194:197], v[46:49]
	v_mfma_f32_16x16x32_bf16 v[50:53], v[178:181], v[210:213], v[50:53]
	v_mfma_f32_16x16x32_bf16 v[42:45], v[186:189], v[210:213], v[42:45]
	v_mfma_f32_16x16x32_bf16 v[78:81], v[178:181], v[218:221], v[78:81]
	v_mfma_f32_16x16x32_bf16 v[70:73], v[186:189], v[218:221], v[70:73]
	v_mfma_f32_16x16x32_bf16 v[102:105], v[178:181], v[226:229], v[102:105]
	v_mfma_f32_16x16x32_bf16 v[94:97], v[186:189], v[226:229], v[94:97]
	v_mfma_f32_16x16x32_bf16 v[54:57], v[182:185], v[206:209], v[54:57]
	v_mfma_f32_16x16x32_bf16 v[46:49], v[190:193], v[206:209], v[46:49]
	v_mfma_f32_16x16x32_bf16 v[50:53], v[182:185], v[214:217], v[50:53]
	v_mfma_f32_16x16x32_bf16 v[42:45], v[190:193], v[214:217], v[42:45]
	v_mfma_f32_16x16x32_bf16 v[78:81], v[182:185], v[222:225], v[78:81]
	v_mfma_f32_16x16x32_bf16 v[70:73], v[190:193], v[222:225], v[70:73]
	v_mfma_f32_16x16x32_bf16 v[102:105], v[182:185], v[230:233], v[102:105]
	v_mfma_f32_16x16x32_bf16 v[94:97], v[190:193], v[230:233], v[94:97]
	s_barrier
; #define PG8_STAGE(bufoff, gbase, voff) do { _Pragma("unroll") for (int _i = 0; _i < 2; ++_i) \
;         __builtin_amdgcn_global_load_lds((const unsigned*)((const char*)(gbase) + (voff)[_i]), (PG8_LAS unsigned*)(lds + (bufoff) + ldsw + _i * 8192), 16, 0, 0); } while (0)
; #define PG8_LDA(dst, b, h) do { _Pragma("unroll") for (int m = 0; m < 4; ++m) _Pragma("unroll") for (int k = 0; k < 2; ++k) dst[m][k] = *(const PG8_LAS bf16x8*)(lds + PG8_SA(b, h) + aoff + m * 2048 + k * 1024); } while (0)
; #define PG8_MMA(ai, bj, At, Bt) do { __builtin_amdgcn_s_setprio(1); _Pragma("unroll") for (int m = 0; m < 4; ++m) _Pragma("unroll") for (int n = 0; n < 2; ++n) _Pragma("unroll") for (int k = 0; k < 2; ++k) \
;         acc[ai][bj][m][n] = __builtin_amdgcn_mfma_f32_16x16x32_bf16(Bt[n][k], At[m][k], acc[ai][bj][m][n], 0, 0, 0); __builtin_amdgcn_s_setprio(0); } while (0)
; #define PG8_WAIT_V(n) asm volatile("s_waitcnt vmcnt(" #n ")" ::: "memory")
; #define PG8_WAIT_L(n) asm volatile("s_waitcnt lgkmcnt(" #n ")" ::: "memory")
; #define PG8_BAR __builtin_amdgcn_s_barrier()
; #define PG8_SCHED __builtin_amdgcn_sched_barrier(0)
; template <class Epi, class Sched, bool ALIGN_EPI = false, bool SP2 = false, bool PAIR_ACC = false>
; __device__ __forceinline__ void gemm_phase(PG8_LAS unsigned char* lds, const Gemm g, const Sched& S, const Epi& E) {
;     ...
;             PG8_LDA(At, 1, 1); PG8_STAGE(PG8_SB(1, 0), b3, voffB); PG8_STAGE(PG8_SB(1, 1), b3 + hstep, voffB); PG8_STAGE(PG8_SA(1, 0), a3, voffA);
;             PG8_WAIT_V(8); PG8_WAIT_L(0); PG8_BAR; PG8_MMA(1, 0, At, B0); PG8_MMA(1, 1, At, B1); PG8_BAR; PG8_SCHED;
;     ...
;         if (!(PAIR_ACC && cur.pn < 4)) {
; #pragma unroll
;         for (int a = 0; a < 2; ++a)
; #pragma unroll
;             for (int b = 0; b < 2; ++b)
; #pragma unroll
;                 for (int m = 0; m < 4; ++m)
; #pragma unroll
;                     for (int n = 0; n < 2; ++n) acc[a][b][m][n] = (f32x4){0.f, 0.f, 0.f, 0.f};
	s_setprio 0
	s_add_i32 s52, s60, s36
	v_lshl_add_u64 v[164:165], v[164:165], 0, s[30:31]
	s_mov_b32 m0, s52
	ds_read_b128 v[194:197], v151 offset:49152
	ds_read_b128 v[206:209], v151 offset:50176
	ds_read_b128 v[210:213], v151 offset:51200
	ds_read_b128 v[214:217], v151 offset:52224
	ds_read_b128 v[218:221], v151 offset:53248
	ds_read_b128 v[222:225], v151 offset:54272
	ds_read_b128 v[226:229], v151 offset:55296
	ds_read_b128 v[230:233], v151 offset:56320
	global_load_lds_dwordx4 v[164:165], off
	s_add_i32 m0, s52, 0x2000
	s_add_u32 s38, s38, 0xb0080
	v_lshl_add_u64 v[164:165], v[170:171], 0, s[30:31]
	s_addc_u32 s39, s39, 0
	s_add_i32 s52, s61, s36
	global_load_lds_dwordx4 v[164:165], off
	v_lshl_add_u64 v[164:165], s[38:39], 0, v[132:133]
	s_mov_b32 m0, s52
	s_nop 0
	global_load_lds_dwordx4 v[164:165], off
	v_lshl_add_u64 v[164:165], s[38:39], 0, v[136:137]
	s_add_i32 m0, s52, 0x2000
	s_nop 0
	global_load_lds_dwordx4 v[164:165], off
	v_lshl_add_u64 v[164:165], v[198:199], 0, s[30:31]
	s_mov_b32 m0, s44
	s_nop 0
	global_load_lds_dwordx4 v[164:165], off
	v_lshl_add_u64 v[164:165], v[234:235], 0, s[30:31]
	s_mov_b32 m0, s45
	s_nop 0
	global_load_lds_dwordx4 v[164:165], off
	s_waitcnt vmcnt(8)
	s_waitcnt lgkmcnt(0)
	s_setprio 3
	s_barrier
	v_mfma_f32_16x16x32_bf16 v[126:129], v[152:155], v[194:197], v[126:129]
	v_mfma_f32_16x16x32_bf16 v[122:125], v[160:163], v[194:197], v[122:125]
	v_mfma_f32_16x16x32_bf16 v[86:89], v[152:155], v[210:213], v[86:89]
	v_mfma_f32_16x16x32_bf16 v[66:69], v[160:163], v[210:213], v[66:69]
	v_mfma_f32_16x16x32_bf16 v[30:33], v[152:155], v[218:221], v[30:33]
	v_mfma_f32_16x16x32_bf16 v[26:29], v[160:163], v[218:221], v[26:29]
	v_mfma_f32_16x16x32_bf16 v[14:17], v[152:155], v[226:229], v[14:17]
	v_mfma_f32_16x16x32_bf16 v[10:13], v[160:163], v[226:229], v[10:13]
	v_mfma_f32_16x16x32_bf16 v[126:129], v[156:159], v[206:209], v[126:129]
	v_mfma_f32_16x16x32_bf16 v[122:125], v[174:177], v[206:209], v[122:125]
	v_mfma_f32_16x16x32_bf16 v[86:89], v[156:159], v[214:217], v[86:89]
	v_mfma_f32_16x16x32_bf16 v[66:69], v[174:177], v[214:217], v[66:69]
	v_mfma_f32_16x16x32_bf16 v[30:33], v[156:159], v[222:225], v[30:33]
	v_mfma_f32_16x16x32_bf16 v[26:29], v[174:177], v[222:225], v[26:29]
	v_mfma_f32_16x16x32_bf16 v[14:17], v[156:159], v[230:233], v[14:17]
	v_mfma_f32_16x16x32_bf16 v[10:13], v[174:177], v[230:233], v[10:13]
	v_mfma_f32_16x16x32_bf16 v[118:121], v[178:181], v[194:197], v[118:121]
	v_mfma_f32_16x16x32_bf16 v[106:109], v[186:189], v[194:197], v[106:109]
	v_mfma_f32_16x16x32_bf16 v[38:41], v[178:181], v[210:213], v[38:41]
	v_mfma_f32_16x16x32_bf16 v[34:37], v[186:189], v[210:213], v[34:37]
	v_mfma_f32_16x16x32_bf16 v[22:25], v[178:181], v[218:221], v[22:25]
	v_mfma_f32_16x16x32_bf16 v[18:21], v[186:189], v[218:221], v[18:21]
	v_mfma_f32_16x16x32_bf16 v[6:9], v[178:181], v[226:229], v[6:9]
	v_mfma_f32_16x16x32_bf16 v[2:5], v[186:189], v[226:229], v[2:5]
	v_mfma_f32_16x16x32_bf16 v[118:121], v[182:185], v[206:209], v[118:121]
	v_mfma_f32_16x16x32_bf16 v[106:109], v[190:193], v[206:209], v[106:109]
	v_mfma_f32_16x16x32_bf16 v[38:41], v[182:185], v[214:217], v[38:41]
	v_mfma_f32_16x16x32_bf16 v[34:37], v[190:193], v[214:217], v[34:37]
	v_mfma_f32_16x16x32_bf16 v[22:25], v[182:185], v[222:225], v[22:25]
	v_mfma_f32_16x16x32_bf16 v[18:21], v[190:193], v[222:225], v[18:21]
	v_mfma_f32_16x16x32_bf16 v[6:9], v[182:185], v[230:233], v[6:9]
	v_mfma_f32_16x16x32_bf16 v[2:5], v[190:193], v[230:233], v[2:5]
	s_barrier
	s_setprio 0
	s_add_i32 s59, s59, 2
	s_add_u32 s50, s50, 0x100
	s_addc_u32 s51, s51, 0
	s_cmp_gt_u32 s59, 41
	s_cbranch_scc0 .LBB0_937
	s_add_u32 s38, s57, 0xffffff00
	s_addc_u32 s39, s58, -1
	s_and_b64 vcc, exec, s[8:9]
	s_cbranch_vccnz .LBB0_924
	v_mov_b32_e32 v2, 0
	s_mov_b32 s18, s54
	s_mov_b32 s5, s55
	s_mov_b64 s[28:29], s[48:49]
	s_mov_b32 s43, s56
	v_mov_b32_e32 v3, v2
	v_mov_b32_e32 v4, v2
	v_mov_b32_e32 v5, v2
	v_mov_b32_e32 v6, v2
	v_mov_b32_e32 v7, v2
	v_mov_b32_e32 v8, v2
	v_mov_b32_e32 v9, v2
	v_mov_b32_e32 v18, v2
	v_mov_b32_e32 v19, v2
	v_mov_b32_e32 v20, v2
	v_mov_b32_e32 v21, v2
	v_mov_b32_e32 v22, v2
	v_mov_b32_e32 v23, v2
	v_mov_b32_e32 v24, v2
	v_mov_b32_e32 v25, v2
	v_mov_b32_e32 v34, v2
	v_mov_b32_e32 v35, v2
	v_mov_b32_e32 v36, v2
	v_mov_b32_e32 v37, v2
	v_mov_b32_e32 v38, v2
	v_mov_b32_e32 v39, v2
	v_mov_b32_e32 v40, v2
	v_mov_b32_e32 v41, v2
	v_mov_b32_e32 v106, v2
	v_mov_b32_e32 v107, v2
	v_mov_b32_e32 v108, v2
	v_mov_b32_e32 v109, v2
	v_mov_b32_e32 v118, v2
	v_mov_b32_e32 v119, v2
	v_mov_b32_e32 v120, v2
	v_mov_b32_e32 v121, v2
	v_mov_b32_e32 v10, v2
	v_mov_b32_e32 v11, v2
	v_mov_b32_e32 v12, v2
	v_mov_b32_e32 v13, v2
	v_mov_b32_e32 v14, v2
	v_mov_b32_e32 v15, v2
	v_mov_b32_e32 v16, v2
	v_mov_b32_e32 v17, v2
	v_mov_b32_e32 v26, v2
	v_mov_b32_e32 v27, v2
	v_mov_b32_e32 v28, v2
	v_mov_b32_e32 v29, v2
	v_mov_b32_e32 v30, v2
	v_mov_b32_e32 v31, v2
	v_mov_b32_e32 v32, v2
	v_mov_b32_e32 v33, v2
	v_mov_b32_e32 v66, v2
	v_mov_b32_e32 v67, v2
	v_mov_b32_e32 v68, v2
	v_mov_b32_e32 v69, v2
	v_mov_b32_e32 v86, v2
	v_mov_b32_e32 v87, v2
	v_mov_b32_e32 v88, v2
	v_mov_b32_e32 v89, v2
	v_mov_b32_e32 v122, v2
	v_mov_b32_e32 v123, v2
	v_mov_b32_e32 v124, v2
	v_mov_b32_e32 v125, v2
	v_mov_b32_e32 v126, v2
	v_mov_b32_e32 v127, v2
	v_mov_b32_e32 v128, v2
	v_mov_b32_e32 v129, v2
	v_mov_b32_e32 v94, v2
	v_mov_b32_e32 v95, v2
	v_mov_b32_e32 v96, v2
	v_mov_b32_e32 v97, v2
	v_mov_b32_e32 v102, v2
	v_mov_b32_e32 v103, v2
	v_mov_b32_e32 v104, v2
	v_mov_b32_e32 v105, v2
	v_mov_b32_e32 v70, v2
	v_mov_b32_e32 v71, v2
	v_mov_b32_e32 v72, v2
	v_mov_b32_e32 v73, v2
	v_mov_b32_e32 v78, v2
	v_mov_b32_e32 v79, v2
	v_mov_b32_e32 v80, v2
	v_mov_b32_e32 v81, v2
	v_mov_b32_e32 v42, v2
	v_mov_b32_e32 v43, v2
	v_mov_b32_e32 v44, v2
	v_mov_b32_e32 v45, v2
	v_mov_b32_e32 v50, v2
	v_mov_b32_e32 v51, v2
	v_mov_b32_e32 v52, v2
	v_mov_b32_e32 v53, v2
	v_mov_b32_e32 v46, v2
	v_mov_b32_e32 v47, v2
	v_mov_b32_e32 v48, v2
	v_mov_b32_e32 v49, v2
	v_mov_b32_e32 v54, v2
	v_mov_b32_e32 v55, v2
	v_mov_b32_e32 v56, v2
	v_mov_b32_e32 v57, v2
	v_mov_b32_e32 v110, v2
	v_mov_b32_e32 v111, v2
	v_mov_b32_e32 v112, v2
	v_mov_b32_e32 v113, v2
	v_mov_b32_e32 v114, v2
	v_mov_b32_e32 v115, v2
	v_mov_b32_e32 v116, v2
	v_mov_b32_e32 v117, v2
	v_mov_b32_e32 v90, v2
	v_mov_b32_e32 v91, v2
	v_mov_b32_e32 v92, v2
	v_mov_b32_e32 v93, v2
	v_mov_b32_e32 v98, v2
	v_mov_b32_e32 v99, v2
	v_mov_b32_e32 v100, v2
	v_mov_b32_e32 v101, v2
	v_mov_b32_e32 v74, v2
	v_mov_b32_e32 v75, v2
	v_mov_b32_e32 v76, v2
	v_mov_b32_e32 v77, v2
	v_mov_b32_e32 v82, v2
	v_mov_b32_e32 v83, v2
	v_mov_b32_e32 v84, v2
	v_mov_b32_e32 v85, v2
	v_mov_b32_e32 v62, v2
	v_mov_b32_e32 v63, v2
	v_mov_b32_e32 v64, v2
	v_mov_b32_e32 v65, v2
	v_mov_b32_e32 v58, v2
	v_mov_b32_e32 v59, v2
	v_mov_b32_e32 v60, v2
	v_mov_b32_e32 v61, v2
	s_andn2_b64 vcc, exec, s[6:7]
	s_cbranch_vccnz .LBB0_925

; #define PG8_STAGE(bufoff, gbase, voff) do { _Pragma("unroll") for (int _i = 0; _i < 2; ++_i) \
;         __builtin_amdgcn_global_load_lds((const unsigned*)((const char*)(gbase) + (voff)[_i]), (PG8_LAS unsigned*)(lds + (bufoff) + ldsw + _i * 8192), 16, 0, 0); } while (0)
; #define PG8_LDA(dst, b, h) do { _Pragma("unroll") for (int m = 0; m < 4; ++m) _Pragma("unroll") for (int k = 0; k < 2; ++k) dst[m][k] = *(const PG8_LAS bf16x8*)(lds + PG8_SA(b, h) + aoff + m * 2048 + k * 1024); } while (0)
; #define PG8_LDB(dst, b, h) do { _Pragma("unroll") for (int n = 0; n < 2; ++n) _Pragma("unroll") for (int k = 0; k < 2; ++k) dst[n][k] = *(const PG8_LAS bf16x8*)(lds + PG8_SB(b, h) + boff + n * 2048 + k * 1024); } while (0)
; #define PG8_WAIT_V(n) asm volatile("s_waitcnt vmcnt(" #n ")" ::: "memory")
; #define PG8_WAIT_L(n) asm volatile("s_waitcnt lgkmcnt(" #n ")" ::: "memory")
; #define PG8_BAR __builtin_amdgcn_s_barrier()
; template <class Epi, class Sched, bool ALIGN_EPI = false, bool SP2 = false, bool PAIR_ACC = false>
; __device__ __forceinline__ void gemm_phase(PG8_LAS unsigned char* lds, const Gemm g, const Sched& S, const Epi& E) {
;     ...
;         const bool has_next = S.next(ui + 1, nxt);
;         const char* nA = has_next ? (const char*)g.A + (size_t)nxt.pm * tstep + (size_t)(nxt.pn / g.a_div) * g.a_sel : cA; const char* nB = has_next ? (const char*)g.Bt + (size_t)nxt.pn * tstep : cB;
;         for (int t = 0; t < nt; t += 2) {
;             const bool last = (t == nt - 2);
;             const char* a1 = cA + (size_t)(t + 1) * kstep;
;             const char* a2 = last ? nA : cA + (size_t)(t + 2) * kstep; const char* b2 = last ? nB : cB + (size_t)(t + 2) * kstep;
;             const char* a3 = a2 + kstep; const char* b3 = b2 + kstep;
;             if (last && has_next) S.a_ready(nxt);
;             if constexpr (SP2) {
;             PG8_LDB(B0, 0, 0); PG8_LDB(B1, 0, 1); PG8_SCHED; PG8_LDA(At, 0, 0); PG8_STAGE(PG8_SA(1, 1), a1 + hstep, voffA);
;             PG8_WAIT_V(8); PG8_WAIT_L(0); PG8_BAR; PG8_MMA(0, 0, At, B0); PG8_MMA(0, 1, At, B1); PG8_BAR; PG8_SCHED;
;             PG8_LDA(At, 0, 1); PG8_STAGE(PG8_SB(0, 0), b2, voffB); PG8_STAGE(PG8_SB(0, 1), b2 + hstep, voffB); PG8_STAGE(PG8_SA(0, 0), a2, voffA);
;             PG8_WAIT_V(8); PG8_WAIT_L(0); PG8_BAR; PG8_MMA(1, 0, At, B0); PG8_MMA(1, 1, At, B1); PG8_BAR; PG8_SCHED;
.LBB0_1092:
	s_mov_b32 s78, s23
	s_ashr_i32 s79, s23, 31
	s_lshl_b64 s[20:21], s[78:79], 19
	s_add_u32 s82, s59, s20
	s_addc_u32 s83, s61, s21
	s_mov_b32 s76, s19
	s_and_b64 s[20:21], s[80:81], exec
	s_cselect_b32 s15, s83, s13
	s_cselect_b32 s19, s82, s12
	s_ashr_i32 s77, s76, 31
	s_lshl_b64 s[20:21], s[76:77], 19
	s_add_u32 s84, s63, s20
	s_addc_u32 s85, s69, s21
	s_and_b64 s[20:21], s[80:81], exec
	s_cselect_b32 s22, s85, s17
	s_cselect_b32 s23, s84, s16
	s_add_u32 s12, s12, 0x40080
	s_addc_u32 s13, s13, 0
	s_add_u32 s30, s16, 0x100
	s_addc_u32 s42, s17, 0
	s_mov_b32 s43, -2
	s_waitcnt lgkmcnt(0)
	ds_read_b128 v[130:133], v195
	ds_read_b128 v[134:137], v195 offset:1024
	ds_read_b128 v[138:141], v195 offset:2048
	ds_read_b128 v[142:145], v195 offset:3072
	ds_read_b128 v[176:179], v196
	ds_read_b128 v[180:183], v196 offset:1024
	ds_read_b128 v[184:187], v196 offset:2048
	ds_read_b128 v[188:191], v196 offset:3072
	s_add_u32 s16, s12, 0xfffc0080
	s_addc_u32 s17, s13, -1
	s_cmp_eq_u32 s43, 12
	s_cselect_b32 s21, s15, s17
	s_cselect_b32 s20, s19, s16
	s_cselect_b32 s17, s22, s42
	s_cselect_b32 s16, s23, s30
	v_lshl_add_u64 v[192:193], s[12:13], 0, v[170:171]
	s_add_i32 m0, s73, 0xc000
	ds_read_b128 v[200:203], v197
	ds_read_b128 v[204:207], v197 offset:1024
	ds_read_b128 v[208:211], v197 offset:2048
	ds_read_b128 v[212:215], v197 offset:3072
	ds_read_b128 v[216:219], v197 offset:4096
	ds_read_b128 v[220:223], v197 offset:5120
	ds_read_b128 v[224:227], v197 offset:6144
	ds_read_b128 v[228:231], v197 offset:7168
	global_load_lds_dwordx4 v[192:193], off
	v_lshl_add_u64 v[192:193], s[12:13], 0, v[172:173]
	s_add_i32 m0, s73, 0xe000
	s_nop 0
	global_load_lds_dwordx4 v[192:193], off
	s_waitcnt vmcnt(8)
	s_waitcnt lgkmcnt(0)
	s_setprio 3
	s_barrier
	v_mfma_f32_16x16x32_bf16 v[126:129], v[130:133], v[200:203], 0
	v_mfma_f32_16x16x32_bf16 v[122:125], v[138:141], v[200:203], 0
	v_mfma_f32_16x16x32_bf16 v[110:113], v[130:133], v[208:211], 0
	v_mfma_f32_16x16x32_bf16 v[106:109], v[138:141], v[208:211], 0
	v_mfma_f32_16x16x32_bf16 v[94:97], v[130:133], v[216:219], 0
	v_mfma_f32_16x16x32_bf16 v[90:93], v[138:141], v[216:219], 0
	v_mfma_f32_16x16x32_bf16 v[78:81], v[130:133], v[224:227], 0
	v_mfma_f32_16x16x32_bf16 v[74:77], v[138:141], v[224:227], 0
	v_mfma_f32_16x16x32_bf16 v[126:129], v[134:137], v[204:207], v[126:129]
	v_mfma_f32_16x16x32_bf16 v[122:125], v[142:145], v[204:207], v[122:125]
	v_mfma_f32_16x16x32_bf16 v[110:113], v[134:137], v[212:215], v[110:113]
	v_mfma_f32_16x16x32_bf16 v[106:109], v[142:145], v[212:215], v[106:109]
	v_mfma_f32_16x16x32_bf16 v[94:97], v[134:137], v[220:223], v[94:97]
	v_mfma_f32_16x16x32_bf16 v[90:93], v[142:145], v[220:223], v[90:93]
	v_mfma_f32_16x16x32_bf16 v[78:81], v[134:137], v[228:231], v[78:81]
	v_mfma_f32_16x16x32_bf16 v[74:77], v[142:145], v[228:231], v[74:77]
	v_mfma_f32_16x16x32_bf16 v[118:121], v[176:179], v[200:203], 0
	v_mfma_f32_16x16x32_bf16 v[114:117], v[184:187], v[200:203], 0
	v_mfma_f32_16x16x32_bf16 v[102:105], v[176:179], v[208:211], 0
	v_mfma_f32_16x16x32_bf16 v[98:101], v[184:187], v[208:211], 0
	v_mfma_f32_16x16x32_bf16 v[86:89], v[176:179], v[216:219], 0
	v_mfma_f32_16x16x32_bf16 v[82:85], v[184:187], v[216:219], 0
	v_mfma_f32_16x16x32_bf16 v[70:73], v[176:179], v[224:227], 0
	v_mfma_f32_16x16x32_bf16 v[66:69], v[184:187], v[224:227], 0
	v_mfma_f32_16x16x32_bf16 v[118:121], v[180:183], v[204:207], v[118:121]
	v_mfma_f32_16x16x32_bf16 v[114:117], v[188:191], v[204:207], v[114:117]
	v_mfma_f32_16x16x32_bf16 v[102:105], v[180:183], v[212:215], v[102:105]
	v_mfma_f32_16x16x32_bf16 v[98:101], v[188:191], v[212:215], v[98:101]
	v_mfma_f32_16x16x32_bf16 v[86:89], v[180:183], v[220:223], v[86:89]
	v_mfma_f32_16x16x32_bf16 v[82:85], v[188:191], v[220:223], v[82:85]
	v_mfma_f32_16x16x32_bf16 v[70:73], v[180:183], v[228:231], v[70:73]
	v_mfma_f32_16x16x32_bf16 v[66:69], v[188:191], v[228:231], v[66:69]
	s_barrier
	s_setprio 0
	s_add_i32 s77, s34, s71
	v_lshl_add_u64 v[192:193], s[16:17], 0, v[148:149]
	s_mov_b32 m0, s77
	ds_read_b128 v[200:203], v197 offset:16384
	ds_read_b128 v[204:207], v197 offset:17408
	ds_read_b128 v[208:211], v197 offset:18432
	ds_read_b128 v[212:215], v197 offset:19456
	ds_read_b128 v[216:219], v197 offset:20480
	ds_read_b128 v[220:223], v197 offset:21504
	ds_read_b128 v[224:227], v197 offset:22528
	ds_read_b128 v[228:231], v197 offset:23552
	global_load_lds_dwordx4 v[192:193], off
	s_add_i32 m0, s77, 0x2000
	s_add_u32 s86, s16, 0x40000
	v_lshl_add_u64 v[232:233], s[16:17], 0, v[152:153]
	s_addc_u32 s87, s17, 0
	s_add_i32 s77, s35, s71
	global_load_lds_dwordx4 v[232:233], off
	v_lshl_add_u64 v[234:235], s[86:87], 0, v[148:149]
	s_mov_b32 m0, s77
	v_lshl_add_u64 v[236:237], s[20:21], 0, v[150:151]
	global_load_lds_dwordx4 v[234:235], off
	v_lshl_add_u64 v[234:235], s[86:87], 0, v[152:153]
	s_add_i32 m0, s77, 0x2000
	s_nop 0
	global_load_lds_dwordx4 v[234:235], off
	v_lshl_add_u64 v[234:235], s[20:21], 0, v[146:147]
	s_mov_b32 m0, s73
	s_nop 0
	global_load_lds_dwordx4 v[234:235], off
	s_mov_b32 m0, s75
	s_nop 0
	global_load_lds_dwordx4 v[236:237], off
	s_waitcnt vmcnt(8)
	s_waitcnt lgkmcnt(0)
	s_setprio 3
	s_barrier
; #define PG8_STAGE(bufoff, gbase, voff) do { _Pragma("unroll") for (int _i = 0; _i < 2; ++_i) \
;         __builtin_amdgcn_global_load_lds((const unsigned*)((const char*)(gbase) + (voff)[_i]), (PG8_LAS unsigned*)(lds + (bufoff) + ldsw + _i * 8192), 16, 0, 0); } while (0)
; #define PG8_LDA(dst, b, h) do { _Pragma("unroll") for (int m = 0; m < 4; ++m) _Pragma("unroll") for (int k = 0; k < 2; ++k) dst[m][k] = *(const PG8_LAS bf16x8*)(lds + PG8_SA(b, h) + aoff + m * 2048 + k * 1024); } while (0)
; #define PG8_LDB(dst, b, h) do { _Pragma("unroll") for (int n = 0; n < 2; ++n) _Pragma("unroll") for (int k = 0; k < 2; ++k) dst[n][k] = *(const PG8_LAS bf16x8*)(lds + PG8_SB(b, h) + boff + n * 2048 + k * 1024); } while (0)
; #define PG8_MMA(ai, bj, At, Bt) do { __builtin_amdgcn_s_setprio(1); _Pragma("unroll") for (int m = 0; m < 4; ++m) _Pragma("unroll") for (int n = 0; n < 2; ++n) _Pragma("unroll") for (int k = 0; k < 2; ++k) \
;         acc[ai][bj][m][n] = __builtin_amdgcn_mfma_f32_16x16x32_bf16(Bt[n][k], At[m][k], acc[ai][bj][m][n], 0, 0, 0); __builtin_amdgcn_s_setprio(0); } while (0)
; template <class Epi, class Sched, bool ALIGN_EPI = false, bool SP2 = false, bool PAIR_ACC = false>
; __device__ __forceinline__ void gemm_phase(PG8_LAS unsigned char* lds, const Gemm g, const Sched& S, const Epi& E) {
;     ...
;             if constexpr (SP2) {
;             PG8_LDB(B0, 0, 0); PG8_LDB(B1, 0, 1); PG8_SCHED; PG8_LDA(At, 0, 0); PG8_STAGE(PG8_SA(1, 1), a1 + hstep, voffA);
;             PG8_WAIT_V(8); PG8_WAIT_L(0); PG8_BAR; PG8_MMA(0, 0, At, B0); PG8_MMA(0, 1, At, B1); PG8_BAR; PG8_SCHED;
;             PG8_LDA(At, 0, 1); PG8_STAGE(PG8_SB(0, 0), b2, voffB); PG8_STAGE(PG8_SB(0, 1), b2 + hstep, voffB); PG8_STAGE(PG8_SA(0, 0), a2, voffA);
;             PG8_WAIT_V(8); PG8_WAIT_L(0); PG8_BAR; PG8_MMA(1, 0, At, B0); PG8_MMA(1, 1, At, B1); PG8_BAR; PG8_SCHED;
;             PG8_LDB(B0, 1, 0); PG8_LDB(B1, 1, 1); PG8_SCHED; PG8_LDA(At, 1, 0); PG8_STAGE(PG8_SA(0, 1), a2 + hstep, voffA);
;             PG8_WAIT_V(8); PG8_WAIT_L(0); PG8_BAR; PG8_MMA(0, 0, At, B0); PG8_MMA(0, 1, At, B1); PG8_BAR; PG8_SCHED;
;             PG8_LDA(At, 1, 1); PG8_STAGE(PG8_SB(1, 0), b3, voffB); PG8_STAGE(PG8_SB(1, 1), b3 + hstep, voffB); PG8_STAGE(PG8_SA(1, 0), a3, voffA);
;             PG8_WAIT_V(8); PG8_WAIT_L(0); PG8_BAR; PG8_MMA(1, 0, At, B0); PG8_MMA(1, 1, At, B1); PG8_BAR; PG8_SCHED;
	v_mfma_f32_16x16x32_bf16 v[62:65], v[130:133], v[200:203], 0
	v_mfma_f32_16x16x32_bf16 v[58:61], v[138:141], v[200:203], 0
	v_mfma_f32_16x16x32_bf16 v[46:49], v[130:133], v[208:211], 0
	v_mfma_f32_16x16x32_bf16 v[42:45], v[138:141], v[208:211], 0
	v_mfma_f32_16x16x32_bf16 v[30:33], v[130:133], v[216:219], 0
	v_mfma_f32_16x16x32_bf16 v[26:29], v[138:141], v[216:219], 0
	v_mfma_f32_16x16x32_bf16 v[14:17], v[130:133], v[224:227], 0
	v_mfma_f32_16x16x32_bf16 v[10:13], v[138:141], v[224:227], 0
	v_mfma_f32_16x16x32_bf16 v[62:65], v[134:137], v[204:207], v[62:65]
	v_mfma_f32_16x16x32_bf16 v[58:61], v[142:145], v[204:207], v[58:61]
	v_mfma_f32_16x16x32_bf16 v[46:49], v[134:137], v[212:215], v[46:49]
	v_mfma_f32_16x16x32_bf16 v[42:45], v[142:145], v[212:215], v[42:45]
	v_mfma_f32_16x16x32_bf16 v[30:33], v[134:137], v[220:223], v[30:33]
	v_mfma_f32_16x16x32_bf16 v[26:29], v[142:145], v[220:223], v[26:29]
	v_mfma_f32_16x16x32_bf16 v[14:17], v[134:137], v[228:231], v[14:17]
	v_mfma_f32_16x16x32_bf16 v[10:13], v[142:145], v[228:231], v[10:13]
	v_mfma_f32_16x16x32_bf16 v[54:57], v[176:179], v[200:203], 0
	v_mfma_f32_16x16x32_bf16 v[50:53], v[184:187], v[200:203], 0
	v_mfma_f32_16x16x32_bf16 v[38:41], v[176:179], v[208:211], 0
	v_mfma_f32_16x16x32_bf16 v[34:37], v[184:187], v[208:211], 0
	v_mfma_f32_16x16x32_bf16 v[22:25], v[176:179], v[216:219], 0
	v_mfma_f32_16x16x32_bf16 v[18:21], v[184:187], v[216:219], 0
	v_mfma_f32_16x16x32_bf16 v[6:9], v[176:179], v[224:227], 0
	v_mfma_f32_16x16x32_bf16 v[2:5], v[184:187], v[224:227], 0
	v_mfma_f32_16x16x32_bf16 v[54:57], v[180:183], v[204:207], v[54:57]
	v_mfma_f32_16x16x32_bf16 v[50:53], v[188:191], v[204:207], v[50:53]
	v_mfma_f32_16x16x32_bf16 v[38:41], v[180:183], v[212:215], v[38:41]
	v_mfma_f32_16x16x32_bf16 v[34:37], v[188:191], v[212:215], v[34:37]
	v_mfma_f32_16x16x32_bf16 v[22:25], v[180:183], v[220:223], v[22:25]
	v_mfma_f32_16x16x32_bf16 v[18:21], v[188:191], v[220:223], v[18:21]
	v_mfma_f32_16x16x32_bf16 v[6:9], v[180:183], v[228:231], v[6:9]
	v_mfma_f32_16x16x32_bf16 v[2:5], v[188:191], v[228:231], v[2:5]
	s_barrier
	s_setprio 0
	s_branch .Lpeel_mid_1093
.LBB0_1093:
	ds_read_b128 v[130:133], v195
	ds_read_b128 v[134:137], v195 offset:1024
	ds_read_b128 v[138:141], v195 offset:2048
	ds_read_b128 v[142:145], v195 offset:3072
	ds_read_b128 v[176:179], v196
	ds_read_b128 v[180:183], v196 offset:1024
	ds_read_b128 v[184:187], v196 offset:2048
	ds_read_b128 v[188:191], v196 offset:3072
	s_add_u32 s16, s12, 0xfffc0080
	s_addc_u32 s17, s13, -1
	s_cmp_eq_u32 s43, 12
	s_cselect_b32 s21, s15, s17
	s_cselect_b32 s20, s19, s16
	s_cselect_b32 s17, s22, s42
	s_cselect_b32 s16, s23, s30
	v_lshl_add_u64 v[192:193], s[12:13], 0, v[170:171]
	s_add_i32 m0, s73, 0xc000
	ds_read_b128 v[200:203], v197
	ds_read_b128 v[204:207], v197 offset:1024
	ds_read_b128 v[208:211], v197 offset:2048
	ds_read_b128 v[212:215], v197 offset:3072
	ds_read_b128 v[216:219], v197 offset:4096
	ds_read_b128 v[220:223], v197 offset:5120
	ds_read_b128 v[224:227], v197 offset:6144
	ds_read_b128 v[228:231], v197 offset:7168
	global_load_lds_dwordx4 v[192:193], off
	v_lshl_add_u64 v[192:193], s[12:13], 0, v[172:173]
	s_add_i32 m0, s73, 0xe000
	s_nop 0
	global_load_lds_dwordx4 v[192:193], off
	s_waitcnt vmcnt(8)
	s_waitcnt lgkmcnt(0)
	s_setprio 3
	s_barrier
	v_mfma_f32_16x16x32_bf16 v[126:129], v[130:133], v[200:203], v[126:129]
	v_mfma_f32_16x16x32_bf16 v[122:125], v[138:141], v[200:203], v[122:125]
	v_mfma_f32_16x16x32_bf16 v[110:113], v[130:133], v[208:211], v[110:113]
	v_mfma_f32_16x16x32_bf16 v[106:109], v[138:141], v[208:211], v[106:109]
	v_mfma_f32_16x16x32_bf16 v[94:97], v[130:133], v[216:219], v[94:97]
	v_mfma_f32_16x16x32_bf16 v[90:93], v[138:141], v[216:219], v[90:93]
	v_mfma_f32_16x16x32_bf16 v[78:81], v[130:133], v[224:227], v[78:81]
	v_mfma_f32_16x16x32_bf16 v[74:77], v[138:141], v[224:227], v[74:77]
	v_mfma_f32_16x16x32_bf16 v[126:129], v[134:137], v[204:207], v[126:129]
	v_mfma_f32_16x16x32_bf16 v[122:125], v[142:145], v[204:207], v[122:125]
	v_mfma_f32_16x16x32_bf16 v[110:113], v[134:137], v[212:215], v[110:113]
	v_mfma_f32_16x16x32_bf16 v[106:109], v[142:145], v[212:215], v[106:109]
	v_mfma_f32_16x16x32_bf16 v[94:97], v[134:137], v[220:223], v[94:97]
	v_mfma_f32_16x16x32_bf16 v[90:93], v[142:145], v[220:223], v[90:93]
	v_mfma_f32_16x16x32_bf16 v[78:81], v[134:137], v[228:231], v[78:81]
	v_mfma_f32_16x16x32_bf16 v[74:77], v[142:145], v[228:231], v[74:77]
	v_mfma_f32_16x16x32_bf16 v[118:121], v[176:179], v[200:203], v[118:121]
	v_mfma_f32_16x16x32_bf16 v[114:117], v[184:187], v[200:203], v[114:117]
	v_mfma_f32_16x16x32_bf16 v[102:105], v[176:179], v[208:211], v[102:105]
	v_mfma_f32_16x16x32_bf16 v[98:101], v[184:187], v[208:211], v[98:101]
	v_mfma_f32_16x16x32_bf16 v[86:89], v[176:179], v[216:219], v[86:89]
	v_mfma_f32_16x16x32_bf16 v[82:85], v[184:187], v[216:219], v[82:85]
	v_mfma_f32_16x16x32_bf16 v[70:73], v[176:179], v[224:227], v[70:73]
	v_mfma_f32_16x16x32_bf16 v[66:69], v[184:187], v[224:227], v[66:69]
	v_mfma_f32_16x16x32_bf16 v[118:121], v[180:183], v[204:207], v[118:121]
	v_mfma_f32_16x16x32_bf16 v[114:117], v[188:191], v[204:207], v[114:117]
	v_mfma_f32_16x16x32_bf16 v[102:105], v[180:183], v[212:215], v[102:105]
	v_mfma_f32_16x16x32_bf16 v[98:101], v[188:191], v[212:215], v[98:101]
	v_mfma_f32_16x16x32_bf16 v[86:89], v[180:183], v[220:223], v[86:89]
	v_mfma_f32_16x16x32_bf16 v[82:85], v[188:191], v[220:223], v[82:85]
	v_mfma_f32_16x16x32_bf16 v[70:73], v[180:183], v[228:231], v[70:73]
	v_mfma_f32_16x16x32_bf16 v[66:69], v[188:191], v[228:231], v[66:69]
	s_barrier
; #define PG8_STAGE(bufoff, gbase, voff) do { _Pragma("unroll") for (int _i = 0; _i < 2; ++_i) \
;         __builtin_amdgcn_global_load_lds((const unsigned*)((const char*)(gbase) + (voff)[_i]), (PG8_LAS unsigned*)(lds + (bufoff) + ldsw + _i * 8192), 16, 0, 0); } while (0)
; #define PG8_LDA(dst, b, h) do { _Pragma("unroll") for (int m = 0; m < 4; ++m) _Pragma("unroll") for (int k = 0; k < 2; ++k) dst[m][k] = *(const PG8_LAS bf16x8*)(lds + PG8_SA(b, h) + aoff + m * 2048 + k * 1024); } while (0)
; #define PG8_LDB(dst, b, h) do { _Pragma("unroll") for (int n = 0; n < 2; ++n) _Pragma("unroll") for (int k = 0; k < 2; ++k) dst[n][k] = *(const PG8_LAS bf16x8*)(lds + PG8_SB(b, h) + boff + n * 2048 + k * 1024); } while (0)
; #define PG8_MMA(ai, bj, At, Bt) do { __builtin_amdgcn_s_setprio(1); _Pragma("unroll") for (int m = 0; m < 4; ++m) _Pragma("unroll") for (int n = 0; n < 2; ++n) _Pragma("unroll") for (int k = 0; k < 2; ++k) \
;         acc[ai][bj][m][n] = __builtin_amdgcn_mfma_f32_16x16x32_bf16(Bt[n][k], At[m][k], acc[ai][bj][m][n], 0, 0, 0); __builtin_amdgcn_s_setprio(0); } while (0)
; template <class Epi, class Sched, bool ALIGN_EPI = false, bool SP2 = false, bool PAIR_ACC = false>
; __device__ __forceinline__ void gemm_phase(PG8_LAS unsigned char* lds, const Gemm g, const Sched& S, const Epi& E) {
;     ...
;             if constexpr (SP2) {
;             PG8_LDB(B0, 0, 0); PG8_LDB(B1, 0, 1); PG8_SCHED; PG8_LDA(At, 0, 0); PG8_STAGE(PG8_SA(1, 1), a1 + hstep, voffA);
;             PG8_WAIT_V(8); PG8_WAIT_L(0); PG8_BAR; PG8_MMA(0, 0, At, B0); PG8_MMA(0, 1, At, B1); PG8_BAR; PG8_SCHED;
;             PG8_LDA(At, 0, 1); PG8_STAGE(PG8_SB(0, 0), b2, voffB); PG8_STAGE(PG8_SB(0, 1), b2 + hstep, voffB); PG8_STAGE(PG8_SA(0, 0), a2, voffA);
;             PG8_WAIT_V(8); PG8_WAIT_L(0); PG8_BAR; PG8_MMA(1, 0, At, B0); PG8_MMA(1, 1, At, B1); PG8_BAR; PG8_SCHED;
;             PG8_LDB(B0, 1, 0); PG8_LDB(B1, 1, 1); PG8_SCHED; PG8_LDA(At, 1, 0); PG8_STAGE(PG8_SA(0, 1), a2 + hstep, voffA);
;             PG8_WAIT_V(8); PG8_WAIT_L(0); PG8_BAR; PG8_MMA(0, 0, At, B0); PG8_MMA(0, 1, At, B1); PG8_BAR; PG8_SCHED;
;             PG8_LDA(At, 1, 1); PG8_STAGE(PG8_SB(1, 0), b3, voffB); PG8_STAGE(PG8_SB(1, 1), b3 + hstep, voffB); PG8_STAGE(PG8_SA(1, 0), a3, voffA);
;             PG8_WAIT_V(8); PG8_WAIT_L(0); PG8_BAR; PG8_MMA(1, 0, At, B0); PG8_MMA(1, 1, At, B1); PG8_BAR; PG8_SCHED;
	s_setprio 0
	s_add_i32 s77, s34, s71
	v_lshl_add_u64 v[192:193], s[16:17], 0, v[148:149]
	s_mov_b32 m0, s77
	ds_read_b128 v[200:203], v197 offset:16384
	ds_read_b128 v[204:207], v197 offset:17408
	ds_read_b128 v[208:211], v197 offset:18432
	ds_read_b128 v[212:215], v197 offset:19456
	ds_read_b128 v[216:219], v197 offset:20480
	ds_read_b128 v[220:223], v197 offset:21504
	ds_read_b128 v[224:227], v197 offset:22528
	ds_read_b128 v[228:231], v197 offset:23552
	global_load_lds_dwordx4 v[192:193], off
	s_add_i32 m0, s77, 0x2000
	s_add_u32 s86, s16, 0x40000
	v_lshl_add_u64 v[232:233], s[16:17], 0, v[152:153]
	s_addc_u32 s87, s17, 0
	s_add_i32 s77, s35, s71
	global_load_lds_dwordx4 v[232:233], off
	v_lshl_add_u64 v[234:235], s[86:87], 0, v[148:149]
	s_mov_b32 m0, s77
	v_lshl_add_u64 v[236:237], s[20:21], 0, v[150:151]
	global_load_lds_dwordx4 v[234:235], off
	v_lshl_add_u64 v[234:235], s[86:87], 0, v[152:153]
	s_add_i32 m0, s77, 0x2000
	s_nop 0
	global_load_lds_dwordx4 v[234:235], off
	v_lshl_add_u64 v[234:235], s[20:21], 0, v[146:147]
	s_mov_b32 m0, s73
	s_nop 0
	global_load_lds_dwordx4 v[234:235], off
	s_mov_b32 m0, s75
	s_nop 0
	global_load_lds_dwordx4 v[236:237], off
	s_waitcnt vmcnt(8)
	s_waitcnt lgkmcnt(0)
	s_setprio 3
	s_barrier
	v_mfma_f32_16x16x32_bf16 v[62:65], v[130:133], v[200:203], v[62:65]
	v_mfma_f32_16x16x32_bf16 v[58:61], v[138:141], v[200:203], v[58:61]
	v_mfma_f32_16x16x32_bf16 v[46:49], v[130:133], v[208:211], v[46:49]
	v_mfma_f32_16x16x32_bf16 v[42:45], v[138:141], v[208:211], v[42:45]
	v_mfma_f32_16x16x32_bf16 v[30:33], v[130:133], v[216:219], v[30:33]
	v_mfma_f32_16x16x32_bf16 v[26:29], v[138:141], v[216:219], v[26:29]
	v_mfma_f32_16x16x32_bf16 v[14:17], v[130:133], v[224:227], v[14:17]
	v_mfma_f32_16x16x32_bf16 v[10:13], v[138:141], v[224:227], v[10:13]
	v_mfma_f32_16x16x32_bf16 v[62:65], v[134:137], v[204:207], v[62:65]
	v_mfma_f32_16x16x32_bf16 v[58:61], v[142:145], v[204:207], v[58:61]
	v_mfma_f32_16x16x32_bf16 v[46:49], v[134:137], v[212:215], v[46:49]
	v_mfma_f32_16x16x32_bf16 v[42:45], v[142:145], v[212:215], v[42:45]
	v_mfma_f32_16x16x32_bf16 v[30:33], v[134:137], v[220:223], v[30:33]
	v_mfma_f32_16x16x32_bf16 v[26:29], v[142:145], v[220:223], v[26:29]
	v_mfma_f32_16x16x32_bf16 v[14:17], v[134:137], v[228:231], v[14:17]
	v_mfma_f32_16x16x32_bf16 v[10:13], v[142:145], v[228:231], v[10:13]
	v_mfma_f32_16x16x32_bf16 v[54:57], v[176:179], v[200:203], v[54:57]
	v_mfma_f32_16x16x32_bf16 v[50:53], v[184:187], v[200:203], v[50:53]
	v_mfma_f32_16x16x32_bf16 v[38:41], v[176:179], v[208:211], v[38:41]
	v_mfma_f32_16x16x32_bf16 v[34:37], v[184:187], v[208:211], v[34:37]
	v_mfma_f32_16x16x32_bf16 v[22:25], v[176:179], v[216:219], v[22:25]
	v_mfma_f32_16x16x32_bf16 v[18:21], v[184:187], v[216:219], v[18:21]
	v_mfma_f32_16x16x32_bf16 v[6:9], v[176:179], v[224:227], v[6:9]
	v_mfma_f32_16x16x32_bf16 v[2:5], v[184:187], v[224:227], v[2:5]
	v_mfma_f32_16x16x32_bf16 v[54:57], v[180:183], v[204:207], v[54:57]
	v_mfma_f32_16x16x32_bf16 v[50:53], v[188:191], v[204:207], v[50:53]
	v_mfma_f32_16x16x32_bf16 v[38:41], v[180:183], v[212:215], v[38:41]
	v_mfma_f32_16x16x32_bf16 v[34:37], v[188:191], v[212:215], v[34:37]
	v_mfma_f32_16x16x32_bf16 v[22:25], v[180:183], v[220:223], v[22:25]
	v_mfma_f32_16x16x32_bf16 v[18:21], v[188:191], v[220:223], v[18:21]
	v_mfma_f32_16x16x32_bf16 v[6:9], v[180:183], v[228:231], v[6:9]
	v_mfma_f32_16x16x32_bf16 v[2:5], v[188:191], v[228:231], v[2:5]
	s_barrier
	s_setprio 0
.Lpeel_mid_1093:
	s_add_i32 s77, 0, 0x18000
	s_add_i32 s79, 0, 0x1c000
	v_add_u32_e32 v142, s77, v194
	v_add_u32_e32 v154, s79, v194
	ds_read_b128 v[130:133], v142
	ds_read_b128 v[134:137], v142 offset:1024
	ds_read_b128 v[138:141], v142 offset:2048
	ds_read_b128 v[142:145], v142 offset:3072
	ds_read_b128 v[176:179], v154
	ds_read_b128 v[180:183], v154 offset:1024
	ds_read_b128 v[184:187], v154 offset:2048
	ds_read_b128 v[188:191], v154 offset:3072
	s_add_u32 s20, s20, 0x40000
	s_addc_u32 s21, s21, 0
	s_mov_b32 m0, s44
	v_lshl_add_u64 v[238:239], s[20:21], 0, v[146:147]
	ds_read_b128 v[200:203], v197 offset:32768
	ds_read_b128 v[204:207], v197 offset:33792
	ds_read_b128 v[208:211], v197 offset:34816
	ds_read_b128 v[212:215], v197 offset:35840
	ds_read_b128 v[216:219], v197 offset:36864
	ds_read_b128 v[220:223], v197 offset:37888
	ds_read_b128 v[224:227], v197 offset:38912
	ds_read_b128 v[228:231], v197 offset:39936
	global_load_lds_dwordx4 v[238:239], off
	v_lshl_add_u64 v[238:239], s[20:21], 0, v[150:151]
	s_mov_b32 m0, s45
	s_nop 0
	global_load_lds_dwordx4 v[238:239], off
	s_waitcnt vmcnt(8)
	s_waitcnt lgkmcnt(0)
	s_setprio 3
	s_barrier
; #define PG8_STAGE(bufoff, gbase, voff) do { _Pragma("unroll") for (int _i = 0; _i < 2; ++_i) \
;         __builtin_amdgcn_global_load_lds((const unsigned*)((const char*)(gbase) + (voff)[_i]), (PG8_LAS unsigned*)(lds + (bufoff) + ldsw + _i * 8192), 16, 0, 0); } while (0)
; #define PG8_LDA(dst, b, h) do { _Pragma("unroll") for (int m = 0; m < 4; ++m) _Pragma("unroll") for (int k = 0; k < 2; ++k) dst[m][k] = *(const PG8_LAS bf16x8*)(lds + PG8_SA(b, h) + aoff + m * 2048 + k * 1024); } while (0)
; #define PG8_LDB(dst, b, h) do { _Pragma("unroll") for (int n = 0; n < 2; ++n) _Pragma("unroll") for (int k = 0; k < 2; ++k) dst[n][k] = *(const PG8_LAS bf16x8*)(lds + PG8_SB(b, h) + boff + n * 2048 + k * 1024); } while (0)
; #define PG8_MMA(ai, bj, At, Bt) do { __builtin_amdgcn_s_setprio(1); _Pragma("unroll") for (int m = 0; m < 4; ++m) _Pragma("unroll") for (int n = 0; n < 2; ++n) _Pragma("unroll") for (int k = 0; k < 2; ++k) \
;         acc[ai][bj][m][n] = __builtin_amdgcn_mfma_f32_16x16x32_bf16(Bt[n][k], At[m][k], acc[ai][bj][m][n], 0, 0, 0); __builtin_amdgcn_s_setprio(0); } while (0)
; template <class Epi, class Sched, bool ALIGN_EPI = false, bool SP2 = false, bool PAIR_ACC = false>
; __device__ __forceinline__ void gemm_phase(PG8_LAS unsigned char* lds, const Gemm g, const Sched& S, const Epi& E) {
;     ...
;             if constexpr (SP2) {
;             PG8_LDB(B0, 0, 0); PG8_LDB(B1, 0, 1); PG8_SCHED; PG8_LDA(At, 0, 0); PG8_STAGE(PG8_SA(1, 1), a1 + hstep, voffA);
;             PG8_WAIT_V(8); PG8_WAIT_L(0); PG8_BAR; PG8_MMA(0, 0, At, B0); PG8_MMA(0, 1, At, B1); PG8_BAR; PG8_SCHED;
;             PG8_LDA(At, 0, 1); PG8_STAGE(PG8_SB(0, 0), b2, voffB); PG8_STAGE(PG8_SB(0, 1), b2 + hstep, voffB); PG8_STAGE(PG8_SA(0, 0), a2, voffA);
;             PG8_WAIT_V(8); PG8_WAIT_L(0); PG8_BAR; PG8_MMA(1, 0, At, B0); PG8_MMA(1, 1, At, B1); PG8_BAR; PG8_SCHED;
;             PG8_LDB(B0, 1, 0); PG8_LDB(B1, 1, 1); PG8_SCHED; PG8_LDA(At, 1, 0); PG8_STAGE(PG8_SA(0, 1), a2 + hstep, voffA);
;             PG8_WAIT_V(8); PG8_WAIT_L(0); PG8_BAR; PG8_MMA(0, 0, At, B0); PG8_MMA(0, 1, At, B1); PG8_BAR; PG8_SCHED;
;             PG8_LDA(At, 1, 1); PG8_STAGE(PG8_SB(1, 0), b3, voffB); PG8_STAGE(PG8_SB(1, 1), b3 + hstep, voffB); PG8_STAGE(PG8_SA(1, 0), a3, voffA);
;             PG8_WAIT_V(8); PG8_WAIT_L(0); PG8_BAR; PG8_MMA(1, 0, At, B0); PG8_MMA(1, 1, At, B1); PG8_BAR; PG8_SCHED;
	v_mfma_f32_16x16x32_bf16 v[126:129], v[130:133], v[200:203], v[126:129]
	v_mfma_f32_16x16x32_bf16 v[122:125], v[138:141], v[200:203], v[122:125]
	v_mfma_f32_16x16x32_bf16 v[110:113], v[130:133], v[208:211], v[110:113]
	v_mfma_f32_16x16x32_bf16 v[106:109], v[138:141], v[208:211], v[106:109]
	v_mfma_f32_16x16x32_bf16 v[94:97], v[130:133], v[216:219], v[94:97]
	v_mfma_f32_16x16x32_bf16 v[90:93], v[138:141], v[216:219], v[90:93]
	v_mfma_f32_16x16x32_bf16 v[78:81], v[130:133], v[224:227], v[78:81]
	v_mfma_f32_16x16x32_bf16 v[74:77], v[138:141], v[224:227], v[74:77]
	v_mfma_f32_16x16x32_bf16 v[126:129], v[134:137], v[204:207], v[126:129]
	v_mfma_f32_16x16x32_bf16 v[122:125], v[142:145], v[204:207], v[122:125]
	v_mfma_f32_16x16x32_bf16 v[110:113], v[134:137], v[212:215], v[110:113]
	v_mfma_f32_16x16x32_bf16 v[106:109], v[142:145], v[212:215], v[106:109]
	v_mfma_f32_16x16x32_bf16 v[94:97], v[134:137], v[220:223], v[94:97]
	v_mfma_f32_16x16x32_bf16 v[90:93], v[142:145], v[220:223], v[90:93]
	v_mfma_f32_16x16x32_bf16 v[78:81], v[134:137], v[228:231], v[78:81]
	v_mfma_f32_16x16x32_bf16 v[74:77], v[142:145], v[228:231], v[74:77]
	v_mfma_f32_16x16x32_bf16 v[118:121], v[176:179], v[200:203], v[118:121]
	v_mfma_f32_16x16x32_bf16 v[114:117], v[184:187], v[200:203], v[114:117]
	v_mfma_f32_16x16x32_bf16 v[102:105], v[176:179], v[208:211], v[102:105]
	v_mfma_f32_16x16x32_bf16 v[98:101], v[184:187], v[208:211], v[98:101]
	v_mfma_f32_16x16x32_bf16 v[86:89], v[176:179], v[216:219], v[86:89]
	v_mfma_f32_16x16x32_bf16 v[82:85], v[184:187], v[216:219], v[82:85]
	v_mfma_f32_16x16x32_bf16 v[70:73], v[176:179], v[224:227], v[70:73]
	v_mfma_f32_16x16x32_bf16 v[66:69], v[184:187], v[224:227], v[66:69]
	v_mfma_f32_16x16x32_bf16 v[118:121], v[180:183], v[204:207], v[118:121]
	v_mfma_f32_16x16x32_bf16 v[114:117], v[188:191], v[204:207], v[114:117]
	v_mfma_f32_16x16x32_bf16 v[102:105], v[180:183], v[212:215], v[102:105]
	v_mfma_f32_16x16x32_bf16 v[98:101], v[188:191], v[212:215], v[98:101]
	v_mfma_f32_16x16x32_bf16 v[86:89], v[180:183], v[220:223], v[86:89]
	v_mfma_f32_16x16x32_bf16 v[82:85], v[188:191], v[220:223], v[82:85]
	v_mfma_f32_16x16x32_bf16 v[70:73], v[180:183], v[228:231], v[70:73]
	v_mfma_f32_16x16x32_bf16 v[66:69], v[188:191], v[228:231], v[66:69]
	s_barrier
	s_setprio 0
	s_add_i32 s20, s77, s71
	v_lshl_add_u64 v[192:193], v[192:193], 0, s[48:49]
	s_mov_b32 m0, s20
	ds_read_b128 v[200:203], v197 offset:49152
	ds_read_b128 v[204:207], v197 offset:50176
	ds_read_b128 v[208:211], v197 offset:51200
	ds_read_b128 v[212:215], v197 offset:52224
	ds_read_b128 v[216:219], v197 offset:53248
	ds_read_b128 v[220:223], v197 offset:54272
	ds_read_b128 v[224:227], v197 offset:55296
	ds_read_b128 v[228:231], v197 offset:56320
	global_load_lds_dwordx4 v[192:193], off
	s_add_i32 m0, s20, 0x2000
	s_add_u32 s16, s16, 0x40080
	v_lshl_add_u64 v[192:193], v[232:233], 0, s[48:49]
	s_addc_u32 s17, s17, 0
	s_add_i32 s20, s79, s71
	global_load_lds_dwordx4 v[192:193], off
	v_lshl_add_u64 v[192:193], s[16:17], 0, v[148:149]
	s_mov_b32 m0, s20
	s_nop 0
	global_load_lds_dwordx4 v[192:193], off
	v_lshl_add_u64 v[192:193], s[16:17], 0, v[152:153]
	s_add_i32 m0, s20, 0x2000
	s_nop 0
	global_load_lds_dwordx4 v[192:193], off
	v_lshl_add_u64 v[192:193], v[234:235], 0, s[48:49]
	s_mov_b32 m0, s36
	s_nop 0
	global_load_lds_dwordx4 v[192:193], off
	v_lshl_add_u64 v[192:193], v[236:237], 0, s[48:49]
	s_mov_b32 m0, s37
	s_nop 0
	global_load_lds_dwordx4 v[192:193], off
	s_waitcnt vmcnt(8)
	s_waitcnt lgkmcnt(0)
	s_setprio 3
	s_barrier
	v_mfma_f32_16x16x32_bf16 v[62:65], v[130:133], v[200:203], v[62:65]
	v_mfma_f32_16x16x32_bf16 v[58:61], v[138:141], v[200:203], v[58:61]
	v_mfma_f32_16x16x32_bf16 v[46:49], v[130:133], v[208:211], v[46:49]
	v_mfma_f32_16x16x32_bf16 v[42:45], v[138:141], v[208:211], v[42:45]
	v_mfma_f32_16x16x32_bf16 v[30:33], v[130:133], v[216:219], v[30:33]
	v_mfma_f32_16x16x32_bf16 v[26:29], v[138:141], v[216:219], v[26:29]
	v_mfma_f32_16x16x32_bf16 v[14:17], v[130:133], v[224:227], v[14:17]
	v_mfma_f32_16x16x32_bf16 v[10:13], v[138:141], v[224:227], v[10:13]
	v_mfma_f32_16x16x32_bf16 v[62:65], v[134:137], v[204:207], v[62:65]
	v_mfma_f32_16x16x32_bf16 v[58:61], v[142:145], v[204:207], v[58:61]
	v_mfma_f32_16x16x32_bf16 v[46:49], v[134:137], v[212:215], v[46:49]
	v_mfma_f32_16x16x32_bf16 v[42:45], v[142:145], v[212:215], v[42:45]
	v_mfma_f32_16x16x32_bf16 v[30:33], v[134:137], v[220:223], v[30:33]
	v_mfma_f32_16x16x32_bf16 v[26:29], v[142:145], v[220:223], v[26:29]
	v_mfma_f32_16x16x32_bf16 v[14:17], v[134:137], v[228:231], v[14:17]
	v_mfma_f32_16x16x32_bf16 v[10:13], v[142:145], v[228:231], v[10:13]
	v_mfma_f32_16x16x32_bf16 v[54:57], v[176:179], v[200:203], v[54:57]
	v_mfma_f32_16x16x32_bf16 v[50:53], v[184:187], v[200:203], v[50:53]
	v_mfma_f32_16x16x32_bf16 v[38:41], v[176:179], v[208:211], v[38:41]
	v_mfma_f32_16x16x32_bf16 v[34:37], v[184:187], v[208:211], v[34:37]
	v_mfma_f32_16x16x32_bf16 v[22:25], v[176:179], v[216:219], v[22:25]
	v_mfma_f32_16x16x32_bf16 v[18:21], v[184:187], v[216:219], v[18:21]
	v_mfma_f32_16x16x32_bf16 v[6:9], v[176:179], v[224:227], v[6:9]
	v_mfma_f32_16x16x32_bf16 v[2:5], v[184:187], v[224:227], v[2:5]
	v_mfma_f32_16x16x32_bf16 v[54:57], v[180:183], v[204:207], v[54:57]
	v_mfma_f32_16x16x32_bf16 v[50:53], v[188:191], v[204:207], v[50:53]
	v_mfma_f32_16x16x32_bf16 v[38:41], v[180:183], v[212:215], v[38:41]
	v_mfma_f32_16x16x32_bf16 v[34:37], v[188:191], v[212:215], v[34:37]
	v_mfma_f32_16x16x32_bf16 v[22:25], v[180:183], v[220:223], v[22:25]
	v_mfma_f32_16x16x32_bf16 v[18:21], v[188:191], v[220:223], v[18:21]
	v_mfma_f32_16x16x32_bf16 v[6:9], v[180:183], v[228:231], v[6:9]
	v_mfma_f32_16x16x32_bf16 v[2:5], v[188:191], v[228:231], v[2:5]
	s_barrier
	s_setprio 0
	s_add_i32 s43, s43, 2
	s_add_u32 s12, s12, 0x100
	s_addc_u32 s13, s13, 0
	s_add_u32 s30, s30, 0x100
	s_addc_u32 s42, s42, 0
	s_cmp_gt_u32 s43, 13
	s_cbranch_scc0 .LBB0_1093
	s_and_b64 vcc, exec, s[50:51]
	s_cbranch_vccz .LBB0_1096
	s_barrier

; #define PG8_STAGE(bufoff, gbase, voff) do { _Pragma("unroll") for (int _i = 0; _i < 2; ++_i) \
;         __builtin_amdgcn_global_load_lds((const unsigned*)((const char*)(gbase) + (voff)[_i]), (PG8_LAS unsigned*)(lds + (bufoff) + ldsw + _i * 8192), 16, 0, 0); } while (0)
; #define PG8_LDA(dst, b, h) do { _Pragma("unroll") for (int m = 0; m < 4; ++m) _Pragma("unroll") for (int k = 0; k < 2; ++k) dst[m][k] = *(const PG8_LAS bf16x8*)(lds + PG8_SA(b, h) + aoff + m * 2048 + k * 1024); } while (0)
; #define PG8_WAIT_V(n) asm volatile("s_waitcnt vmcnt(" #n ")" ::: "memory")
; #define PG8_WAIT_L(n) asm volatile("s_waitcnt lgkmcnt(" #n ")" ::: "memory")
; #define PG8_BAR __builtin_amdgcn_s_barrier()
; template <class Epi, class Sched, bool ALIGN_EPI = false, bool SP2 = false, bool PAIR_ACC = false>
; __device__ __forceinline__ void gemm_phase(PG8_LAS unsigned char* lds, const Gemm g, const Sched& S, const Epi& E) {
;     ...
;         for (int t = 0; t < nt; t += 2) {
;             const bool last = (t == nt - 2);
;             const char* a1 = cA + (size_t)(t + 1) * kstep;
;             const char* a2 = last ? nA : cA + (size_t)(t + 2) * kstep; const char* b2 = last ? nB : cB + (size_t)(t + 2) * kstep;
;             const char* a3 = a2 + kstep; const char* b3 = b2 + kstep;
;             if (last && has_next) S.a_ready(nxt);
;             if constexpr (SP2) {
;             PG8_LDB(B0, 0, 0); PG8_LDB(B1, 0, 1); PG8_SCHED; PG8_LDA(At, 0, 0); PG8_STAGE(PG8_SA(1, 1), a1 + hstep, voffA);
;             PG8_WAIT_V(8); PG8_WAIT_L(0); PG8_BAR; PG8_MMA(0, 0, At, B0); PG8_MMA(0, 1, At, B1); PG8_BAR; PG8_SCHED;
;             PG8_LDA(At, 0, 1); PG8_STAGE(PG8_SB(0, 0), b2, voffB); PG8_STAGE(PG8_SB(0, 1), b2 + hstep, voffB); PG8_STAGE(PG8_SA(0, 0), a2, voffA);
;             PG8_WAIT_V(8); PG8_WAIT_L(0); PG8_BAR; PG8_MMA(1, 0, At, B0); PG8_MMA(1, 1, At, B1); PG8_BAR; PG8_SCHED;
;             PG8_LDB(B0, 1, 0); PG8_LDB(B1, 1, 1); PG8_SCHED; PG8_LDA(At, 1, 0); PG8_STAGE(PG8_SA(0, 1), a2 + hstep, voffA);
;             PG8_WAIT_V(8); PG8_WAIT_L(0); PG8_BAR; PG8_MMA(0, 0, At, B0); PG8_MMA(0, 1, At, B1); PG8_BAR; PG8_SCHED;
;             PG8_LDA(At, 1, 1); PG8_STAGE(PG8_SB(1, 0), b3, voffB); PG8_STAGE(PG8_SB(1, 1), b3 + hstep, voffB); PG8_STAGE(PG8_SA(1, 0), a3, voffA);
;             PG8_WAIT_V(8); PG8_WAIT_L(0); PG8_BAR; PG8_MMA(1, 0, At, B0); PG8_MMA(1, 1, At, B1); PG8_BAR; PG8_SCHED;
.LBB0_1488:
	v_add_u32_e32 v142, s51, v199
	v_add_u32_e32 v166, s52, v199
	ds_read_b128 v[130:133], v142
	ds_read_b128 v[134:137], v142 offset:1024
	ds_read_b128 v[138:141], v142 offset:2048
	ds_read_b128 v[142:145], v142 offset:3072
	ds_read_b128 v[146:149], v166
	ds_read_b128 v[150:153], v166 offset:1024
	ds_read_b128 v[154:157], v166 offset:2048
	ds_read_b128 v[176:179], v166 offset:3072
	s_add_u32 s46, s8, 0xfffc0080
	s_addc_u32 s47, s9, -1
	s_cmp_eq_u32 s54, 12
	s_cselect_b32 s49, s31, s47
	s_cselect_b32 s48, s30, s46
	s_cselect_b32 s47, s23, s53
	s_cselect_b32 s46, s29, s41
	v_lshl_add_u64 v[196:197], s[8:9], 0, v[168:169]
	s_add_i32 m0, s35, 0xc000
	ds_read_b128 v[180:183], v201
	ds_read_b128 v[184:187], v201 offset:1024
	ds_read_b128 v[188:191], v201 offset:2048
	ds_read_b128 v[192:195], v201 offset:3072
	ds_read_b128 v[202:205], v201 offset:4096
	ds_read_b128 v[206:209], v201 offset:5120
	ds_read_b128 v[210:213], v201 offset:6144
	ds_read_b128 v[214:217], v201 offset:7168
	global_load_lds_dwordx4 v[196:197], off
	v_lshl_add_u64 v[196:197], s[8:9], 0, v[170:171]
	s_add_i32 m0, s35, 0xe000
	s_nop 0
	global_load_lds_dwordx4 v[196:197], off
	s_waitcnt vmcnt(8)
	s_waitcnt lgkmcnt(0)
	s_setprio 3
	s_barrier
	v_mfma_f32_16x16x32_bf16 v[126:129], v[130:133], v[180:183], v[126:129]
	v_mfma_f32_16x16x32_bf16 v[122:125], v[138:141], v[180:183], v[122:125]
	v_mfma_f32_16x16x32_bf16 v[118:121], v[130:133], v[188:191], v[118:121]
	v_mfma_f32_16x16x32_bf16 v[114:117], v[138:141], v[188:191], v[114:117]
	v_mfma_f32_16x16x32_bf16 v[110:113], v[130:133], v[202:205], v[110:113]
	v_mfma_f32_16x16x32_bf16 v[106:109], v[138:141], v[202:205], v[106:109]
	v_mfma_f32_16x16x32_bf16 v[102:105], v[130:133], v[210:213], v[102:105]
	v_mfma_f32_16x16x32_bf16 v[98:101], v[138:141], v[210:213], v[98:101]
	v_mfma_f32_16x16x32_bf16 v[126:129], v[134:137], v[184:187], v[126:129]
	v_mfma_f32_16x16x32_bf16 v[122:125], v[142:145], v[184:187], v[122:125]
	v_mfma_f32_16x16x32_bf16 v[118:121], v[134:137], v[192:195], v[118:121]
	v_mfma_f32_16x16x32_bf16 v[114:117], v[142:145], v[192:195], v[114:117]
	v_mfma_f32_16x16x32_bf16 v[110:113], v[134:137], v[206:209], v[110:113]
	v_mfma_f32_16x16x32_bf16 v[106:109], v[142:145], v[206:209], v[106:109]
	v_mfma_f32_16x16x32_bf16 v[102:105], v[134:137], v[214:217], v[102:105]
	v_mfma_f32_16x16x32_bf16 v[98:101], v[142:145], v[214:217], v[98:101]
	v_mfma_f32_16x16x32_bf16 v[94:97], v[146:149], v[180:183], v[94:97]
	v_mfma_f32_16x16x32_bf16 v[90:93], v[154:157], v[180:183], v[90:93]
	v_mfma_f32_16x16x32_bf16 v[86:89], v[146:149], v[188:191], v[86:89]
	v_mfma_f32_16x16x32_bf16 v[82:85], v[154:157], v[188:191], v[82:85]
	v_mfma_f32_16x16x32_bf16 v[78:81], v[146:149], v[202:205], v[78:81]
	v_mfma_f32_16x16x32_bf16 v[74:77], v[154:157], v[202:205], v[74:77]
	v_mfma_f32_16x16x32_bf16 v[70:73], v[146:149], v[210:213], v[70:73]
	v_mfma_f32_16x16x32_bf16 v[66:69], v[154:157], v[210:213], v[66:69]
	v_mfma_f32_16x16x32_bf16 v[94:97], v[150:153], v[184:187], v[94:97]
	v_mfma_f32_16x16x32_bf16 v[90:93], v[176:179], v[184:187], v[90:93]
	v_mfma_f32_16x16x32_bf16 v[86:89], v[150:153], v[192:195], v[86:89]
	v_mfma_f32_16x16x32_bf16 v[82:85], v[176:179], v[192:195], v[82:85]
	v_mfma_f32_16x16x32_bf16 v[78:81], v[150:153], v[206:209], v[78:81]
	v_mfma_f32_16x16x32_bf16 v[74:77], v[176:179], v[206:209], v[74:77]
	v_mfma_f32_16x16x32_bf16 v[70:73], v[150:153], v[214:217], v[70:73]
	v_mfma_f32_16x16x32_bf16 v[66:69], v[176:179], v[214:217], v[66:69]
	s_barrier
	s_setprio 0
	s_add_i32 s55, s51, s34
	v_lshl_add_u64 v[196:197], s[46:47], 0, v[160:161]
	s_mov_b32 m0, s55
	ds_read_b128 v[180:183], v201 offset:16384
	ds_read_b128 v[184:187], v201 offset:17408
	ds_read_b128 v[188:191], v201 offset:18432
	ds_read_b128 v[192:195], v201 offset:19456
	ds_read_b128 v[202:205], v201 offset:20480
	ds_read_b128 v[206:209], v201 offset:21504
	ds_read_b128 v[210:213], v201 offset:22528
	ds_read_b128 v[214:217], v201 offset:23552
	global_load_lds_dwordx4 v[196:197], off
	s_add_i32 m0, s55, 0x2000
	s_add_u32 s56, s46, 0x40000
	v_lshl_add_u64 v[218:219], s[46:47], 0, v[164:165]
	s_addc_u32 s57, s47, 0
	s_add_i32 s55, s52, s34
	global_load_lds_dwordx4 v[218:219], off
	v_lshl_add_u64 v[220:221], s[56:57], 0, v[160:161]
	s_mov_b32 m0, s55
	v_lshl_add_u64 v[222:223], s[48:49], 0, v[162:163]
	global_load_lds_dwordx4 v[220:221], off
	v_lshl_add_u64 v[220:221], s[56:57], 0, v[164:165]
	s_add_i32 m0, s55, 0x2000
	s_nop 0
	global_load_lds_dwordx4 v[220:221], off
	v_lshl_add_u64 v[220:221], s[48:49], 0, v[158:159]
	s_mov_b32 m0, s35
	s_nop 0
	global_load_lds_dwordx4 v[220:221], off
	s_mov_b32 m0, s36
	s_nop 0
	global_load_lds_dwordx4 v[222:223], off
	s_waitcnt vmcnt(8)
	s_waitcnt lgkmcnt(0)
	s_setprio 3
	s_barrier
; #define PG8_STAGE(bufoff, gbase, voff) do { _Pragma("unroll") for (int _i = 0; _i < 2; ++_i) \
;         __builtin_amdgcn_global_load_lds((const unsigned*)((const char*)(gbase) + (voff)[_i]), (PG8_LAS unsigned*)(lds + (bufoff) + ldsw + _i * 8192), 16, 0, 0); } while (0)
; #define PG8_LDA(dst, b, h) do { _Pragma("unroll") for (int m = 0; m < 4; ++m) _Pragma("unroll") for (int k = 0; k < 2; ++k) dst[m][k] = *(const PG8_LAS bf16x8*)(lds + PG8_SA(b, h) + aoff + m * 2048 + k * 1024); } while (0)
; #define PG8_LDB(dst, b, h) do { _Pragma("unroll") for (int n = 0; n < 2; ++n) _Pragma("unroll") for (int k = 0; k < 2; ++k) dst[n][k] = *(const PG8_LAS bf16x8*)(lds + PG8_SB(b, h) + boff + n * 2048 + k * 1024); } while (0)
; #define PG8_MMA(ai, bj, At, Bt) do { __builtin_amdgcn_s_setprio(1); _Pragma("unroll") for (int m = 0; m < 4; ++m) _Pragma("unroll") for (int n = 0; n < 2; ++n) _Pragma("unroll") for (int k = 0; k < 2; ++k) \
;         acc[ai][bj][m][n] = __builtin_amdgcn_mfma_f32_16x16x32_bf16(Bt[n][k], At[m][k], acc[ai][bj][m][n], 0, 0, 0); __builtin_amdgcn_s_setprio(0); } while (0)
; template <class Epi, class Sched, bool ALIGN_EPI = false, bool SP2 = false, bool PAIR_ACC = false>
; __device__ __forceinline__ void gemm_phase(PG8_LAS unsigned char* lds, const Gemm g, const Sched& S, const Epi& E) {
;     ...
;             if constexpr (SP2) {
;             PG8_LDB(B0, 0, 0); PG8_LDB(B1, 0, 1); PG8_SCHED; PG8_LDA(At, 0, 0); PG8_STAGE(PG8_SA(1, 1), a1 + hstep, voffA);
;             PG8_WAIT_V(8); PG8_WAIT_L(0); PG8_BAR; PG8_MMA(0, 0, At, B0); PG8_MMA(0, 1, At, B1); PG8_BAR; PG8_SCHED;
;             PG8_LDA(At, 0, 1); PG8_STAGE(PG8_SB(0, 0), b2, voffB); PG8_STAGE(PG8_SB(0, 1), b2 + hstep, voffB); PG8_STAGE(PG8_SA(0, 0), a2, voffA);
;             PG8_WAIT_V(8); PG8_WAIT_L(0); PG8_BAR; PG8_MMA(1, 0, At, B0); PG8_MMA(1, 1, At, B1); PG8_BAR; PG8_SCHED;
;             PG8_LDB(B0, 1, 0); PG8_LDB(B1, 1, 1); PG8_SCHED; PG8_LDA(At, 1, 0); PG8_STAGE(PG8_SA(0, 1), a2 + hstep, voffA);
;             PG8_WAIT_V(8); PG8_WAIT_L(0); PG8_BAR; PG8_MMA(0, 0, At, B0); PG8_MMA(0, 1, At, B1); PG8_BAR; PG8_SCHED;
;             PG8_LDA(At, 1, 1); PG8_STAGE(PG8_SB(1, 0), b3, voffB); PG8_STAGE(PG8_SB(1, 1), b3 + hstep, voffB); PG8_STAGE(PG8_SA(1, 0), a3, voffA);
;             PG8_WAIT_V(8); PG8_WAIT_L(0); PG8_BAR; PG8_MMA(1, 0, At, B0); PG8_MMA(1, 1, At, B1); PG8_BAR; PG8_SCHED;
	v_mfma_f32_16x16x32_bf16 v[62:65], v[130:133], v[180:183], v[62:65]
	v_mfma_f32_16x16x32_bf16 v[58:61], v[138:141], v[180:183], v[58:61]
	v_mfma_f32_16x16x32_bf16 v[54:57], v[130:133], v[188:191], v[54:57]
	v_mfma_f32_16x16x32_bf16 v[50:53], v[138:141], v[188:191], v[50:53]
	v_mfma_f32_16x16x32_bf16 v[46:49], v[130:133], v[202:205], v[46:49]
	v_mfma_f32_16x16x32_bf16 v[42:45], v[138:141], v[202:205], v[42:45]
	v_mfma_f32_16x16x32_bf16 v[38:41], v[130:133], v[210:213], v[38:41]
	v_mfma_f32_16x16x32_bf16 v[34:37], v[138:141], v[210:213], v[34:37]
	v_mfma_f32_16x16x32_bf16 v[62:65], v[134:137], v[184:187], v[62:65]
	v_mfma_f32_16x16x32_bf16 v[58:61], v[142:145], v[184:187], v[58:61]
	v_mfma_f32_16x16x32_bf16 v[54:57], v[134:137], v[192:195], v[54:57]
	v_mfma_f32_16x16x32_bf16 v[50:53], v[142:145], v[192:195], v[50:53]
	v_mfma_f32_16x16x32_bf16 v[46:49], v[134:137], v[206:209], v[46:49]
	v_mfma_f32_16x16x32_bf16 v[42:45], v[142:145], v[206:209], v[42:45]
	v_mfma_f32_16x16x32_bf16 v[38:41], v[134:137], v[214:217], v[38:41]
	v_mfma_f32_16x16x32_bf16 v[34:37], v[142:145], v[214:217], v[34:37]
	v_mfma_f32_16x16x32_bf16 v[30:33], v[146:149], v[180:183], v[30:33]
	v_mfma_f32_16x16x32_bf16 v[26:29], v[154:157], v[180:183], v[26:29]
	v_mfma_f32_16x16x32_bf16 v[22:25], v[146:149], v[188:191], v[22:25]
	v_mfma_f32_16x16x32_bf16 v[18:21], v[154:157], v[188:191], v[18:21]
	v_mfma_f32_16x16x32_bf16 v[14:17], v[146:149], v[202:205], v[14:17]
	v_mfma_f32_16x16x32_bf16 v[10:13], v[154:157], v[202:205], v[10:13]
	v_mfma_f32_16x16x32_bf16 v[6:9], v[146:149], v[210:213], v[6:9]
	v_mfma_f32_16x16x32_bf16 v[2:5], v[154:157], v[210:213], v[2:5]
	v_mfma_f32_16x16x32_bf16 v[30:33], v[150:153], v[184:187], v[30:33]
	v_mfma_f32_16x16x32_bf16 v[26:29], v[176:179], v[184:187], v[26:29]
	v_mfma_f32_16x16x32_bf16 v[22:25], v[150:153], v[192:195], v[22:25]
	v_mfma_f32_16x16x32_bf16 v[18:21], v[176:179], v[192:195], v[18:21]
	v_mfma_f32_16x16x32_bf16 v[14:17], v[150:153], v[206:209], v[14:17]
	v_mfma_f32_16x16x32_bf16 v[10:13], v[176:179], v[206:209], v[10:13]
	v_mfma_f32_16x16x32_bf16 v[6:9], v[150:153], v[214:217], v[6:9]
	v_mfma_f32_16x16x32_bf16 v[2:5], v[176:179], v[214:217], v[2:5]
	s_barrier
	s_setprio 0
	s_add_i32 s55, 0, 0x18000
	s_add_i32 s56, 0, 0x1c000
	v_add_u32_e32 v142, s55, v199
	v_add_u32_e32 v166, s56, v199
	ds_read_b128 v[130:133], v142
	ds_read_b128 v[134:137], v142 offset:1024
	ds_read_b128 v[138:141], v142 offset:2048
	ds_read_b128 v[142:145], v142 offset:3072
	ds_read_b128 v[146:149], v166
	ds_read_b128 v[150:153], v166 offset:1024
	ds_read_b128 v[154:157], v166 offset:2048
	ds_read_b128 v[176:179], v166 offset:3072
	s_add_u32 s48, s48, 0x40000
	s_addc_u32 s49, s49, 0
	s_mov_b32 m0, s37
	v_lshl_add_u64 v[224:225], s[48:49], 0, v[158:159]
	ds_read_b128 v[180:183], v201 offset:32768
	ds_read_b128 v[184:187], v201 offset:33792
	ds_read_b128 v[188:191], v201 offset:34816
	ds_read_b128 v[192:195], v201 offset:35840
	ds_read_b128 v[202:205], v201 offset:36864
	ds_read_b128 v[206:209], v201 offset:37888
	ds_read_b128 v[210:213], v201 offset:38912
	ds_read_b128 v[214:217], v201 offset:39936
	global_load_lds_dwordx4 v[224:225], off
	v_lshl_add_u64 v[224:225], s[48:49], 0, v[162:163]
	s_mov_b32 m0, s42
	s_nop 0
	global_load_lds_dwordx4 v[224:225], off
	s_waitcnt vmcnt(8)
	s_waitcnt lgkmcnt(0)
	s_setprio 3
	s_barrier
	v_mfma_f32_16x16x32_bf16 v[126:129], v[130:133], v[180:183], v[126:129]
	v_mfma_f32_16x16x32_bf16 v[122:125], v[138:141], v[180:183], v[122:125]
	v_mfma_f32_16x16x32_bf16 v[118:121], v[130:133], v[188:191], v[118:121]
	v_mfma_f32_16x16x32_bf16 v[114:117], v[138:141], v[188:191], v[114:117]
	v_mfma_f32_16x16x32_bf16 v[110:113], v[130:133], v[202:205], v[110:113]
	v_mfma_f32_16x16x32_bf16 v[106:109], v[138:141], v[202:205], v[106:109]
	v_mfma_f32_16x16x32_bf16 v[102:105], v[130:133], v[210:213], v[102:105]
	v_mfma_f32_16x16x32_bf16 v[98:101], v[138:141], v[210:213], v[98:101]
	v_mfma_f32_16x16x32_bf16 v[126:129], v[134:137], v[184:187], v[126:129]
	v_mfma_f32_16x16x32_bf16 v[122:125], v[142:145], v[184:187], v[122:125]
	v_mfma_f32_16x16x32_bf16 v[118:121], v[134:137], v[192:195], v[118:121]
	v_mfma_f32_16x16x32_bf16 v[114:117], v[142:145], v[192:195], v[114:117]
	v_mfma_f32_16x16x32_bf16 v[110:113], v[134:137], v[206:209], v[110:113]
	v_mfma_f32_16x16x32_bf16 v[106:109], v[142:145], v[206:209], v[106:109]
	v_mfma_f32_16x16x32_bf16 v[102:105], v[134:137], v[214:217], v[102:105]
	v_mfma_f32_16x16x32_bf16 v[98:101], v[142:145], v[214:217], v[98:101]
	v_mfma_f32_16x16x32_bf16 v[94:97], v[146:149], v[180:183], v[94:97]
	v_mfma_f32_16x16x32_bf16 v[90:93], v[154:157], v[180:183], v[90:93]
	v_mfma_f32_16x16x32_bf16 v[86:89], v[146:149], v[188:191], v[86:89]
	v_mfma_f32_16x16x32_bf16 v[82:85], v[154:157], v[188:191], v[82:85]
	v_mfma_f32_16x16x32_bf16 v[78:81], v[146:149], v[202:205], v[78:81]
	v_mfma_f32_16x16x32_bf16 v[74:77], v[154:157], v[202:205], v[74:77]
	v_mfma_f32_16x16x32_bf16 v[70:73], v[146:149], v[210:213], v[70:73]
	v_mfma_f32_16x16x32_bf16 v[66:69], v[154:157], v[210:213], v[66:69]
	v_mfma_f32_16x16x32_bf16 v[94:97], v[150:153], v[184:187], v[94:97]
	v_mfma_f32_16x16x32_bf16 v[90:93], v[176:179], v[184:187], v[90:93]
	v_mfma_f32_16x16x32_bf16 v[86:89], v[150:153], v[192:195], v[86:89]
	v_mfma_f32_16x16x32_bf16 v[82:85], v[176:179], v[192:195], v[82:85]
	v_mfma_f32_16x16x32_bf16 v[78:81], v[150:153], v[206:209], v[78:81]
	v_mfma_f32_16x16x32_bf16 v[74:77], v[176:179], v[206:209], v[74:77]
	v_mfma_f32_16x16x32_bf16 v[70:73], v[150:153], v[214:217], v[70:73]
	v_mfma_f32_16x16x32_bf16 v[66:69], v[176:179], v[214:217], v[66:69]
	s_barrier
; #define PG8_STAGE(bufoff, gbase, voff) do { _Pragma("unroll") for (int _i = 0; _i < 2; ++_i) \
;         __builtin_amdgcn_global_load_lds((const unsigned*)((const char*)(gbase) + (voff)[_i]), (PG8_LAS unsigned*)(lds + (bufoff) + ldsw + _i * 8192), 16, 0, 0); } while (0)
; #define PG8_LDA(dst, b, h) do { _Pragma("unroll") for (int m = 0; m < 4; ++m) _Pragma("unroll") for (int k = 0; k < 2; ++k) dst[m][k] = *(const PG8_LAS bf16x8*)(lds + PG8_SA(b, h) + aoff + m * 2048 + k * 1024); } while (0)
; #define PG8_LDB(dst, b, h) do { _Pragma("unroll") for (int n = 0; n < 2; ++n) _Pragma("unroll") for (int k = 0; k < 2; ++k) dst[n][k] = *(const PG8_LAS bf16x8*)(lds + PG8_SB(b, h) + boff + n * 2048 + k * 1024); } while (0)
; #define PG8_MMA(ai, bj, At, Bt) do { __builtin_amdgcn_s_setprio(1); _Pragma("unroll") for (int m = 0; m < 4; ++m) _Pragma("unroll") for (int n = 0; n < 2; ++n) _Pragma("unroll") for (int k = 0; k < 2; ++k) \
;         acc[ai][bj][m][n] = __builtin_amdgcn_mfma_f32_16x16x32_bf16(Bt[n][k], At[m][k], acc[ai][bj][m][n], 0, 0, 0); __builtin_amdgcn_s_setprio(0); } while (0)
; template <class Epi, class Sched, bool ALIGN_EPI = false, bool SP2 = false, bool PAIR_ACC = false>
; __device__ __forceinline__ void gemm_phase(PG8_LAS unsigned char* lds, const Gemm g, const Sched& S, const Epi& E) {
;     ...
;             if constexpr (SP2) {
;             PG8_LDB(B0, 0, 0); PG8_LDB(B1, 0, 1); PG8_SCHED; PG8_LDA(At, 0, 0); PG8_STAGE(PG8_SA(1, 1), a1 + hstep, voffA);
;             PG8_WAIT_V(8); PG8_WAIT_L(0); PG8_BAR; PG8_MMA(0, 0, At, B0); PG8_MMA(0, 1, At, B1); PG8_BAR; PG8_SCHED;
;             PG8_LDA(At, 0, 1); PG8_STAGE(PG8_SB(0, 0), b2, voffB); PG8_STAGE(PG8_SB(0, 1), b2 + hstep, voffB); PG8_STAGE(PG8_SA(0, 0), a2, voffA);
;             PG8_WAIT_V(8); PG8_WAIT_L(0); PG8_BAR; PG8_MMA(1, 0, At, B0); PG8_MMA(1, 1, At, B1); PG8_BAR; PG8_SCHED;
;             PG8_LDB(B0, 1, 0); PG8_LDB(B1, 1, 1); PG8_SCHED; PG8_LDA(At, 1, 0); PG8_STAGE(PG8_SA(0, 1), a2 + hstep, voffA);
;             PG8_WAIT_V(8); PG8_WAIT_L(0); PG8_BAR; PG8_MMA(0, 0, At, B0); PG8_MMA(0, 1, At, B1); PG8_BAR; PG8_SCHED;
;             PG8_LDA(At, 1, 1); PG8_STAGE(PG8_SB(1, 0), b3, voffB); PG8_STAGE(PG8_SB(1, 1), b3 + hstep, voffB); PG8_STAGE(PG8_SA(1, 0), a3, voffA);
;             PG8_WAIT_V(8); PG8_WAIT_L(0); PG8_BAR; PG8_MMA(1, 0, At, B0); PG8_MMA(1, 1, At, B1); PG8_BAR; PG8_SCHED;
	s_setprio 0
	s_add_i32 s48, s55, s34
	v_lshl_add_u64 v[196:197], v[196:197], 0, s[18:19]
	s_mov_b32 m0, s48
	ds_read_b128 v[180:183], v201 offset:49152
	ds_read_b128 v[184:187], v201 offset:50176
	ds_read_b128 v[188:191], v201 offset:51200
	ds_read_b128 v[192:195], v201 offset:52224
	ds_read_b128 v[202:205], v201 offset:53248
	ds_read_b128 v[206:209], v201 offset:54272
	ds_read_b128 v[210:213], v201 offset:55296
	ds_read_b128 v[214:217], v201 offset:56320
	global_load_lds_dwordx4 v[196:197], off
	s_add_i32 m0, s48, 0x2000
	s_add_u32 s46, s46, 0x40080
	v_lshl_add_u64 v[196:197], v[218:219], 0, s[18:19]
	s_addc_u32 s47, s47, 0
	s_add_i32 s48, s56, s34
	global_load_lds_dwordx4 v[196:197], off
	v_lshl_add_u64 v[196:197], s[46:47], 0, v[160:161]
	s_mov_b32 m0, s48
	s_nop 0
	global_load_lds_dwordx4 v[196:197], off
	v_lshl_add_u64 v[196:197], s[46:47], 0, v[164:165]
	s_add_i32 m0, s48, 0x2000
	s_nop 0
	global_load_lds_dwordx4 v[196:197], off
	v_lshl_add_u64 v[196:197], v[220:221], 0, s[18:19]
	s_mov_b32 m0, s45
	s_nop 0
	global_load_lds_dwordx4 v[196:197], off
	v_lshl_add_u64 v[196:197], v[222:223], 0, s[18:19]
	s_mov_b32 m0, s50
	s_nop 0
	global_load_lds_dwordx4 v[196:197], off
	s_waitcnt vmcnt(8)
	s_waitcnt lgkmcnt(0)
	s_setprio 3
	s_barrier
	v_mfma_f32_16x16x32_bf16 v[62:65], v[130:133], v[180:183], v[62:65]
	v_mfma_f32_16x16x32_bf16 v[58:61], v[138:141], v[180:183], v[58:61]
	v_mfma_f32_16x16x32_bf16 v[54:57], v[130:133], v[188:191], v[54:57]
	v_mfma_f32_16x16x32_bf16 v[50:53], v[138:141], v[188:191], v[50:53]
	v_mfma_f32_16x16x32_bf16 v[46:49], v[130:133], v[202:205], v[46:49]
	v_mfma_f32_16x16x32_bf16 v[42:45], v[138:141], v[202:205], v[42:45]
	v_mfma_f32_16x16x32_bf16 v[38:41], v[130:133], v[210:213], v[38:41]
	v_mfma_f32_16x16x32_bf16 v[34:37], v[138:141], v[210:213], v[34:37]
	v_mfma_f32_16x16x32_bf16 v[62:65], v[134:137], v[184:187], v[62:65]
	v_mfma_f32_16x16x32_bf16 v[58:61], v[142:145], v[184:187], v[58:61]
	v_mfma_f32_16x16x32_bf16 v[54:57], v[134:137], v[192:195], v[54:57]
	v_mfma_f32_16x16x32_bf16 v[50:53], v[142:145], v[192:195], v[50:53]
	v_mfma_f32_16x16x32_bf16 v[46:49], v[134:137], v[206:209], v[46:49]
	v_mfma_f32_16x16x32_bf16 v[42:45], v[142:145], v[206:209], v[42:45]
	v_mfma_f32_16x16x32_bf16 v[38:41], v[134:137], v[214:217], v[38:41]
	v_mfma_f32_16x16x32_bf16 v[34:37], v[142:145], v[214:217], v[34:37]
	v_mfma_f32_16x16x32_bf16 v[30:33], v[146:149], v[180:183], v[30:33]
	v_mfma_f32_16x16x32_bf16 v[26:29], v[154:157], v[180:183], v[26:29]
	v_mfma_f32_16x16x32_bf16 v[22:25], v[146:149], v[188:191], v[22:25]
	v_mfma_f32_16x16x32_bf16 v[18:21], v[154:157], v[188:191], v[18:21]
	v_mfma_f32_16x16x32_bf16 v[14:17], v[146:149], v[202:205], v[14:17]
	v_mfma_f32_16x16x32_bf16 v[10:13], v[154:157], v[202:205], v[10:13]
	v_mfma_f32_16x16x32_bf16 v[6:9], v[146:149], v[210:213], v[6:9]
	v_mfma_f32_16x16x32_bf16 v[2:5], v[154:157], v[210:213], v[2:5]
	v_mfma_f32_16x16x32_bf16 v[30:33], v[150:153], v[184:187], v[30:33]
	v_mfma_f32_16x16x32_bf16 v[26:29], v[176:179], v[184:187], v[26:29]
	v_mfma_f32_16x16x32_bf16 v[22:25], v[150:153], v[192:195], v[22:25]
	v_mfma_f32_16x16x32_bf16 v[18:21], v[176:179], v[192:195], v[18:21]
	v_mfma_f32_16x16x32_bf16 v[14:17], v[150:153], v[206:209], v[14:17]
	v_mfma_f32_16x16x32_bf16 v[10:13], v[176:179], v[206:209], v[10:13]
	v_mfma_f32_16x16x32_bf16 v[6:9], v[150:153], v[214:217], v[6:9]
	v_mfma_f32_16x16x32_bf16 v[2:5], v[176:179], v[214:217], v[2:5]
	s_barrier
	s_setprio 0
	s_add_i32 s54, s54, 2
	s_add_u32 s8, s8, 0x100
	s_addc_u32 s9, s9, 0
	s_add_u32 s41, s41, 0x100
	s_addc_u32 s53, s53, 0
	s_cmp_gt_u32 s54, 13
	s_cbranch_scc0 .LBB0_1488
	s_and_b64 vcc, exec, s[20:21]
	s_cbranch_vccz .LBB0_1491
	s_barrier

; #define PG8_STAGE(bufoff, gbase, voff) do { _Pragma("unroll") for (int _i = 0; _i < 2; ++_i) \
;         __builtin_amdgcn_global_load_lds((const unsigned*)((const char*)(gbase) + (voff)[_i]), (PG8_LAS unsigned*)(lds + (bufoff) + ldsw + _i * 8192), 16, 0, 0); } while (0)
; #define PG8_LDA(dst, b, h) do { _Pragma("unroll") for (int m = 0; m < 4; ++m) _Pragma("unroll") for (int k = 0; k < 2; ++k) dst[m][k] = *(const PG8_LAS bf16x8*)(lds + PG8_SA(b, h) + aoff + m * 2048 + k * 1024); } while (0)
; #define PG8_WAIT_V(n) asm volatile("s_waitcnt vmcnt(" #n ")" ::: "memory")
; #define PG8_WAIT_L(n) asm volatile("s_waitcnt lgkmcnt(" #n ")" ::: "memory")
; #define PG8_BAR __builtin_amdgcn_s_barrier()
; template <class Epi, class Sched, bool ALIGN_EPI = false, bool SP2 = false, bool PAIR_ACC = false>
; __device__ __forceinline__ void gemm_phase(PG8_LAS unsigned char* lds, const Gemm g, const Sched& S, const Epi& E) {
;     ...
;         for (int t = 0; t < nt; t += 2) {
;             const bool last = (t == nt - 2);
;             const char* a1 = cA + (size_t)(t + 1) * kstep;
;             const char* a2 = last ? nA : cA + (size_t)(t + 2) * kstep; const char* b2 = last ? nB : cB + (size_t)(t + 2) * kstep;
;             const char* a3 = a2 + kstep; const char* b3 = b2 + kstep;
;             if (last && has_next) S.a_ready(nxt);
;             if constexpr (SP2) {
;             PG8_LDB(B0, 0, 0); PG8_LDB(B1, 0, 1); PG8_SCHED; PG8_LDA(At, 0, 0); PG8_STAGE(PG8_SA(1, 1), a1 + hstep, voffA);
;             PG8_WAIT_V(8); PG8_WAIT_L(0); PG8_BAR; PG8_MMA(0, 0, At, B0); PG8_MMA(0, 1, At, B1); PG8_BAR; PG8_SCHED;
;             PG8_LDA(At, 0, 1); PG8_STAGE(PG8_SB(0, 0), b2, voffB); PG8_STAGE(PG8_SB(0, 1), b2 + hstep, voffB); PG8_STAGE(PG8_SA(0, 0), a2, voffA);
;             PG8_WAIT_V(8); PG8_WAIT_L(0); PG8_BAR; PG8_MMA(1, 0, At, B0); PG8_MMA(1, 1, At, B1); PG8_BAR; PG8_SCHED;
;             PG8_LDB(B0, 1, 0); PG8_LDB(B1, 1, 1); PG8_SCHED; PG8_LDA(At, 1, 0); PG8_STAGE(PG8_SA(0, 1), a2 + hstep, voffA);
;             PG8_WAIT_V(8); PG8_WAIT_L(0); PG8_BAR; PG8_MMA(0, 0, At, B0); PG8_MMA(0, 1, At, B1); PG8_BAR; PG8_SCHED;
;             PG8_LDA(At, 1, 1); PG8_STAGE(PG8_SB(1, 0), b3, voffB); PG8_STAGE(PG8_SB(1, 1), b3 + hstep, voffB); PG8_STAGE(PG8_SA(1, 0), a3, voffA);
;             PG8_WAIT_V(8); PG8_WAIT_L(0); PG8_BAR; PG8_MMA(1, 0, At, B0); PG8_MMA(1, 1, At, B1); PG8_BAR; PG8_SCHED;
.LBB0_1630:
	v_add_u32_e32 v164, s57, v150
	ds_read_b128 v[152:155], v164
	ds_read_b128 v[156:159], v164 offset:1024
	ds_read_b128 v[160:163], v164 offset:2048
	ds_read_b128 v[170:173], v164 offset:3072
	v_add_u32_e32 v164, s58, v150
	s_add_u32 s46, s20, s44
	ds_read_b128 v[174:177], v164
	ds_read_b128 v[178:181], v164 offset:1024
	ds_read_b128 v[182:185], v164 offset:2048
	ds_read_b128 v[186:189], v164 offset:3072
	s_addc_u32 s47, s21, s45
	s_add_u32 s46, s46, 0x100
	s_addc_u32 s47, s47, 0
	s_add_u32 s63, s42, s44
	s_addc_u32 s64, s43, s45
	s_cmpk_eq_i32 s44, 0x700
	s_cselect_b32 s49, s31, s47
	s_cselect_b32 s48, s60, s46
	s_cselect_b32 s47, s29, s64
	s_cselect_b32 s46, s61, s63
	v_lshl_add_u64 v[164:165], v[146:147], 0, s[44:45]
	s_add_i32 m0, s50, 0xc000
	ds_read_b128 v[190:193], v151
	ds_read_b128 v[194:197], v151 offset:1024
	ds_read_b128 v[198:201], v151 offset:2048
	ds_read_b128 v[202:205], v151 offset:3072
	ds_read_b128 v[206:209], v151 offset:4096
	ds_read_b128 v[210:213], v151 offset:5120
	ds_read_b128 v[214:217], v151 offset:6144
	ds_read_b128 v[218:221], v151 offset:7168
	global_load_lds_dwordx4 v[164:165], off
	v_lshl_add_u64 v[164:165], v[148:149], 0, s[44:45]
	s_add_i32 m0, s50, 0xe000
	s_nop 0
	global_load_lds_dwordx4 v[164:165], off
	s_waitcnt vmcnt(8)
	s_waitcnt lgkmcnt(0)
	s_setprio 3
	s_barrier
	v_mfma_f32_16x16x32_bf16 v[58:61], v[152:155], v[190:193], v[58:61]
	v_mfma_f32_16x16x32_bf16 v[62:65], v[160:163], v[190:193], v[62:65]
	v_mfma_f32_16x16x32_bf16 v[78:81], v[152:155], v[198:201], v[78:81]
	v_mfma_f32_16x16x32_bf16 v[70:73], v[160:163], v[198:201], v[70:73]
	v_mfma_f32_16x16x32_bf16 v[98:101], v[152:155], v[206:209], v[98:101]
	v_mfma_f32_16x16x32_bf16 v[90:93], v[160:163], v[206:209], v[90:93]
	v_mfma_f32_16x16x32_bf16 v[114:117], v[152:155], v[214:217], v[114:117]
	v_mfma_f32_16x16x32_bf16 v[106:109], v[160:163], v[214:217], v[106:109]
	v_mfma_f32_16x16x32_bf16 v[58:61], v[156:159], v[194:197], v[58:61]
	v_mfma_f32_16x16x32_bf16 v[62:65], v[170:173], v[194:197], v[62:65]
	v_mfma_f32_16x16x32_bf16 v[78:81], v[156:159], v[202:205], v[78:81]
	v_mfma_f32_16x16x32_bf16 v[70:73], v[170:173], v[202:205], v[70:73]
	v_mfma_f32_16x16x32_bf16 v[98:101], v[156:159], v[210:213], v[98:101]
	v_mfma_f32_16x16x32_bf16 v[90:93], v[170:173], v[210:213], v[90:93]
	v_mfma_f32_16x16x32_bf16 v[114:117], v[156:159], v[218:221], v[114:117]
	v_mfma_f32_16x16x32_bf16 v[106:109], v[170:173], v[218:221], v[106:109]
	v_mfma_f32_16x16x32_bf16 v[54:57], v[174:177], v[190:193], v[54:57]
	v_mfma_f32_16x16x32_bf16 v[46:49], v[182:185], v[190:193], v[46:49]
	v_mfma_f32_16x16x32_bf16 v[50:53], v[174:177], v[198:201], v[50:53]
	v_mfma_f32_16x16x32_bf16 v[42:45], v[182:185], v[198:201], v[42:45]
	v_mfma_f32_16x16x32_bf16 v[74:77], v[174:177], v[206:209], v[74:77]
	v_mfma_f32_16x16x32_bf16 v[66:69], v[182:185], v[206:209], v[66:69]
	v_mfma_f32_16x16x32_bf16 v[102:105], v[174:177], v[214:217], v[102:105]
	v_mfma_f32_16x16x32_bf16 v[94:97], v[182:185], v[214:217], v[94:97]
	v_mfma_f32_16x16x32_bf16 v[54:57], v[178:181], v[194:197], v[54:57]
	v_mfma_f32_16x16x32_bf16 v[46:49], v[186:189], v[194:197], v[46:49]
	v_mfma_f32_16x16x32_bf16 v[50:53], v[178:181], v[202:205], v[50:53]
	v_mfma_f32_16x16x32_bf16 v[42:45], v[186:189], v[202:205], v[42:45]
	v_mfma_f32_16x16x32_bf16 v[74:77], v[178:181], v[210:213], v[74:77]
	v_mfma_f32_16x16x32_bf16 v[66:69], v[186:189], v[210:213], v[66:69]
	v_mfma_f32_16x16x32_bf16 v[102:105], v[178:181], v[218:221], v[102:105]
	v_mfma_f32_16x16x32_bf16 v[94:97], v[186:189], v[218:221], v[94:97]
	s_barrier
	s_setprio 0
	s_add_i32 s63, s57, s37
	v_lshl_add_u64 v[164:165], s[46:47], 0, v[132:133]
	s_mov_b32 m0, s63
	ds_read_b128 v[190:193], v151 offset:16384
	ds_read_b128 v[194:197], v151 offset:17408
	ds_read_b128 v[198:201], v151 offset:18432
	ds_read_b128 v[202:205], v151 offset:19456
	ds_read_b128 v[206:209], v151 offset:20480
	ds_read_b128 v[210:213], v151 offset:21504
	ds_read_b128 v[214:217], v151 offset:22528
	ds_read_b128 v[218:221], v151 offset:23552
	global_load_lds_dwordx4 v[164:165], off
	s_add_i32 m0, s63, 0x2000
	s_add_u32 s68, s46, 0x40000
	v_lshl_add_u64 v[222:223], s[46:47], 0, v[136:137]
	s_addc_u32 s69, s47, 0
	s_add_i32 s63, s58, s37
	global_load_lds_dwordx4 v[222:223], off
	v_lshl_add_u64 v[224:225], s[68:69], 0, v[132:133]
	s_mov_b32 m0, s63
	v_lshl_add_u64 v[226:227], s[48:49], 0, v[134:135]
	global_load_lds_dwordx4 v[224:225], off
	v_lshl_add_u64 v[224:225], s[68:69], 0, v[136:137]
	s_add_i32 m0, s63, 0x2000
	s_nop 0
	global_load_lds_dwordx4 v[224:225], off
	v_lshl_add_u64 v[224:225], s[48:49], 0, v[130:131]
	s_mov_b32 m0, s50
	s_nop 0
	global_load_lds_dwordx4 v[224:225], off
	s_mov_b32 m0, s51
	s_nop 0
	global_load_lds_dwordx4 v[226:227], off
	s_waitcnt vmcnt(8)
	s_waitcnt lgkmcnt(0)
	s_setprio 3
	s_barrier
; #define PG8_STAGE(bufoff, gbase, voff) do { _Pragma("unroll") for (int _i = 0; _i < 2; ++_i) \
;         __builtin_amdgcn_global_load_lds((const unsigned*)((const char*)(gbase) + (voff)[_i]), (PG8_LAS unsigned*)(lds + (bufoff) + ldsw + _i * 8192), 16, 0, 0); } while (0)
; #define PG8_LDA(dst, b, h) do { _Pragma("unroll") for (int m = 0; m < 4; ++m) _Pragma("unroll") for (int k = 0; k < 2; ++k) dst[m][k] = *(const PG8_LAS bf16x8*)(lds + PG8_SA(b, h) + aoff + m * 2048 + k * 1024); } while (0)
; #define PG8_LDB(dst, b, h) do { _Pragma("unroll") for (int n = 0; n < 2; ++n) _Pragma("unroll") for (int k = 0; k < 2; ++k) dst[n][k] = *(const PG8_LAS bf16x8*)(lds + PG8_SB(b, h) + boff + n * 2048 + k * 1024); } while (0)
; #define PG8_MMA(ai, bj, At, Bt) do { __builtin_amdgcn_s_setprio(1); _Pragma("unroll") for (int m = 0; m < 4; ++m) _Pragma("unroll") for (int n = 0; n < 2; ++n) _Pragma("unroll") for (int k = 0; k < 2; ++k) \
;         acc[ai][bj][m][n] = __builtin_amdgcn_mfma_f32_16x16x32_bf16(Bt[n][k], At[m][k], acc[ai][bj][m][n], 0, 0, 0); __builtin_amdgcn_s_setprio(0); } while (0)
; template <class Epi, class Sched, bool ALIGN_EPI = false, bool SP2 = false, bool PAIR_ACC = false>
; __device__ __forceinline__ void gemm_phase(PG8_LAS unsigned char* lds, const Gemm g, const Sched& S, const Epi& E) {
;     ...
;             if constexpr (SP2) {
;             PG8_LDB(B0, 0, 0); PG8_LDB(B1, 0, 1); PG8_SCHED; PG8_LDA(At, 0, 0); PG8_STAGE(PG8_SA(1, 1), a1 + hstep, voffA);
;             PG8_WAIT_V(8); PG8_WAIT_L(0); PG8_BAR; PG8_MMA(0, 0, At, B0); PG8_MMA(0, 1, At, B1); PG8_BAR; PG8_SCHED;
;             PG8_LDA(At, 0, 1); PG8_STAGE(PG8_SB(0, 0), b2, voffB); PG8_STAGE(PG8_SB(0, 1), b2 + hstep, voffB); PG8_STAGE(PG8_SA(0, 0), a2, voffA);
;             PG8_WAIT_V(8); PG8_WAIT_L(0); PG8_BAR; PG8_MMA(1, 0, At, B0); PG8_MMA(1, 1, At, B1); PG8_BAR; PG8_SCHED;
;             PG8_LDB(B0, 1, 0); PG8_LDB(B1, 1, 1); PG8_SCHED; PG8_LDA(At, 1, 0); PG8_STAGE(PG8_SA(0, 1), a2 + hstep, voffA);
;             PG8_WAIT_V(8); PG8_WAIT_L(0); PG8_BAR; PG8_MMA(0, 0, At, B0); PG8_MMA(0, 1, At, B1); PG8_BAR; PG8_SCHED;
;             PG8_LDA(At, 1, 1); PG8_STAGE(PG8_SB(1, 0), b3, voffB); PG8_STAGE(PG8_SB(1, 1), b3 + hstep, voffB); PG8_STAGE(PG8_SA(1, 0), a3, voffA);
;             PG8_WAIT_V(8); PG8_WAIT_L(0); PG8_BAR; PG8_MMA(1, 0, At, B0); PG8_MMA(1, 1, At, B1); PG8_BAR; PG8_SCHED;
	v_mfma_f32_16x16x32_bf16 v[126:129], v[152:155], v[190:193], v[126:129]
	v_mfma_f32_16x16x32_bf16 v[122:125], v[160:163], v[190:193], v[122:125]
	v_mfma_f32_16x16x32_bf16 v[86:89], v[152:155], v[198:201], v[86:89]
	v_mfma_f32_16x16x32_bf16 v[82:85], v[160:163], v[198:201], v[82:85]
	v_mfma_f32_16x16x32_bf16 v[30:33], v[152:155], v[206:209], v[30:33]
	v_mfma_f32_16x16x32_bf16 v[26:29], v[160:163], v[206:209], v[26:29]
	v_mfma_f32_16x16x32_bf16 v[14:17], v[152:155], v[214:217], v[14:17]
	v_mfma_f32_16x16x32_bf16 v[10:13], v[160:163], v[214:217], v[10:13]
	v_mfma_f32_16x16x32_bf16 v[126:129], v[156:159], v[194:197], v[126:129]
	v_mfma_f32_16x16x32_bf16 v[122:125], v[170:173], v[194:197], v[122:125]
	v_mfma_f32_16x16x32_bf16 v[86:89], v[156:159], v[202:205], v[86:89]
	v_mfma_f32_16x16x32_bf16 v[82:85], v[170:173], v[202:205], v[82:85]
	v_mfma_f32_16x16x32_bf16 v[30:33], v[156:159], v[210:213], v[30:33]
	v_mfma_f32_16x16x32_bf16 v[26:29], v[170:173], v[210:213], v[26:29]
	v_mfma_f32_16x16x32_bf16 v[14:17], v[156:159], v[218:221], v[14:17]
	v_mfma_f32_16x16x32_bf16 v[10:13], v[170:173], v[218:221], v[10:13]
	v_mfma_f32_16x16x32_bf16 v[118:121], v[174:177], v[190:193], v[118:121]
	v_mfma_f32_16x16x32_bf16 v[110:113], v[182:185], v[190:193], v[110:113]
	v_mfma_f32_16x16x32_bf16 v[38:41], v[174:177], v[198:201], v[38:41]
	v_mfma_f32_16x16x32_bf16 v[34:37], v[182:185], v[198:201], v[34:37]
	v_mfma_f32_16x16x32_bf16 v[22:25], v[174:177], v[206:209], v[22:25]
	v_mfma_f32_16x16x32_bf16 v[18:21], v[182:185], v[206:209], v[18:21]
	v_mfma_f32_16x16x32_bf16 v[6:9], v[174:177], v[214:217], v[6:9]
	v_mfma_f32_16x16x32_bf16 v[2:5], v[182:185], v[214:217], v[2:5]
	v_mfma_f32_16x16x32_bf16 v[118:121], v[178:181], v[194:197], v[118:121]
	v_mfma_f32_16x16x32_bf16 v[110:113], v[186:189], v[194:197], v[110:113]
	v_mfma_f32_16x16x32_bf16 v[38:41], v[178:181], v[202:205], v[38:41]
	v_mfma_f32_16x16x32_bf16 v[34:37], v[186:189], v[202:205], v[34:37]
	v_mfma_f32_16x16x32_bf16 v[22:25], v[178:181], v[210:213], v[22:25]
	v_mfma_f32_16x16x32_bf16 v[18:21], v[186:189], v[210:213], v[18:21]
	v_mfma_f32_16x16x32_bf16 v[6:9], v[178:181], v[218:221], v[6:9]
	v_mfma_f32_16x16x32_bf16 v[2:5], v[186:189], v[218:221], v[2:5]
	s_barrier
	s_setprio 0
	s_add_i32 s63, 0, 0x18000
	v_add_u32_e32 v169, s63, v150
	s_add_i32 s64, 0, 0x1c000
	ds_read_b128 v[152:155], v169
	ds_read_b128 v[156:159], v169 offset:1024
	ds_read_b128 v[160:163], v169 offset:2048
	ds_read_b128 v[170:173], v169 offset:3072
	v_add_u32_e32 v169, s64, v150
	ds_read_b128 v[174:177], v169
	ds_read_b128 v[178:181], v169 offset:1024
	ds_read_b128 v[182:185], v169 offset:2048
	ds_read_b128 v[186:189], v169 offset:3072
	s_add_u32 s48, s48, 0x40000
	s_addc_u32 s49, s49, 0
	s_mov_b32 m0, s52
	v_lshl_add_u64 v[228:229], s[48:49], 0, v[130:131]
	ds_read_b128 v[190:193], v151 offset:32768
	ds_read_b128 v[194:197], v151 offset:33792
	ds_read_b128 v[198:201], v151 offset:34816
	ds_read_b128 v[202:205], v151 offset:35840
	ds_read_b128 v[206:209], v151 offset:36864
	ds_read_b128 v[210:213], v151 offset:37888
	ds_read_b128 v[214:217], v151 offset:38912
	ds_read_b128 v[218:221], v151 offset:39936
	global_load_lds_dwordx4 v[228:229], off
	v_lshl_add_u64 v[228:229], s[48:49], 0, v[134:135]
	s_mov_b32 m0, s53
	s_nop 0
	global_load_lds_dwordx4 v[228:229], off
	s_waitcnt vmcnt(8)
	s_waitcnt lgkmcnt(0)
	s_setprio 3
	s_barrier
	v_mfma_f32_16x16x32_bf16 v[58:61], v[152:155], v[190:193], v[58:61]
	v_mfma_f32_16x16x32_bf16 v[62:65], v[160:163], v[190:193], v[62:65]
	v_mfma_f32_16x16x32_bf16 v[78:81], v[152:155], v[198:201], v[78:81]
	v_mfma_f32_16x16x32_bf16 v[70:73], v[160:163], v[198:201], v[70:73]
	v_mfma_f32_16x16x32_bf16 v[98:101], v[152:155], v[206:209], v[98:101]
	v_mfma_f32_16x16x32_bf16 v[90:93], v[160:163], v[206:209], v[90:93]
	v_mfma_f32_16x16x32_bf16 v[114:117], v[152:155], v[214:217], v[114:117]
	v_mfma_f32_16x16x32_bf16 v[106:109], v[160:163], v[214:217], v[106:109]
	v_mfma_f32_16x16x32_bf16 v[58:61], v[156:159], v[194:197], v[58:61]
	v_mfma_f32_16x16x32_bf16 v[62:65], v[170:173], v[194:197], v[62:65]
	v_mfma_f32_16x16x32_bf16 v[78:81], v[156:159], v[202:205], v[78:81]
	v_mfma_f32_16x16x32_bf16 v[70:73], v[170:173], v[202:205], v[70:73]
	v_mfma_f32_16x16x32_bf16 v[98:101], v[156:159], v[210:213], v[98:101]
	v_mfma_f32_16x16x32_bf16 v[90:93], v[170:173], v[210:213], v[90:93]
	v_mfma_f32_16x16x32_bf16 v[114:117], v[156:159], v[218:221], v[114:117]
	v_mfma_f32_16x16x32_bf16 v[106:109], v[170:173], v[218:221], v[106:109]
	v_mfma_f32_16x16x32_bf16 v[54:57], v[174:177], v[190:193], v[54:57]
	v_mfma_f32_16x16x32_bf16 v[46:49], v[182:185], v[190:193], v[46:49]
	v_mfma_f32_16x16x32_bf16 v[50:53], v[174:177], v[198:201], v[50:53]
	v_mfma_f32_16x16x32_bf16 v[42:45], v[182:185], v[198:201], v[42:45]
	v_mfma_f32_16x16x32_bf16 v[74:77], v[174:177], v[206:209], v[74:77]
	v_mfma_f32_16x16x32_bf16 v[66:69], v[182:185], v[206:209], v[66:69]
	v_mfma_f32_16x16x32_bf16 v[102:105], v[174:177], v[214:217], v[102:105]
	v_mfma_f32_16x16x32_bf16 v[94:97], v[182:185], v[214:217], v[94:97]
	v_mfma_f32_16x16x32_bf16 v[54:57], v[178:181], v[194:197], v[54:57]
	v_mfma_f32_16x16x32_bf16 v[46:49], v[186:189], v[194:197], v[46:49]
	v_mfma_f32_16x16x32_bf16 v[50:53], v[178:181], v[202:205], v[50:53]
	v_mfma_f32_16x16x32_bf16 v[42:45], v[186:189], v[202:205], v[42:45]
	v_mfma_f32_16x16x32_bf16 v[74:77], v[178:181], v[210:213], v[74:77]
	v_mfma_f32_16x16x32_bf16 v[66:69], v[186:189], v[210:213], v[66:69]
	v_mfma_f32_16x16x32_bf16 v[102:105], v[178:181], v[218:221], v[102:105]
	v_mfma_f32_16x16x32_bf16 v[94:97], v[186:189], v[218:221], v[94:97]
	s_barrier
; #define PG8_STAGE(bufoff, gbase, voff) do { _Pragma("unroll") for (int _i = 0; _i < 2; ++_i) \
;         __builtin_amdgcn_global_load_lds((const unsigned*)((const char*)(gbase) + (voff)[_i]), (PG8_LAS unsigned*)(lds + (bufoff) + ldsw + _i * 8192), 16, 0, 0); } while (0)
; #define PG8_LDA(dst, b, h) do { _Pragma("unroll") for (int m = 0; m < 4; ++m) _Pragma("unroll") for (int k = 0; k < 2; ++k) dst[m][k] = *(const PG8_LAS bf16x8*)(lds + PG8_SA(b, h) + aoff + m * 2048 + k * 1024); } while (0)
; #define PG8_LDB(dst, b, h) do { _Pragma("unroll") for (int n = 0; n < 2; ++n) _Pragma("unroll") for (int k = 0; k < 2; ++k) dst[n][k] = *(const PG8_LAS bf16x8*)(lds + PG8_SB(b, h) + boff + n * 2048 + k * 1024); } while (0)
; #define PG8_BAR __builtin_amdgcn_s_barrier()
; template <class Epi, class Sched, bool ALIGN_EPI = false, bool SP2 = false, bool PAIR_ACC = false>
; __device__ __forceinline__ void gemm_phase(PG8_LAS unsigned char* lds, const Gemm g, const Sched& S, const Epi& E) {
;     ...
;             if constexpr (SP2) {
;             PG8_LDB(B0, 0, 0); PG8_LDB(B1, 0, 1); PG8_SCHED; PG8_LDA(At, 0, 0); PG8_STAGE(PG8_SA(1, 1), a1 + hstep, voffA);
;             PG8_WAIT_V(8); PG8_WAIT_L(0); PG8_BAR; PG8_MMA(0, 0, At, B0); PG8_MMA(0, 1, At, B1); PG8_BAR; PG8_SCHED;
;             PG8_LDA(At, 0, 1); PG8_STAGE(PG8_SB(0, 0), b2, voffB); PG8_STAGE(PG8_SB(0, 1), b2 + hstep, voffB); PG8_STAGE(PG8_SA(0, 0), a2, voffA);
;             PG8_WAIT_V(8); PG8_WAIT_L(0); PG8_BAR; PG8_MMA(1, 0, At, B0); PG8_MMA(1, 1, At, B1); PG8_BAR; PG8_SCHED;
;             PG8_LDB(B0, 1, 0); PG8_LDB(B1, 1, 1); PG8_SCHED; PG8_LDA(At, 1, 0); PG8_STAGE(PG8_SA(0, 1), a2 + hstep, voffA);
;             PG8_WAIT_V(8); PG8_WAIT_L(0); PG8_BAR; PG8_MMA(0, 0, At, B0); PG8_MMA(0, 1, At, B1); PG8_BAR; PG8_SCHED;
;             PG8_LDA(At, 1, 1); PG8_STAGE(PG8_SB(1, 0), b3, voffB); PG8_STAGE(PG8_SB(1, 1), b3 + hstep, voffB); PG8_STAGE(PG8_SA(1, 0), a3, voffA);
;             PG8_WAIT_V(8); PG8_WAIT_L(0); PG8_BAR; PG8_MMA(1, 0, At, B0); PG8_MMA(1, 1, At, B1); PG8_BAR; PG8_SCHED;
;     ...
;         if (!(PAIR_ACC && cur.pn < 4)) {
; #pragma unroll
;         for (int a = 0; a < 2; ++a)
; #pragma unroll
;             for (int b = 0; b < 2; ++b)
; #pragma unroll
;                 for (int m = 0; m < 4; ++m)
; #pragma unroll
;                     for (int n = 0; n < 2; ++n) acc[a][b][m][n] = (f32x4){0.f, 0.f, 0.f, 0.f};
	s_setprio 0
	s_add_i32 s48, s63, s37
	v_lshl_add_u64 v[164:165], v[164:165], 0, s[22:23]
	s_mov_b32 m0, s48
	ds_read_b128 v[190:193], v151 offset:49152
	ds_read_b128 v[194:197], v151 offset:50176
	ds_read_b128 v[198:201], v151 offset:51200
	ds_read_b128 v[202:205], v151 offset:52224
	ds_read_b128 v[206:209], v151 offset:53248
	ds_read_b128 v[210:213], v151 offset:54272
	ds_read_b128 v[214:217], v151 offset:55296
	ds_read_b128 v[218:221], v151 offset:56320
	global_load_lds_dwordx4 v[164:165], off
	s_add_i32 m0, s48, 0x2000
	s_add_u32 s46, s46, 0x40080
	v_lshl_add_u64 v[164:165], v[222:223], 0, s[22:23]
	s_addc_u32 s47, s47, 0
	s_add_i32 s48, s64, s37
	global_load_lds_dwordx4 v[164:165], off
	v_lshl_add_u64 v[164:165], s[46:47], 0, v[132:133]
	s_mov_b32 m0, s48
	s_nop 0
	global_load_lds_dwordx4 v[164:165], off
	v_lshl_add_u64 v[164:165], s[46:47], 0, v[136:137]
	s_add_i32 m0, s48, 0x2000
	s_nop 0
	global_load_lds_dwordx4 v[164:165], off
	v_lshl_add_u64 v[164:165], v[224:225], 0, s[22:23]
	s_mov_b32 m0, s55
	s_nop 0
	global_load_lds_dwordx4 v[164:165], off
	v_lshl_add_u64 v[164:165], v[226:227], 0, s[22:23]
	s_mov_b32 m0, s56
	s_nop 0
	global_load_lds_dwordx4 v[164:165], off
	s_waitcnt vmcnt(8)
	s_waitcnt lgkmcnt(0)
	s_setprio 3
	s_barrier
	v_mfma_f32_16x16x32_bf16 v[126:129], v[152:155], v[190:193], v[126:129]
	v_mfma_f32_16x16x32_bf16 v[122:125], v[160:163], v[190:193], v[122:125]
	v_mfma_f32_16x16x32_bf16 v[86:89], v[152:155], v[198:201], v[86:89]
	v_mfma_f32_16x16x32_bf16 v[82:85], v[160:163], v[198:201], v[82:85]
	v_mfma_f32_16x16x32_bf16 v[30:33], v[152:155], v[206:209], v[30:33]
	v_mfma_f32_16x16x32_bf16 v[26:29], v[160:163], v[206:209], v[26:29]
	v_mfma_f32_16x16x32_bf16 v[14:17], v[152:155], v[214:217], v[14:17]
	v_mfma_f32_16x16x32_bf16 v[10:13], v[160:163], v[214:217], v[10:13]
	v_mfma_f32_16x16x32_bf16 v[126:129], v[156:159], v[194:197], v[126:129]
	v_mfma_f32_16x16x32_bf16 v[122:125], v[170:173], v[194:197], v[122:125]
	v_mfma_f32_16x16x32_bf16 v[86:89], v[156:159], v[202:205], v[86:89]
	v_mfma_f32_16x16x32_bf16 v[82:85], v[170:173], v[202:205], v[82:85]
	v_mfma_f32_16x16x32_bf16 v[30:33], v[156:159], v[210:213], v[30:33]
	v_mfma_f32_16x16x32_bf16 v[26:29], v[170:173], v[210:213], v[26:29]
	v_mfma_f32_16x16x32_bf16 v[14:17], v[156:159], v[218:221], v[14:17]
	v_mfma_f32_16x16x32_bf16 v[10:13], v[170:173], v[218:221], v[10:13]
	v_mfma_f32_16x16x32_bf16 v[118:121], v[174:177], v[190:193], v[118:121]
	v_mfma_f32_16x16x32_bf16 v[110:113], v[182:185], v[190:193], v[110:113]
	v_mfma_f32_16x16x32_bf16 v[38:41], v[174:177], v[198:201], v[38:41]
	v_mfma_f32_16x16x32_bf16 v[34:37], v[182:185], v[198:201], v[34:37]
	v_mfma_f32_16x16x32_bf16 v[22:25], v[174:177], v[206:209], v[22:25]
	v_mfma_f32_16x16x32_bf16 v[18:21], v[182:185], v[206:209], v[18:21]
	v_mfma_f32_16x16x32_bf16 v[6:9], v[174:177], v[214:217], v[6:9]
	v_mfma_f32_16x16x32_bf16 v[2:5], v[182:185], v[214:217], v[2:5]
	v_mfma_f32_16x16x32_bf16 v[118:121], v[178:181], v[194:197], v[118:121]
	v_mfma_f32_16x16x32_bf16 v[110:113], v[186:189], v[194:197], v[110:113]
	v_mfma_f32_16x16x32_bf16 v[38:41], v[178:181], v[202:205], v[38:41]
	v_mfma_f32_16x16x32_bf16 v[34:37], v[186:189], v[202:205], v[34:37]
	v_mfma_f32_16x16x32_bf16 v[22:25], v[178:181], v[210:213], v[22:25]
	v_mfma_f32_16x16x32_bf16 v[18:21], v[186:189], v[210:213], v[18:21]
	v_mfma_f32_16x16x32_bf16 v[6:9], v[178:181], v[218:221], v[6:9]
	v_mfma_f32_16x16x32_bf16 v[2:5], v[186:189], v[218:221], v[2:5]
	s_barrier
	s_setprio 0
	s_add_i32 s62, s62, 2
	s_add_u32 s44, s44, 0x100
	s_addc_u32 s45, s45, 0
	s_cmp_gt_u32 s62, 13
	s_cbranch_scc0 .LBB0_1630
	s_add_u32 s42, s42, 0xffffff00
	s_addc_u32 s43, s43, -1
	s_andn2_b64 vcc, exec, s[8:9]
	s_cbranch_vccnz .LBB0_1621
	v_mov_b32_e32 v2, 0
	s_mov_b32 s10, s28
	s_mov_b32 s18, s30
	s_mov_b64 s[20:21], s[40:41]
	s_mov_b32 s54, s59
	v_mov_b32_e32 v3, v2
	v_mov_b32_e32 v4, v2
	v_mov_b32_e32 v5, v2
	v_mov_b32_e32 v6, v2
	v_mov_b32_e32 v7, v2
	v_mov_b32_e32 v8, v2
	v_mov_b32_e32 v9, v2
	v_mov_b32_e32 v18, v2
	v_mov_b32_e32 v19, v2
	v_mov_b32_e32 v20, v2
	v_mov_b32_e32 v21, v2
	v_mov_b32_e32 v22, v2
	v_mov_b32_e32 v23, v2
	v_mov_b32_e32 v24, v2
	v_mov_b32_e32 v25, v2
	v_mov_b32_e32 v34, v2
	v_mov_b32_e32 v35, v2
	v_mov_b32_e32 v36, v2
	v_mov_b32_e32 v37, v2
	v_mov_b32_e32 v38, v2
	v_mov_b32_e32 v39, v2
	v_mov_b32_e32 v40, v2
	v_mov_b32_e32 v41, v2
	v_mov_b32_e32 v110, v2
	v_mov_b32_e32 v111, v2
	v_mov_b32_e32 v112, v2
	v_mov_b32_e32 v113, v2
	v_mov_b32_e32 v118, v2
	v_mov_b32_e32 v119, v2
	v_mov_b32_e32 v120, v2
	v_mov_b32_e32 v121, v2
	v_mov_b32_e32 v10, v2
	v_mov_b32_e32 v11, v2
	v_mov_b32_e32 v12, v2
	v_mov_b32_e32 v13, v2
	v_mov_b32_e32 v14, v2
	v_mov_b32_e32 v15, v2
	v_mov_b32_e32 v16, v2
	v_mov_b32_e32 v17, v2
	v_mov_b32_e32 v26, v2
	v_mov_b32_e32 v27, v2
	v_mov_b32_e32 v28, v2
	v_mov_b32_e32 v29, v2
	v_mov_b32_e32 v30, v2
	v_mov_b32_e32 v31, v2
	v_mov_b32_e32 v32, v2
	v_mov_b32_e32 v33, v2
	v_mov_b32_e32 v82, v2
	v_mov_b32_e32 v83, v2
	v_mov_b32_e32 v84, v2
	v_mov_b32_e32 v85, v2
	v_mov_b32_e32 v86, v2
	v_mov_b32_e32 v87, v2
	v_mov_b32_e32 v88, v2
	v_mov_b32_e32 v89, v2
	v_mov_b32_e32 v122, v2
	v_mov_b32_e32 v123, v2
	v_mov_b32_e32 v124, v2
	v_mov_b32_e32 v125, v2
	v_mov_b32_e32 v126, v2
	v_mov_b32_e32 v127, v2
	v_mov_b32_e32 v128, v2
	v_mov_b32_e32 v129, v2
	v_mov_b32_e32 v94, v2
	v_mov_b32_e32 v95, v2
	v_mov_b32_e32 v96, v2
	v_mov_b32_e32 v97, v2
	v_mov_b32_e32 v102, v2
	v_mov_b32_e32 v103, v2
	v_mov_b32_e32 v104, v2
	v_mov_b32_e32 v105, v2
	v_mov_b32_e32 v66, v2
	v_mov_b32_e32 v67, v2
	v_mov_b32_e32 v68, v2
	v_mov_b32_e32 v69, v2
	v_mov_b32_e32 v74, v2
	v_mov_b32_e32 v75, v2
	v_mov_b32_e32 v76, v2
	v_mov_b32_e32 v77, v2
	v_mov_b32_e32 v42, v2
	v_mov_b32_e32 v43, v2
	v_mov_b32_e32 v44, v2
	v_mov_b32_e32 v45, v2
	v_mov_b32_e32 v50, v2
	v_mov_b32_e32 v51, v2
	v_mov_b32_e32 v52, v2
	v_mov_b32_e32 v53, v2
	v_mov_b32_e32 v46, v2
	v_mov_b32_e32 v47, v2
	v_mov_b32_e32 v48, v2
	v_mov_b32_e32 v49, v2
	v_mov_b32_e32 v54, v2
	v_mov_b32_e32 v55, v2
	v_mov_b32_e32 v56, v2
	v_mov_b32_e32 v57, v2
	v_mov_b32_e32 v106, v2
	v_mov_b32_e32 v107, v2
	v_mov_b32_e32 v108, v2
	v_mov_b32_e32 v109, v2
	v_mov_b32_e32 v114, v2
	v_mov_b32_e32 v115, v2
	v_mov_b32_e32 v116, v2
	v_mov_b32_e32 v117, v2
	v_mov_b32_e32 v90, v2
	v_mov_b32_e32 v91, v2
	v_mov_b32_e32 v92, v2
	v_mov_b32_e32 v93, v2
	v_mov_b32_e32 v98, v2
	v_mov_b32_e32 v99, v2
	v_mov_b32_e32 v100, v2
	v_mov_b32_e32 v101, v2
	v_mov_b32_e32 v70, v2
	v_mov_b32_e32 v71, v2
	v_mov_b32_e32 v72, v2
	v_mov_b32_e32 v73, v2
	v_mov_b32_e32 v78, v2
	v_mov_b32_e32 v79, v2
	v_mov_b32_e32 v80, v2
	v_mov_b32_e32 v81, v2
	v_mov_b32_e32 v62, v2
	v_mov_b32_e32 v63, v2
	v_mov_b32_e32 v64, v2
	v_mov_b32_e32 v65, v2
	v_mov_b32_e32 v58, v2
	v_mov_b32_e32 v59, v2
	v_mov_b32_e32 v60, v2
	v_mov_b32_e32 v61, v2
	s_andn2_b64 vcc, exec, s[6:7]
	s_cbranch_vccnz .LBB0_1622

; #define PG8_STAGE(bufoff, gbase, voff) do { _Pragma("unroll") for (int _i = 0; _i < 2; ++_i) \
;         __builtin_amdgcn_global_load_lds((const unsigned*)((const char*)(gbase) + (voff)[_i]), (PG8_LAS unsigned*)(lds + (bufoff) + ldsw + _i * 8192), 16, 0, 0); } while (0)
; #define PG8_WAIT_V(n) asm volatile("s_waitcnt vmcnt(" #n ")" ::: "memory")
; #define PG8_WAIT_L(n) asm volatile("s_waitcnt lgkmcnt(" #n ")" ::: "memory")
; template <class Epi, class Sched, bool ALIGN_EPI = false, bool SP2 = false, bool PAIR_ACC = false>
; __device__ __forceinline__ void gemm_phase(PG8_LAS unsigned char* lds, const Gemm g, const Sched& S, const Epi& E) {
;     ...
;         const bool has_next = S.next(ui + 1, nxt);
;         const char* nA = has_next ? (const char*)g.A + (size_t)nxt.pm * tstep + (size_t)(nxt.pn / g.a_div) * g.a_sel : cA; const char* nB = has_next ? (const char*)g.Bt + (size_t)nxt.pn * tstep : cB;
;         for (int t = 0; t < nt; t += 2) {
;             const bool last = (t == nt - 2);
;             const char* a1 = cA + (size_t)(t + 1) * kstep;
;             const char* a2 = last ? nA : cA + (size_t)(t + 2) * kstep; const char* b2 = last ? nB : cB + (size_t)(t + 2) * kstep;
;             const char* a3 = a2 + kstep; const char* b3 = b2 + kstep;
;             if (last && has_next) S.a_ready(nxt);
;             if constexpr (SP2) {
;             PG8_LDB(B0, 0, 0); PG8_LDB(B1, 0, 1); PG8_SCHED; PG8_LDA(At, 0, 0); PG8_STAGE(PG8_SA(1, 1), a1 + hstep, voffA);
;             PG8_WAIT_V(8); PG8_WAIT_L(0); PG8_BAR; PG8_MMA(0, 0, At, B0); PG8_MMA(0, 1, At, B1); PG8_BAR; PG8_SCHED;
;             PG8_LDA(At, 0, 1); PG8_STAGE(PG8_SB(0, 0), b2, voffB); PG8_STAGE(PG8_SB(0, 1), b2 + hstep, voffB); PG8_STAGE(PG8_SA(0, 0), a2, voffA);
;             PG8_WAIT_V(8); PG8_WAIT_L(0); PG8_BAR; PG8_MMA(1, 0, At, B0); PG8_MMA(1, 1, At, B1); PG8_BAR; PG8_SCHED;
;             PG8_LDB(B0, 1, 0); PG8_LDB(B1, 1, 1); PG8_SCHED; PG8_LDA(At, 1, 0); PG8_STAGE(PG8_SA(0, 1), a2 + hstep, voffA);
;             PG8_WAIT_V(8); PG8_WAIT_L(0); PG8_BAR; PG8_MMA(0, 0, At, B0); PG8_MMA(0, 1, At, B1); PG8_BAR; PG8_SCHED;
;             PG8_LDA(At, 1, 1); PG8_STAGE(PG8_SB(1, 0), b3, voffB); PG8_STAGE(PG8_SB(1, 1), b3 + hstep, voffB); PG8_STAGE(PG8_SA(1, 0), a3, voffA);
;             PG8_WAIT_V(8); PG8_WAIT_L(0); PG8_BAR; PG8_MMA(1, 0, At, B0); PG8_MMA(1, 1, At, B1); PG8_BAR; PG8_SCHED;
.LBB0_1736:
	s_ashr_i32 s53, s52, 31
	s_lshl_b64 s[10:11], s[52:53], 19
	s_add_u32 s54, s4, s10
	s_addc_u32 s55, s5, s11
	s_and_b64 s[10:11], s[8:9], exec
	s_cselect_b32 s53, s55, s63
	s_cselect_b32 s75, s54, s62
	s_ashr_i32 s51, s50, 31
	s_lshl_b64 s[10:11], s[50:51], 19
	s_add_u32 s56, s24, s10
	s_addc_u32 s57, s25, s11
	s_and_b64 s[10:11], s[8:9], exec
	s_cselect_b32 s51, s57, s61
	s_cselect_b32 s76, s56, s60
	s_add_u32 s10, s62, 0x40080
	s_addc_u32 s11, s63, 0
	s_add_u32 s77, s60, 0x100
	s_addc_u32 s78, s61, 0
	s_mov_b32 s79, -2
	ds_read_b128 v[74:77], v196
	ds_read_b128 v[78:81], v196 offset:1024
	ds_read_b128 v[82:85], v196 offset:2048
	ds_read_b128 v[86:89], v196 offset:3072
	ds_read_b128 v[90:93], v197
	ds_read_b128 v[94:97], v197 offset:1024
	ds_read_b128 v[98:101], v197 offset:2048
	ds_read_b128 v[106:109], v197 offset:3072
	s_add_u32 s60, s10, 0xfffc0080
	s_addc_u32 s61, s11, -1
	s_cmp_eq_u32 s79, 12
	s_cselect_b32 s63, s53, s61
	s_cselect_b32 s62, s75, s60
	s_cselect_b32 s61, s51, s78
	s_cselect_b32 s60, s76, s77
	v_lshl_add_u64 v[170:171], s[10:11], 0, v[184:185]
	s_add_i32 m0, s36, 0xc000
	ds_read_b128 v[162:165], v198
	ds_read_b128 v[166:169], v198 offset:1024
	ds_read_b128 v[204:207], v198 offset:2048
	ds_read_b128 v[208:211], v198 offset:3072
	ds_read_b128 v[212:215], v198 offset:4096
	ds_read_b128 v[216:219], v198 offset:5120
	ds_read_b128 v[220:223], v198 offset:6144
	ds_read_b128 v[224:227], v198 offset:7168
	global_load_lds_dwordx4 v[170:171], off
	v_lshl_add_u64 v[170:171], s[10:11], 0, v[186:187]
	s_add_i32 m0, s36, 0xe000
	s_nop 0
	global_load_lds_dwordx4 v[170:171], off
	s_waitcnt vmcnt(8)
	s_waitcnt lgkmcnt(0)
	s_setprio 3
	s_barrier
	v_mfma_f32_16x16x32_bf16 v[150:153], v[74:77], v[162:165], 0
	v_mfma_f32_16x16x32_bf16 v[146:149], v[82:85], v[162:165], 0
	v_mfma_f32_16x16x32_bf16 v[134:137], v[74:77], v[204:207], 0
	v_mfma_f32_16x16x32_bf16 v[130:133], v[82:85], v[204:207], 0
	v_mfma_f32_16x16x32_bf16 v[118:121], v[74:77], v[212:215], 0
	v_mfma_f32_16x16x32_bf16 v[110:113], v[82:85], v[212:215], 0
	v_mfma_f32_16x16x32_bf16 v[114:117], v[74:77], v[220:223], 0
	v_mfma_f32_16x16x32_bf16 v[102:105], v[82:85], v[220:223], 0
	v_mfma_f32_16x16x32_bf16 v[150:153], v[78:81], v[166:169], v[150:153]
	v_mfma_f32_16x16x32_bf16 v[146:149], v[86:89], v[166:169], v[146:149]
	v_mfma_f32_16x16x32_bf16 v[134:137], v[78:81], v[208:211], v[134:137]
	v_mfma_f32_16x16x32_bf16 v[130:133], v[86:89], v[208:211], v[130:133]
	v_mfma_f32_16x16x32_bf16 v[118:121], v[78:81], v[216:219], v[118:121]
	v_mfma_f32_16x16x32_bf16 v[110:113], v[86:89], v[216:219], v[110:113]
	v_mfma_f32_16x16x32_bf16 v[114:117], v[78:81], v[224:227], v[114:117]
	v_mfma_f32_16x16x32_bf16 v[102:105], v[86:89], v[224:227], v[102:105]
	v_mfma_f32_16x16x32_bf16 v[158:161], v[90:93], v[162:165], 0
	v_mfma_f32_16x16x32_bf16 v[154:157], v[98:101], v[162:165], 0
	v_mfma_f32_16x16x32_bf16 v[142:145], v[90:93], v[204:207], 0
	v_mfma_f32_16x16x32_bf16 v[138:141], v[98:101], v[204:207], 0
	v_mfma_f32_16x16x32_bf16 v[126:129], v[90:93], v[212:215], 0
	v_mfma_f32_16x16x32_bf16 v[122:125], v[98:101], v[212:215], 0
	v_mfma_f32_16x16x32_bf16 v[70:73], v[90:93], v[220:223], 0
	v_mfma_f32_16x16x32_bf16 v[66:69], v[98:101], v[220:223], 0
	v_mfma_f32_16x16x32_bf16 v[158:161], v[94:97], v[166:169], v[158:161]
	v_mfma_f32_16x16x32_bf16 v[154:157], v[106:109], v[166:169], v[154:157]
	v_mfma_f32_16x16x32_bf16 v[142:145], v[94:97], v[208:211], v[142:145]
	v_mfma_f32_16x16x32_bf16 v[138:141], v[106:109], v[208:211], v[138:141]
	v_mfma_f32_16x16x32_bf16 v[126:129], v[94:97], v[216:219], v[126:129]
	v_mfma_f32_16x16x32_bf16 v[122:125], v[106:109], v[216:219], v[122:125]
	v_mfma_f32_16x16x32_bf16 v[70:73], v[94:97], v[224:227], v[70:73]
	v_mfma_f32_16x16x32_bf16 v[66:69], v[106:109], v[224:227], v[66:69]
	s_barrier
	s_setprio 0
	s_add_i32 s80, s70, s34
	v_lshl_add_u64 v[170:171], s[60:61], 0, v[176:177]
	s_mov_b32 m0, s80
	ds_read_b128 v[162:165], v198 offset:16384
	ds_read_b128 v[166:169], v198 offset:17408
	ds_read_b128 v[204:207], v198 offset:18432
	ds_read_b128 v[208:211], v198 offset:19456
	ds_read_b128 v[212:215], v198 offset:20480
	ds_read_b128 v[216:219], v198 offset:21504
	ds_read_b128 v[220:223], v198 offset:22528
	ds_read_b128 v[224:227], v198 offset:23552
	global_load_lds_dwordx4 v[170:171], off
	s_add_i32 m0, s80, 0x2000
	s_add_u32 s80, s60, 0x40000
	v_lshl_add_u64 v[192:193], s[60:61], 0, v[172:173]
	s_addc_u32 s81, s61, 0
	s_add_i32 s82, s71, s34
	global_load_lds_dwordx4 v[192:193], off
	v_lshl_add_u64 v[228:229], s[80:81], 0, v[176:177]
	s_mov_b32 m0, s82
	v_lshl_add_u64 v[230:231], s[62:63], 0, v[174:175]
	global_load_lds_dwordx4 v[228:229], off
	v_lshl_add_u64 v[228:229], s[80:81], 0, v[172:173]
	s_add_i32 m0, s82, 0x2000
	s_nop 0
	global_load_lds_dwordx4 v[228:229], off
	v_lshl_add_u64 v[228:229], s[62:63], 0, v[178:179]
	s_mov_b32 m0, s36
	s_nop 0
	global_load_lds_dwordx4 v[228:229], off
	s_mov_b32 m0, s37
	s_nop 0
	global_load_lds_dwordx4 v[230:231], off
	s_waitcnt vmcnt(8)
	s_waitcnt lgkmcnt(0)
	s_setprio 3
	s_barrier
; #define PG8_STAGE(bufoff, gbase, voff) do { _Pragma("unroll") for (int _i = 0; _i < 2; ++_i) \
;         __builtin_amdgcn_global_load_lds((const unsigned*)((const char*)(gbase) + (voff)[_i]), (PG8_LAS unsigned*)(lds + (bufoff) + ldsw + _i * 8192), 16, 0, 0); } while (0)
; #define PG8_LDA(dst, b, h) do { _Pragma("unroll") for (int m = 0; m < 4; ++m) _Pragma("unroll") for (int k = 0; k < 2; ++k) dst[m][k] = *(const PG8_LAS bf16x8*)(lds + PG8_SA(b, h) + aoff + m * 2048 + k * 1024); } while (0)
; #define PG8_LDB(dst, b, h) do { _Pragma("unroll") for (int n = 0; n < 2; ++n) _Pragma("unroll") for (int k = 0; k < 2; ++k) dst[n][k] = *(const PG8_LAS bf16x8*)(lds + PG8_SB(b, h) + boff + n * 2048 + k * 1024); } while (0)
; #define PG8_MMA(ai, bj, At, Bt) do { __builtin_amdgcn_s_setprio(1); _Pragma("unroll") for (int m = 0; m < 4; ++m) _Pragma("unroll") for (int n = 0; n < 2; ++n) _Pragma("unroll") for (int k = 0; k < 2; ++k) \
;         acc[ai][bj][m][n] = __builtin_amdgcn_mfma_f32_16x16x32_bf16(Bt[n][k], At[m][k], acc[ai][bj][m][n], 0, 0, 0); __builtin_amdgcn_s_setprio(0); } while (0)
; template <class Epi, class Sched, bool ALIGN_EPI = false, bool SP2 = false, bool PAIR_ACC = false>
; __device__ __forceinline__ void gemm_phase(PG8_LAS unsigned char* lds, const Gemm g, const Sched& S, const Epi& E) {
;     ...
;             if constexpr (SP2) {
;             PG8_LDB(B0, 0, 0); PG8_LDB(B1, 0, 1); PG8_SCHED; PG8_LDA(At, 0, 0); PG8_STAGE(PG8_SA(1, 1), a1 + hstep, voffA);
;             PG8_WAIT_V(8); PG8_WAIT_L(0); PG8_BAR; PG8_MMA(0, 0, At, B0); PG8_MMA(0, 1, At, B1); PG8_BAR; PG8_SCHED;
;             PG8_LDA(At, 0, 1); PG8_STAGE(PG8_SB(0, 0), b2, voffB); PG8_STAGE(PG8_SB(0, 1), b2 + hstep, voffB); PG8_STAGE(PG8_SA(0, 0), a2, voffA);
;             PG8_WAIT_V(8); PG8_WAIT_L(0); PG8_BAR; PG8_MMA(1, 0, At, B0); PG8_MMA(1, 1, At, B1); PG8_BAR; PG8_SCHED;
;             PG8_LDB(B0, 1, 0); PG8_LDB(B1, 1, 1); PG8_SCHED; PG8_LDA(At, 1, 0); PG8_STAGE(PG8_SA(0, 1), a2 + hstep, voffA);
;             PG8_WAIT_V(8); PG8_WAIT_L(0); PG8_BAR; PG8_MMA(0, 0, At, B0); PG8_MMA(0, 1, At, B1); PG8_BAR; PG8_SCHED;
;             PG8_LDA(At, 1, 1); PG8_STAGE(PG8_SB(1, 0), b3, voffB); PG8_STAGE(PG8_SB(1, 1), b3 + hstep, voffB); PG8_STAGE(PG8_SA(1, 0), a3, voffA);
;             PG8_WAIT_V(8); PG8_WAIT_L(0); PG8_BAR; PG8_MMA(1, 0, At, B0); PG8_MMA(1, 1, At, B1); PG8_BAR; PG8_SCHED;
	v_mfma_f32_16x16x32_bf16 v[54:57], v[74:77], v[162:165], 0
	v_mfma_f32_16x16x32_bf16 v[50:53], v[82:85], v[162:165], 0
	v_mfma_f32_16x16x32_bf16 v[38:41], v[74:77], v[204:207], 0
	v_mfma_f32_16x16x32_bf16 v[34:37], v[82:85], v[204:207], 0
	v_mfma_f32_16x16x32_bf16 v[22:25], v[74:77], v[212:215], 0
	v_mfma_f32_16x16x32_bf16 v[14:17], v[82:85], v[212:215], 0
	v_mfma_f32_16x16x32_bf16 v[18:21], v[74:77], v[220:223], 0
	v_mfma_f32_16x16x32_bf16 v[10:13], v[82:85], v[220:223], 0
	v_mfma_f32_16x16x32_bf16 v[54:57], v[78:81], v[166:169], v[54:57]
	v_mfma_f32_16x16x32_bf16 v[50:53], v[86:89], v[166:169], v[50:53]
	v_mfma_f32_16x16x32_bf16 v[38:41], v[78:81], v[208:211], v[38:41]
	v_mfma_f32_16x16x32_bf16 v[34:37], v[86:89], v[208:211], v[34:37]
	v_mfma_f32_16x16x32_bf16 v[22:25], v[78:81], v[216:219], v[22:25]
	v_mfma_f32_16x16x32_bf16 v[14:17], v[86:89], v[216:219], v[14:17]
	v_mfma_f32_16x16x32_bf16 v[18:21], v[78:81], v[224:227], v[18:21]
	v_mfma_f32_16x16x32_bf16 v[10:13], v[86:89], v[224:227], v[10:13]
	v_mfma_f32_16x16x32_bf16 v[62:65], v[90:93], v[162:165], 0
	v_mfma_f32_16x16x32_bf16 v[58:61], v[98:101], v[162:165], 0
	v_mfma_f32_16x16x32_bf16 v[46:49], v[90:93], v[204:207], 0
	v_mfma_f32_16x16x32_bf16 v[42:45], v[98:101], v[204:207], 0
	v_mfma_f32_16x16x32_bf16 v[30:33], v[90:93], v[212:215], 0
	v_mfma_f32_16x16x32_bf16 v[26:29], v[98:101], v[212:215], 0
	v_mfma_f32_16x16x32_bf16 v[6:9], v[90:93], v[220:223], 0
	v_mfma_f32_16x16x32_bf16 v[2:5], v[98:101], v[220:223], 0
	v_mfma_f32_16x16x32_bf16 v[62:65], v[94:97], v[166:169], v[62:65]
	v_mfma_f32_16x16x32_bf16 v[58:61], v[106:109], v[166:169], v[58:61]
	v_mfma_f32_16x16x32_bf16 v[46:49], v[94:97], v[208:211], v[46:49]
	v_mfma_f32_16x16x32_bf16 v[42:45], v[106:109], v[208:211], v[42:45]
	v_mfma_f32_16x16x32_bf16 v[30:33], v[94:97], v[216:219], v[30:33]
	v_mfma_f32_16x16x32_bf16 v[26:29], v[106:109], v[216:219], v[26:29]
	v_mfma_f32_16x16x32_bf16 v[6:9], v[94:97], v[224:227], v[6:9]
	v_mfma_f32_16x16x32_bf16 v[2:5], v[106:109], v[224:227], v[2:5]
	s_barrier
	s_setprio 0
	s_branch .Lpeel_mid_1737
.LBB0_1737:
	ds_read_b128 v[74:77], v196
	ds_read_b128 v[78:81], v196 offset:1024
	ds_read_b128 v[82:85], v196 offset:2048
	ds_read_b128 v[86:89], v196 offset:3072
	ds_read_b128 v[90:93], v197
	ds_read_b128 v[94:97], v197 offset:1024
	ds_read_b128 v[98:101], v197 offset:2048
	ds_read_b128 v[106:109], v197 offset:3072
	s_add_u32 s60, s10, 0xfffc0080
	s_addc_u32 s61, s11, -1
	s_cmp_eq_u32 s79, 12
	s_cselect_b32 s63, s53, s61
	s_cselect_b32 s62, s75, s60
	s_cselect_b32 s61, s51, s78
	s_cselect_b32 s60, s76, s77
	v_lshl_add_u64 v[170:171], s[10:11], 0, v[184:185]
	s_add_i32 m0, s36, 0xc000
	ds_read_b128 v[162:165], v198
	ds_read_b128 v[166:169], v198 offset:1024
	ds_read_b128 v[204:207], v198 offset:2048
	ds_read_b128 v[208:211], v198 offset:3072
	ds_read_b128 v[212:215], v198 offset:4096
	ds_read_b128 v[216:219], v198 offset:5120
	ds_read_b128 v[220:223], v198 offset:6144
	ds_read_b128 v[224:227], v198 offset:7168
	global_load_lds_dwordx4 v[170:171], off
	v_lshl_add_u64 v[170:171], s[10:11], 0, v[186:187]
	s_add_i32 m0, s36, 0xe000
	s_nop 0
	global_load_lds_dwordx4 v[170:171], off
	s_waitcnt vmcnt(8)
	s_waitcnt lgkmcnt(0)
	s_setprio 3
	s_barrier
	v_mfma_f32_16x16x32_bf16 v[150:153], v[74:77], v[162:165], v[150:153]
	v_mfma_f32_16x16x32_bf16 v[146:149], v[82:85], v[162:165], v[146:149]
	v_mfma_f32_16x16x32_bf16 v[134:137], v[74:77], v[204:207], v[134:137]
	v_mfma_f32_16x16x32_bf16 v[130:133], v[82:85], v[204:207], v[130:133]
	v_mfma_f32_16x16x32_bf16 v[118:121], v[74:77], v[212:215], v[118:121]
	v_mfma_f32_16x16x32_bf16 v[110:113], v[82:85], v[212:215], v[110:113]
	v_mfma_f32_16x16x32_bf16 v[114:117], v[74:77], v[220:223], v[114:117]
	v_mfma_f32_16x16x32_bf16 v[102:105], v[82:85], v[220:223], v[102:105]
	v_mfma_f32_16x16x32_bf16 v[150:153], v[78:81], v[166:169], v[150:153]
	v_mfma_f32_16x16x32_bf16 v[146:149], v[86:89], v[166:169], v[146:149]
	v_mfma_f32_16x16x32_bf16 v[134:137], v[78:81], v[208:211], v[134:137]
	v_mfma_f32_16x16x32_bf16 v[130:133], v[86:89], v[208:211], v[130:133]
	v_mfma_f32_16x16x32_bf16 v[118:121], v[78:81], v[216:219], v[118:121]
	v_mfma_f32_16x16x32_bf16 v[110:113], v[86:89], v[216:219], v[110:113]
	v_mfma_f32_16x16x32_bf16 v[114:117], v[78:81], v[224:227], v[114:117]
	v_mfma_f32_16x16x32_bf16 v[102:105], v[86:89], v[224:227], v[102:105]
	v_mfma_f32_16x16x32_bf16 v[158:161], v[90:93], v[162:165], v[158:161]
	v_mfma_f32_16x16x32_bf16 v[154:157], v[98:101], v[162:165], v[154:157]
	v_mfma_f32_16x16x32_bf16 v[142:145], v[90:93], v[204:207], v[142:145]
	v_mfma_f32_16x16x32_bf16 v[138:141], v[98:101], v[204:207], v[138:141]
	v_mfma_f32_16x16x32_bf16 v[126:129], v[90:93], v[212:215], v[126:129]
	v_mfma_f32_16x16x32_bf16 v[122:125], v[98:101], v[212:215], v[122:125]
	v_mfma_f32_16x16x32_bf16 v[70:73], v[90:93], v[220:223], v[70:73]
	v_mfma_f32_16x16x32_bf16 v[66:69], v[98:101], v[220:223], v[66:69]
	v_mfma_f32_16x16x32_bf16 v[158:161], v[94:97], v[166:169], v[158:161]
	v_mfma_f32_16x16x32_bf16 v[154:157], v[106:109], v[166:169], v[154:157]
	v_mfma_f32_16x16x32_bf16 v[142:145], v[94:97], v[208:211], v[142:145]
	v_mfma_f32_16x16x32_bf16 v[138:141], v[106:109], v[208:211], v[138:141]
	v_mfma_f32_16x16x32_bf16 v[126:129], v[94:97], v[216:219], v[126:129]
	v_mfma_f32_16x16x32_bf16 v[122:125], v[106:109], v[216:219], v[122:125]
	v_mfma_f32_16x16x32_bf16 v[70:73], v[94:97], v[224:227], v[70:73]
	v_mfma_f32_16x16x32_bf16 v[66:69], v[106:109], v[224:227], v[66:69]
	s_barrier
; #define PG8_STAGE(bufoff, gbase, voff) do { _Pragma("unroll") for (int _i = 0; _i < 2; ++_i) \
;         __builtin_amdgcn_global_load_lds((const unsigned*)((const char*)(gbase) + (voff)[_i]), (PG8_LAS unsigned*)(lds + (bufoff) + ldsw + _i * 8192), 16, 0, 0); } while (0)
; #define PG8_LDA(dst, b, h) do { _Pragma("unroll") for (int m = 0; m < 4; ++m) _Pragma("unroll") for (int k = 0; k < 2; ++k) dst[m][k] = *(const PG8_LAS bf16x8*)(lds + PG8_SA(b, h) + aoff + m * 2048 + k * 1024); } while (0)
; #define PG8_LDB(dst, b, h) do { _Pragma("unroll") for (int n = 0; n < 2; ++n) _Pragma("unroll") for (int k = 0; k < 2; ++k) dst[n][k] = *(const PG8_LAS bf16x8*)(lds + PG8_SB(b, h) + boff + n * 2048 + k * 1024); } while (0)
; #define PG8_MMA(ai, bj, At, Bt) do { __builtin_amdgcn_s_setprio(1); _Pragma("unroll") for (int m = 0; m < 4; ++m) _Pragma("unroll") for (int n = 0; n < 2; ++n) _Pragma("unroll") for (int k = 0; k < 2; ++k) \
;         acc[ai][bj][m][n] = __builtin_amdgcn_mfma_f32_16x16x32_bf16(Bt[n][k], At[m][k], acc[ai][bj][m][n], 0, 0, 0); __builtin_amdgcn_s_setprio(0); } while (0)
; template <class Epi, class Sched, bool ALIGN_EPI = false, bool SP2 = false, bool PAIR_ACC = false>
; __device__ __forceinline__ void gemm_phase(PG8_LAS unsigned char* lds, const Gemm g, const Sched& S, const Epi& E) {
;     ...
;             if constexpr (SP2) {
;             PG8_LDB(B0, 0, 0); PG8_LDB(B1, 0, 1); PG8_SCHED; PG8_LDA(At, 0, 0); PG8_STAGE(PG8_SA(1, 1), a1 + hstep, voffA);
;             PG8_WAIT_V(8); PG8_WAIT_L(0); PG8_BAR; PG8_MMA(0, 0, At, B0); PG8_MMA(0, 1, At, B1); PG8_BAR; PG8_SCHED;
;             PG8_LDA(At, 0, 1); PG8_STAGE(PG8_SB(0, 0), b2, voffB); PG8_STAGE(PG8_SB(0, 1), b2 + hstep, voffB); PG8_STAGE(PG8_SA(0, 0), a2, voffA);
;             PG8_WAIT_V(8); PG8_WAIT_L(0); PG8_BAR; PG8_MMA(1, 0, At, B0); PG8_MMA(1, 1, At, B1); PG8_BAR; PG8_SCHED;
;             PG8_LDB(B0, 1, 0); PG8_LDB(B1, 1, 1); PG8_SCHED; PG8_LDA(At, 1, 0); PG8_STAGE(PG8_SA(0, 1), a2 + hstep, voffA);
;             PG8_WAIT_V(8); PG8_WAIT_L(0); PG8_BAR; PG8_MMA(0, 0, At, B0); PG8_MMA(0, 1, At, B1); PG8_BAR; PG8_SCHED;
;             PG8_LDA(At, 1, 1); PG8_STAGE(PG8_SB(1, 0), b3, voffB); PG8_STAGE(PG8_SB(1, 1), b3 + hstep, voffB); PG8_STAGE(PG8_SA(1, 0), a3, voffA);
;             PG8_WAIT_V(8); PG8_WAIT_L(0); PG8_BAR; PG8_MMA(1, 0, At, B0); PG8_MMA(1, 1, At, B1); PG8_BAR; PG8_SCHED;
	s_setprio 0
	s_add_i32 s80, s70, s34
	v_lshl_add_u64 v[170:171], s[60:61], 0, v[176:177]
	s_mov_b32 m0, s80
	ds_read_b128 v[162:165], v198 offset:16384
	ds_read_b128 v[166:169], v198 offset:17408
	ds_read_b128 v[204:207], v198 offset:18432
	ds_read_b128 v[208:211], v198 offset:19456
	ds_read_b128 v[212:215], v198 offset:20480
	ds_read_b128 v[216:219], v198 offset:21504
	ds_read_b128 v[220:223], v198 offset:22528
	ds_read_b128 v[224:227], v198 offset:23552
	global_load_lds_dwordx4 v[170:171], off
	s_add_i32 m0, s80, 0x2000
	s_add_u32 s80, s60, 0x40000
	v_lshl_add_u64 v[192:193], s[60:61], 0, v[172:173]
	s_addc_u32 s81, s61, 0
	s_add_i32 s82, s71, s34
	global_load_lds_dwordx4 v[192:193], off
	v_lshl_add_u64 v[228:229], s[80:81], 0, v[176:177]
	s_mov_b32 m0, s82
	v_lshl_add_u64 v[230:231], s[62:63], 0, v[174:175]
	global_load_lds_dwordx4 v[228:229], off
	v_lshl_add_u64 v[228:229], s[80:81], 0, v[172:173]
	s_add_i32 m0, s82, 0x2000
	s_nop 0
	global_load_lds_dwordx4 v[228:229], off
	v_lshl_add_u64 v[228:229], s[62:63], 0, v[178:179]
	s_mov_b32 m0, s36
	s_nop 0
	global_load_lds_dwordx4 v[228:229], off
	s_mov_b32 m0, s37
	s_nop 0
	global_load_lds_dwordx4 v[230:231], off
	s_waitcnt vmcnt(8)
	s_waitcnt lgkmcnt(0)
	s_setprio 3
	s_barrier
	v_mfma_f32_16x16x32_bf16 v[54:57], v[74:77], v[162:165], v[54:57]
	v_mfma_f32_16x16x32_bf16 v[50:53], v[82:85], v[162:165], v[50:53]
	v_mfma_f32_16x16x32_bf16 v[38:41], v[74:77], v[204:207], v[38:41]
	v_mfma_f32_16x16x32_bf16 v[34:37], v[82:85], v[204:207], v[34:37]
	v_mfma_f32_16x16x32_bf16 v[22:25], v[74:77], v[212:215], v[22:25]
	v_mfma_f32_16x16x32_bf16 v[14:17], v[82:85], v[212:215], v[14:17]
	v_mfma_f32_16x16x32_bf16 v[18:21], v[74:77], v[220:223], v[18:21]
	v_mfma_f32_16x16x32_bf16 v[10:13], v[82:85], v[220:223], v[10:13]
	v_mfma_f32_16x16x32_bf16 v[54:57], v[78:81], v[166:169], v[54:57]
	v_mfma_f32_16x16x32_bf16 v[50:53], v[86:89], v[166:169], v[50:53]
	v_mfma_f32_16x16x32_bf16 v[38:41], v[78:81], v[208:211], v[38:41]
	v_mfma_f32_16x16x32_bf16 v[34:37], v[86:89], v[208:211], v[34:37]
	v_mfma_f32_16x16x32_bf16 v[22:25], v[78:81], v[216:219], v[22:25]
	v_mfma_f32_16x16x32_bf16 v[14:17], v[86:89], v[216:219], v[14:17]
	v_mfma_f32_16x16x32_bf16 v[18:21], v[78:81], v[224:227], v[18:21]
	v_mfma_f32_16x16x32_bf16 v[10:13], v[86:89], v[224:227], v[10:13]
	v_mfma_f32_16x16x32_bf16 v[62:65], v[90:93], v[162:165], v[62:65]
	v_mfma_f32_16x16x32_bf16 v[58:61], v[98:101], v[162:165], v[58:61]
	v_mfma_f32_16x16x32_bf16 v[46:49], v[90:93], v[204:207], v[46:49]
	v_mfma_f32_16x16x32_bf16 v[42:45], v[98:101], v[204:207], v[42:45]
	v_mfma_f32_16x16x32_bf16 v[30:33], v[90:93], v[212:215], v[30:33]
	v_mfma_f32_16x16x32_bf16 v[26:29], v[98:101], v[212:215], v[26:29]
	v_mfma_f32_16x16x32_bf16 v[6:9], v[90:93], v[220:223], v[6:9]
	v_mfma_f32_16x16x32_bf16 v[2:5], v[98:101], v[220:223], v[2:5]
	v_mfma_f32_16x16x32_bf16 v[62:65], v[94:97], v[166:169], v[62:65]
	v_mfma_f32_16x16x32_bf16 v[58:61], v[106:109], v[166:169], v[58:61]
	v_mfma_f32_16x16x32_bf16 v[46:49], v[94:97], v[208:211], v[46:49]
	v_mfma_f32_16x16x32_bf16 v[42:45], v[106:109], v[208:211], v[42:45]
	v_mfma_f32_16x16x32_bf16 v[30:33], v[94:97], v[216:219], v[30:33]
	v_mfma_f32_16x16x32_bf16 v[26:29], v[106:109], v[216:219], v[26:29]
	v_mfma_f32_16x16x32_bf16 v[6:9], v[94:97], v[224:227], v[6:9]
	v_mfma_f32_16x16x32_bf16 v[2:5], v[106:109], v[224:227], v[2:5]
	s_barrier
	s_setprio 0
.Lpeel_mid_1737:
	s_add_i32 s80, 0, 0x18000
	s_add_i32 s81, 0, 0x1c000
	v_add_u32_e32 v86, s80, v194
	v_add_u32_e32 v106, s81, v194
	ds_read_b128 v[74:77], v86
	ds_read_b128 v[78:81], v86 offset:1024
	ds_read_b128 v[82:85], v86 offset:2048
	ds_read_b128 v[86:89], v86 offset:3072
	ds_read_b128 v[90:93], v106
	ds_read_b128 v[94:97], v106 offset:1024
	ds_read_b128 v[98:101], v106 offset:2048
	ds_read_b128 v[106:109], v106 offset:3072
	s_add_u32 s62, s62, 0x40000
	s_addc_u32 s63, s63, 0
	s_mov_b32 m0, s49
	v_lshl_add_u64 v[232:233], s[62:63], 0, v[178:179]
	ds_read_b128 v[162:165], v198 offset:32768
	ds_read_b128 v[166:169], v198 offset:33792
	ds_read_b128 v[204:207], v198 offset:34816
	ds_read_b128 v[208:211], v198 offset:35840
	ds_read_b128 v[212:215], v198 offset:36864
	ds_read_b128 v[216:219], v198 offset:37888
	ds_read_b128 v[220:223], v198 offset:38912
	ds_read_b128 v[224:227], v198 offset:39936
	global_load_lds_dwordx4 v[232:233], off
	v_lshl_add_u64 v[232:233], s[62:63], 0, v[174:175]
	s_mov_b32 m0, s64
	s_nop 0
	global_load_lds_dwordx4 v[232:233], off
	s_waitcnt vmcnt(8)
	s_waitcnt lgkmcnt(0)
	s_setprio 3
	s_barrier
; #define PG8_STAGE(bufoff, gbase, voff) do { _Pragma("unroll") for (int _i = 0; _i < 2; ++_i) \
;         __builtin_amdgcn_global_load_lds((const unsigned*)((const char*)(gbase) + (voff)[_i]), (PG8_LAS unsigned*)(lds + (bufoff) + ldsw + _i * 8192), 16, 0, 0); } while (0)
; #define PG8_LDA(dst, b, h) do { _Pragma("unroll") for (int m = 0; m < 4; ++m) _Pragma("unroll") for (int k = 0; k < 2; ++k) dst[m][k] = *(const PG8_LAS bf16x8*)(lds + PG8_SA(b, h) + aoff + m * 2048 + k * 1024); } while (0)
; #define PG8_LDB(dst, b, h) do { _Pragma("unroll") for (int n = 0; n < 2; ++n) _Pragma("unroll") for (int k = 0; k < 2; ++k) dst[n][k] = *(const PG8_LAS bf16x8*)(lds + PG8_SB(b, h) + boff + n * 2048 + k * 1024); } while (0)
; #define PG8_MMA(ai, bj, At, Bt) do { __builtin_amdgcn_s_setprio(1); _Pragma("unroll") for (int m = 0; m < 4; ++m) _Pragma("unroll") for (int n = 0; n < 2; ++n) _Pragma("unroll") for (int k = 0; k < 2; ++k) \
;         acc[ai][bj][m][n] = __builtin_amdgcn_mfma_f32_16x16x32_bf16(Bt[n][k], At[m][k], acc[ai][bj][m][n], 0, 0, 0); __builtin_amdgcn_s_setprio(0); } while (0)
; template <class Epi, class Sched, bool ALIGN_EPI = false, bool SP2 = false, bool PAIR_ACC = false>
; __device__ __forceinline__ void gemm_phase(PG8_LAS unsigned char* lds, const Gemm g, const Sched& S, const Epi& E) {
;     ...
;             if constexpr (SP2) {
;             PG8_LDB(B0, 0, 0); PG8_LDB(B1, 0, 1); PG8_SCHED; PG8_LDA(At, 0, 0); PG8_STAGE(PG8_SA(1, 1), a1 + hstep, voffA);
;             PG8_WAIT_V(8); PG8_WAIT_L(0); PG8_BAR; PG8_MMA(0, 0, At, B0); PG8_MMA(0, 1, At, B1); PG8_BAR; PG8_SCHED;
;             PG8_LDA(At, 0, 1); PG8_STAGE(PG8_SB(0, 0), b2, voffB); PG8_STAGE(PG8_SB(0, 1), b2 + hstep, voffB); PG8_STAGE(PG8_SA(0, 0), a2, voffA);
;             PG8_WAIT_V(8); PG8_WAIT_L(0); PG8_BAR; PG8_MMA(1, 0, At, B0); PG8_MMA(1, 1, At, B1); PG8_BAR; PG8_SCHED;
;             PG8_LDB(B0, 1, 0); PG8_LDB(B1, 1, 1); PG8_SCHED; PG8_LDA(At, 1, 0); PG8_STAGE(PG8_SA(0, 1), a2 + hstep, voffA);
;             PG8_WAIT_V(8); PG8_WAIT_L(0); PG8_BAR; PG8_MMA(0, 0, At, B0); PG8_MMA(0, 1, At, B1); PG8_BAR; PG8_SCHED;
;             PG8_LDA(At, 1, 1); PG8_STAGE(PG8_SB(1, 0), b3, voffB); PG8_STAGE(PG8_SB(1, 1), b3 + hstep, voffB); PG8_STAGE(PG8_SA(1, 0), a3, voffA);
;             PG8_WAIT_V(8); PG8_WAIT_L(0); PG8_BAR; PG8_MMA(1, 0, At, B0); PG8_MMA(1, 1, At, B1); PG8_BAR; PG8_SCHED;
	v_mfma_f32_16x16x32_bf16 v[150:153], v[74:77], v[162:165], v[150:153]
	v_mfma_f32_16x16x32_bf16 v[146:149], v[82:85], v[162:165], v[146:149]
	v_mfma_f32_16x16x32_bf16 v[134:137], v[74:77], v[204:207], v[134:137]
	v_mfma_f32_16x16x32_bf16 v[130:133], v[82:85], v[204:207], v[130:133]
	v_mfma_f32_16x16x32_bf16 v[118:121], v[74:77], v[212:215], v[118:121]
	v_mfma_f32_16x16x32_bf16 v[110:113], v[82:85], v[212:215], v[110:113]
	v_mfma_f32_16x16x32_bf16 v[114:117], v[74:77], v[220:223], v[114:117]
	v_mfma_f32_16x16x32_bf16 v[102:105], v[82:85], v[220:223], v[102:105]
	v_mfma_f32_16x16x32_bf16 v[150:153], v[78:81], v[166:169], v[150:153]
	v_mfma_f32_16x16x32_bf16 v[146:149], v[86:89], v[166:169], v[146:149]
	v_mfma_f32_16x16x32_bf16 v[134:137], v[78:81], v[208:211], v[134:137]
	v_mfma_f32_16x16x32_bf16 v[130:133], v[86:89], v[208:211], v[130:133]
	v_mfma_f32_16x16x32_bf16 v[118:121], v[78:81], v[216:219], v[118:121]
	v_mfma_f32_16x16x32_bf16 v[110:113], v[86:89], v[216:219], v[110:113]
	v_mfma_f32_16x16x32_bf16 v[114:117], v[78:81], v[224:227], v[114:117]
	v_mfma_f32_16x16x32_bf16 v[102:105], v[86:89], v[224:227], v[102:105]
	v_mfma_f32_16x16x32_bf16 v[158:161], v[90:93], v[162:165], v[158:161]
	v_mfma_f32_16x16x32_bf16 v[154:157], v[98:101], v[162:165], v[154:157]
	v_mfma_f32_16x16x32_bf16 v[142:145], v[90:93], v[204:207], v[142:145]
	v_mfma_f32_16x16x32_bf16 v[138:141], v[98:101], v[204:207], v[138:141]
	v_mfma_f32_16x16x32_bf16 v[126:129], v[90:93], v[212:215], v[126:129]
	v_mfma_f32_16x16x32_bf16 v[122:125], v[98:101], v[212:215], v[122:125]
	v_mfma_f32_16x16x32_bf16 v[70:73], v[90:93], v[220:223], v[70:73]
	v_mfma_f32_16x16x32_bf16 v[66:69], v[98:101], v[220:223], v[66:69]
	v_mfma_f32_16x16x32_bf16 v[158:161], v[94:97], v[166:169], v[158:161]
	v_mfma_f32_16x16x32_bf16 v[154:157], v[106:109], v[166:169], v[154:157]
	v_mfma_f32_16x16x32_bf16 v[142:145], v[94:97], v[208:211], v[142:145]
	v_mfma_f32_16x16x32_bf16 v[138:141], v[106:109], v[208:211], v[138:141]
	v_mfma_f32_16x16x32_bf16 v[126:129], v[94:97], v[216:219], v[126:129]
	v_mfma_f32_16x16x32_bf16 v[122:125], v[106:109], v[216:219], v[122:125]
	v_mfma_f32_16x16x32_bf16 v[70:73], v[94:97], v[224:227], v[70:73]
	v_mfma_f32_16x16x32_bf16 v[66:69], v[106:109], v[224:227], v[66:69]
	s_barrier
	s_setprio 0
	s_add_i32 s62, s80, s34
	v_lshl_add_u64 v[170:171], v[170:171], 0, s[30:31]
	s_mov_b32 m0, s62
	ds_read_b128 v[162:165], v198 offset:49152
	ds_read_b128 v[166:169], v198 offset:50176
	ds_read_b128 v[204:207], v198 offset:51200
	ds_read_b128 v[208:211], v198 offset:52224
	ds_read_b128 v[212:215], v198 offset:53248
	ds_read_b128 v[216:219], v198 offset:54272
	ds_read_b128 v[220:223], v198 offset:55296
	ds_read_b128 v[224:227], v198 offset:56320
	global_load_lds_dwordx4 v[170:171], off
	s_add_i32 m0, s62, 0x2000
	s_add_u32 s60, s60, 0x40080
	v_lshl_add_u64 v[170:171], v[192:193], 0, s[30:31]
	s_addc_u32 s61, s61, 0
	s_add_i32 s62, s81, s34
	global_load_lds_dwordx4 v[170:171], off
	v_lshl_add_u64 v[170:171], s[60:61], 0, v[176:177]
	s_mov_b32 m0, s62
	s_nop 0
	global_load_lds_dwordx4 v[170:171], off
	v_lshl_add_u64 v[170:171], s[60:61], 0, v[172:173]
	s_add_i32 m0, s62, 0x2000
	s_nop 0
	global_load_lds_dwordx4 v[170:171], off
	v_lshl_add_u64 v[170:171], v[228:229], 0, s[30:31]
	s_mov_b32 m0, s68
	s_nop 0
	global_load_lds_dwordx4 v[170:171], off
	v_lshl_add_u64 v[170:171], v[230:231], 0, s[30:31]
	s_mov_b32 m0, s69
	s_nop 0
	global_load_lds_dwordx4 v[170:171], off
	s_waitcnt vmcnt(8)
	s_waitcnt lgkmcnt(0)
	s_setprio 3
	s_barrier
	v_mfma_f32_16x16x32_bf16 v[54:57], v[74:77], v[162:165], v[54:57]
	v_mfma_f32_16x16x32_bf16 v[50:53], v[82:85], v[162:165], v[50:53]
	v_mfma_f32_16x16x32_bf16 v[38:41], v[74:77], v[204:207], v[38:41]
	v_mfma_f32_16x16x32_bf16 v[34:37], v[82:85], v[204:207], v[34:37]
	v_mfma_f32_16x16x32_bf16 v[22:25], v[74:77], v[212:215], v[22:25]
	v_mfma_f32_16x16x32_bf16 v[14:17], v[82:85], v[212:215], v[14:17]
	v_mfma_f32_16x16x32_bf16 v[18:21], v[74:77], v[220:223], v[18:21]
	v_mfma_f32_16x16x32_bf16 v[10:13], v[82:85], v[220:223], v[10:13]
	v_mfma_f32_16x16x32_bf16 v[54:57], v[78:81], v[166:169], v[54:57]
	v_mfma_f32_16x16x32_bf16 v[50:53], v[86:89], v[166:169], v[50:53]
	v_mfma_f32_16x16x32_bf16 v[38:41], v[78:81], v[208:211], v[38:41]
	v_mfma_f32_16x16x32_bf16 v[34:37], v[86:89], v[208:211], v[34:37]
	v_mfma_f32_16x16x32_bf16 v[22:25], v[78:81], v[216:219], v[22:25]
	v_mfma_f32_16x16x32_bf16 v[14:17], v[86:89], v[216:219], v[14:17]
	v_mfma_f32_16x16x32_bf16 v[18:21], v[78:81], v[224:227], v[18:21]
	v_mfma_f32_16x16x32_bf16 v[10:13], v[86:89], v[224:227], v[10:13]
	v_mfma_f32_16x16x32_bf16 v[62:65], v[90:93], v[162:165], v[62:65]
	v_mfma_f32_16x16x32_bf16 v[58:61], v[98:101], v[162:165], v[58:61]
	v_mfma_f32_16x16x32_bf16 v[46:49], v[90:93], v[204:207], v[46:49]
	v_mfma_f32_16x16x32_bf16 v[42:45], v[98:101], v[204:207], v[42:45]
	v_mfma_f32_16x16x32_bf16 v[30:33], v[90:93], v[212:215], v[30:33]
	v_mfma_f32_16x16x32_bf16 v[26:29], v[98:101], v[212:215], v[26:29]
	v_mfma_f32_16x16x32_bf16 v[6:9], v[90:93], v[220:223], v[6:9]
	v_mfma_f32_16x16x32_bf16 v[2:5], v[98:101], v[220:223], v[2:5]
	v_mfma_f32_16x16x32_bf16 v[62:65], v[94:97], v[166:169], v[62:65]
	v_mfma_f32_16x16x32_bf16 v[58:61], v[106:109], v[166:169], v[58:61]
	v_mfma_f32_16x16x32_bf16 v[46:49], v[94:97], v[208:211], v[46:49]
	v_mfma_f32_16x16x32_bf16 v[42:45], v[106:109], v[208:211], v[42:45]
	v_mfma_f32_16x16x32_bf16 v[30:33], v[94:97], v[216:219], v[30:33]
	v_mfma_f32_16x16x32_bf16 v[26:29], v[106:109], v[216:219], v[26:29]
	v_mfma_f32_16x16x32_bf16 v[6:9], v[94:97], v[224:227], v[6:9]
	v_mfma_f32_16x16x32_bf16 v[2:5], v[106:109], v[224:227], v[2:5]
	s_barrier
	s_setprio 0
	s_add_i32 s79, s79, 2
	s_add_u32 s10, s10, 0x100
	s_addc_u32 s11, s11, 0
	s_add_u32 s77, s77, 0x100
	s_addc_u32 s78, s78, 0
	s_cmp_gt_u32 s79, 13
	s_cbranch_scc0 .LBB0_1737
	s_and_b64 vcc, exec, s[38:39]
	s_cbranch_vccz .LBB0_1740
	s_barrier

; #define PG8_STAGE(bufoff, gbase, voff) do { _Pragma("unroll") for (int _i = 0; _i < 2; ++_i) \
;         __builtin_amdgcn_global_load_lds((const unsigned*)((const char*)(gbase) + (voff)[_i]), (PG8_LAS unsigned*)(lds + (bufoff) + ldsw + _i * 8192), 16, 0, 0); } while (0)
; #define PG8_LDA(dst, b, h) do { _Pragma("unroll") for (int m = 0; m < 4; ++m) _Pragma("unroll") for (int k = 0; k < 2; ++k) dst[m][k] = *(const PG8_LAS bf16x8*)(lds + PG8_SA(b, h) + aoff + m * 2048 + k * 1024); } while (0)
; #define PG8_WAIT_V(n) asm volatile("s_waitcnt vmcnt(" #n ")" ::: "memory")
; #define PG8_WAIT_L(n) asm volatile("s_waitcnt lgkmcnt(" #n ")" ::: "memory")
; #define PG8_BAR __builtin_amdgcn_s_barrier()
; template <class Epi, class Sched, bool ALIGN_EPI = false, bool SP2 = false, bool PAIR_ACC = false>
; __device__ __forceinline__ void gemm_phase(PG8_LAS unsigned char* lds, const Gemm g, const Sched& S, const Epi& E) {
;     ...
;         for (int t = 0; t < nt; t += 2) {
;             const bool last = (t == nt - 2);
;             const char* a1 = cA + (size_t)(t + 1) * kstep;
;             const char* a2 = last ? nA : cA + (size_t)(t + 2) * kstep; const char* b2 = last ? nB : cB + (size_t)(t + 2) * kstep;
;             const char* a3 = a2 + kstep; const char* b3 = b2 + kstep;
;             if (last && has_next) S.a_ready(nxt);
;             if constexpr (SP2) {
;             PG8_LDB(B0, 0, 0); PG8_LDB(B1, 0, 1); PG8_SCHED; PG8_LDA(At, 0, 0); PG8_STAGE(PG8_SA(1, 1), a1 + hstep, voffA);
;             PG8_WAIT_V(8); PG8_WAIT_L(0); PG8_BAR; PG8_MMA(0, 0, At, B0); PG8_MMA(0, 1, At, B1); PG8_BAR; PG8_SCHED;
;             PG8_LDA(At, 0, 1); PG8_STAGE(PG8_SB(0, 0), b2, voffB); PG8_STAGE(PG8_SB(0, 1), b2 + hstep, voffB); PG8_STAGE(PG8_SA(0, 0), a2, voffA);
;             PG8_WAIT_V(8); PG8_WAIT_L(0); PG8_BAR; PG8_MMA(1, 0, At, B0); PG8_MMA(1, 1, At, B1); PG8_BAR; PG8_SCHED;
;             PG8_LDB(B0, 1, 0); PG8_LDB(B1, 1, 1); PG8_SCHED; PG8_LDA(At, 1, 0); PG8_STAGE(PG8_SA(0, 1), a2 + hstep, voffA);
;             PG8_WAIT_V(8); PG8_WAIT_L(0); PG8_BAR; PG8_MMA(0, 0, At, B0); PG8_MMA(0, 1, At, B1); PG8_BAR; PG8_SCHED;
;             PG8_LDA(At, 1, 1); PG8_STAGE(PG8_SB(1, 0), b3, voffB); PG8_STAGE(PG8_SB(1, 1), b3 + hstep, voffB); PG8_STAGE(PG8_SA(1, 0), a3, voffA);
;             PG8_WAIT_V(8); PG8_WAIT_L(0); PG8_BAR; PG8_MMA(1, 0, At, B0); PG8_MMA(1, 1, At, B1); PG8_BAR; PG8_SCHED;
.LBB0_1840:
	v_add_u32_e32 v164, s45, v150
	ds_read_b128 v[152:155], v164
	ds_read_b128 v[156:159], v164 offset:1024
	ds_read_b128 v[160:163], v164 offset:2048
	ds_read_b128 v[168:171], v164 offset:3072
	v_add_u32_e32 v164, s46, v150
	s_add_u32 s26, s18, s24
	ds_read_b128 v[172:175], v164
	ds_read_b128 v[176:179], v164 offset:1024
	ds_read_b128 v[180:183], v164 offset:2048
	ds_read_b128 v[184:187], v164 offset:3072
	s_addc_u32 s27, s19, s25
	s_add_u32 s26, s26, 0x100
	s_addc_u32 s27, s27, 0
	s_add_u32 s53, s50, s24
	s_addc_u32 s54, s51, s25
	s_cmpk_eq_i32 s24, 0x1500
	s_cselect_b32 s29, s23, s27
	s_cselect_b32 s28, s22, s26
	s_cselect_b32 s27, s5, s54
	s_cselect_b32 s26, s4, s53
	v_lshl_add_u64 v[164:165], v[146:147], 0, s[24:25]
	s_add_i32 m0, s38, 0xc000
	ds_read_b128 v[188:191], v151
	ds_read_b128 v[192:195], v151 offset:1024
	ds_read_b128 v[196:199], v151 offset:2048
	ds_read_b128 v[200:203], v151 offset:3072
	ds_read_b128 v[204:207], v151 offset:4096
	ds_read_b128 v[208:211], v151 offset:5120
	ds_read_b128 v[212:215], v151 offset:6144
	ds_read_b128 v[216:219], v151 offset:7168
	global_load_lds_dwordx4 v[164:165], off
	v_lshl_add_u64 v[164:165], v[148:149], 0, s[24:25]
	s_add_i32 m0, s38, 0xe000
	s_nop 0
	global_load_lds_dwordx4 v[164:165], off
	s_waitcnt vmcnt(8)
	s_waitcnt lgkmcnt(0)
	s_setprio 3
	s_barrier
	v_mfma_f32_16x16x32_bf16 v[102:105], v[152:155], v[188:191], v[102:105]
	v_mfma_f32_16x16x32_bf16 v[106:109], v[160:163], v[188:191], v[106:109]
	v_mfma_f32_16x16x32_bf16 v[114:117], v[152:155], v[196:199], v[114:117]
	v_mfma_f32_16x16x32_bf16 v[118:121], v[160:163], v[196:199], v[118:121]
	v_mfma_f32_16x16x32_bf16 v[126:129], v[152:155], v[204:207], v[126:129]
	v_mfma_f32_16x16x32_bf16 v[122:125], v[160:163], v[204:207], v[122:125]
	v_mfma_f32_16x16x32_bf16 v[78:81], v[152:155], v[212:215], v[78:81]
	v_mfma_f32_16x16x32_bf16 v[74:77], v[160:163], v[212:215], v[74:77]
	v_mfma_f32_16x16x32_bf16 v[102:105], v[156:159], v[192:195], v[102:105]
	v_mfma_f32_16x16x32_bf16 v[106:109], v[168:171], v[192:195], v[106:109]
	v_mfma_f32_16x16x32_bf16 v[114:117], v[156:159], v[200:203], v[114:117]
	v_mfma_f32_16x16x32_bf16 v[118:121], v[168:171], v[200:203], v[118:121]
	v_mfma_f32_16x16x32_bf16 v[126:129], v[156:159], v[208:211], v[126:129]
	v_mfma_f32_16x16x32_bf16 v[122:125], v[168:171], v[208:211], v[122:125]
	v_mfma_f32_16x16x32_bf16 v[78:81], v[156:159], v[216:219], v[78:81]
	v_mfma_f32_16x16x32_bf16 v[74:77], v[168:171], v[216:219], v[74:77]
	v_mfma_f32_16x16x32_bf16 v[86:89], v[172:175], v[188:191], v[86:89]
	v_mfma_f32_16x16x32_bf16 v[82:85], v[180:183], v[188:191], v[82:85]
	v_mfma_f32_16x16x32_bf16 v[94:97], v[172:175], v[196:199], v[94:97]
	v_mfma_f32_16x16x32_bf16 v[90:93], v[180:183], v[196:199], v[90:93]
	v_mfma_f32_16x16x32_bf16 v[110:113], v[172:175], v[204:207], v[110:113]
	v_mfma_f32_16x16x32_bf16 v[98:101], v[180:183], v[204:207], v[98:101]
	v_mfma_f32_16x16x32_bf16 v[70:73], v[172:175], v[212:215], v[70:73]
	v_mfma_f32_16x16x32_bf16 v[66:69], v[180:183], v[212:215], v[66:69]
	v_mfma_f32_16x16x32_bf16 v[86:89], v[176:179], v[192:195], v[86:89]
	v_mfma_f32_16x16x32_bf16 v[82:85], v[184:187], v[192:195], v[82:85]
	v_mfma_f32_16x16x32_bf16 v[94:97], v[176:179], v[200:203], v[94:97]
	v_mfma_f32_16x16x32_bf16 v[90:93], v[184:187], v[200:203], v[90:93]
	v_mfma_f32_16x16x32_bf16 v[110:113], v[176:179], v[208:211], v[110:113]
	v_mfma_f32_16x16x32_bf16 v[98:101], v[184:187], v[208:211], v[98:101]
	v_mfma_f32_16x16x32_bf16 v[70:73], v[176:179], v[216:219], v[70:73]
	v_mfma_f32_16x16x32_bf16 v[66:69], v[184:187], v[216:219], v[66:69]
	s_barrier
	s_setprio 0
	s_add_i32 s53, s45, s37
	v_lshl_add_u64 v[164:165], s[26:27], 0, v[132:133]
	s_mov_b32 m0, s53
	ds_read_b128 v[188:191], v151 offset:16384
	ds_read_b128 v[192:195], v151 offset:17408
	ds_read_b128 v[196:199], v151 offset:18432
	ds_read_b128 v[200:203], v151 offset:19456
	ds_read_b128 v[204:207], v151 offset:20480
	ds_read_b128 v[208:211], v151 offset:21504
	ds_read_b128 v[212:215], v151 offset:22528
	ds_read_b128 v[216:219], v151 offset:23552
	global_load_lds_dwordx4 v[164:165], off
	s_add_i32 m0, s53, 0x2000
	s_add_u32 s54, s26, 0xb0000
	v_lshl_add_u64 v[220:221], s[26:27], 0, v[136:137]
	s_addc_u32 s55, s27, 0
	s_add_i32 s53, s46, s37
	global_load_lds_dwordx4 v[220:221], off
	v_lshl_add_u64 v[222:223], s[54:55], 0, v[132:133]
	s_mov_b32 m0, s53
	v_lshl_add_u64 v[224:225], s[28:29], 0, v[134:135]
	global_load_lds_dwordx4 v[222:223], off
	v_lshl_add_u64 v[222:223], s[54:55], 0, v[136:137]
	s_add_i32 m0, s53, 0x2000
	s_nop 0
	global_load_lds_dwordx4 v[222:223], off
	v_lshl_add_u64 v[222:223], s[28:29], 0, v[130:131]
	s_mov_b32 m0, s38
	s_nop 0
	global_load_lds_dwordx4 v[222:223], off
	s_mov_b32 m0, s39
	s_nop 0
	global_load_lds_dwordx4 v[224:225], off
	s_waitcnt vmcnt(8)
	s_waitcnt lgkmcnt(0)
	s_setprio 3
	s_barrier
; #define PG8_STAGE(bufoff, gbase, voff) do { _Pragma("unroll") for (int _i = 0; _i < 2; ++_i) \
;         __builtin_amdgcn_global_load_lds((const unsigned*)((const char*)(gbase) + (voff)[_i]), (PG8_LAS unsigned*)(lds + (bufoff) + ldsw + _i * 8192), 16, 0, 0); } while (0)
; #define PG8_LDA(dst, b, h) do { _Pragma("unroll") for (int m = 0; m < 4; ++m) _Pragma("unroll") for (int k = 0; k < 2; ++k) dst[m][k] = *(const PG8_LAS bf16x8*)(lds + PG8_SA(b, h) + aoff + m * 2048 + k * 1024); } while (0)
; #define PG8_LDB(dst, b, h) do { _Pragma("unroll") for (int n = 0; n < 2; ++n) _Pragma("unroll") for (int k = 0; k < 2; ++k) dst[n][k] = *(const PG8_LAS bf16x8*)(lds + PG8_SB(b, h) + boff + n * 2048 + k * 1024); } while (0)
; #define PG8_MMA(ai, bj, At, Bt) do { __builtin_amdgcn_s_setprio(1); _Pragma("unroll") for (int m = 0; m < 4; ++m) _Pragma("unroll") for (int n = 0; n < 2; ++n) _Pragma("unroll") for (int k = 0; k < 2; ++k) \
;         acc[ai][bj][m][n] = __builtin_amdgcn_mfma_f32_16x16x32_bf16(Bt[n][k], At[m][k], acc[ai][bj][m][n], 0, 0, 0); __builtin_amdgcn_s_setprio(0); } while (0)
; template <class Epi, class Sched, bool ALIGN_EPI = false, bool SP2 = false, bool PAIR_ACC = false>
; __device__ __forceinline__ void gemm_phase(PG8_LAS unsigned char* lds, const Gemm g, const Sched& S, const Epi& E) {
;     ...
;             if constexpr (SP2) {
;             PG8_LDB(B0, 0, 0); PG8_LDB(B1, 0, 1); PG8_SCHED; PG8_LDA(At, 0, 0); PG8_STAGE(PG8_SA(1, 1), a1 + hstep, voffA);
;             PG8_WAIT_V(8); PG8_WAIT_L(0); PG8_BAR; PG8_MMA(0, 0, At, B0); PG8_MMA(0, 1, At, B1); PG8_BAR; PG8_SCHED;
;             PG8_LDA(At, 0, 1); PG8_STAGE(PG8_SB(0, 0), b2, voffB); PG8_STAGE(PG8_SB(0, 1), b2 + hstep, voffB); PG8_STAGE(PG8_SA(0, 0), a2, voffA);
;             PG8_WAIT_V(8); PG8_WAIT_L(0); PG8_BAR; PG8_MMA(1, 0, At, B0); PG8_MMA(1, 1, At, B1); PG8_BAR; PG8_SCHED;
;             PG8_LDB(B0, 1, 0); PG8_LDB(B1, 1, 1); PG8_SCHED; PG8_LDA(At, 1, 0); PG8_STAGE(PG8_SA(0, 1), a2 + hstep, voffA);
;             PG8_WAIT_V(8); PG8_WAIT_L(0); PG8_BAR; PG8_MMA(0, 0, At, B0); PG8_MMA(0, 1, At, B1); PG8_BAR; PG8_SCHED;
;             PG8_LDA(At, 1, 1); PG8_STAGE(PG8_SB(1, 0), b3, voffB); PG8_STAGE(PG8_SB(1, 1), b3 + hstep, voffB); PG8_STAGE(PG8_SA(1, 0), a3, voffA);
;             PG8_WAIT_V(8); PG8_WAIT_L(0); PG8_BAR; PG8_MMA(1, 0, At, B0); PG8_MMA(1, 1, At, B1); PG8_BAR; PG8_SCHED;
	v_mfma_f32_16x16x32_bf16 v[62:65], v[152:155], v[188:191], v[62:65]
	v_mfma_f32_16x16x32_bf16 v[58:61], v[160:163], v[188:191], v[58:61]
	v_mfma_f32_16x16x32_bf16 v[46:49], v[152:155], v[196:199], v[46:49]
	v_mfma_f32_16x16x32_bf16 v[42:45], v[160:163], v[196:199], v[42:45]
	v_mfma_f32_16x16x32_bf16 v[30:33], v[152:155], v[204:207], v[30:33]
	v_mfma_f32_16x16x32_bf16 v[26:29], v[160:163], v[204:207], v[26:29]
	v_mfma_f32_16x16x32_bf16 v[14:17], v[152:155], v[212:215], v[14:17]
	v_mfma_f32_16x16x32_bf16 v[10:13], v[160:163], v[212:215], v[10:13]
	v_mfma_f32_16x16x32_bf16 v[62:65], v[156:159], v[192:195], v[62:65]
	v_mfma_f32_16x16x32_bf16 v[58:61], v[168:171], v[192:195], v[58:61]
	v_mfma_f32_16x16x32_bf16 v[46:49], v[156:159], v[200:203], v[46:49]
	v_mfma_f32_16x16x32_bf16 v[42:45], v[168:171], v[200:203], v[42:45]
	v_mfma_f32_16x16x32_bf16 v[30:33], v[156:159], v[208:211], v[30:33]
	v_mfma_f32_16x16x32_bf16 v[26:29], v[168:171], v[208:211], v[26:29]
	v_mfma_f32_16x16x32_bf16 v[14:17], v[156:159], v[216:219], v[14:17]
	v_mfma_f32_16x16x32_bf16 v[10:13], v[168:171], v[216:219], v[10:13]
	v_mfma_f32_16x16x32_bf16 v[54:57], v[172:175], v[188:191], v[54:57]
	v_mfma_f32_16x16x32_bf16 v[50:53], v[180:183], v[188:191], v[50:53]
	v_mfma_f32_16x16x32_bf16 v[38:41], v[172:175], v[196:199], v[38:41]
	v_mfma_f32_16x16x32_bf16 v[34:37], v[180:183], v[196:199], v[34:37]
	v_mfma_f32_16x16x32_bf16 v[22:25], v[172:175], v[204:207], v[22:25]
	v_mfma_f32_16x16x32_bf16 v[18:21], v[180:183], v[204:207], v[18:21]
	v_mfma_f32_16x16x32_bf16 v[6:9], v[172:175], v[212:215], v[6:9]
	v_mfma_f32_16x16x32_bf16 v[2:5], v[180:183], v[212:215], v[2:5]
	v_mfma_f32_16x16x32_bf16 v[54:57], v[176:179], v[192:195], v[54:57]
	v_mfma_f32_16x16x32_bf16 v[50:53], v[184:187], v[192:195], v[50:53]
	v_mfma_f32_16x16x32_bf16 v[38:41], v[176:179], v[200:203], v[38:41]
	v_mfma_f32_16x16x32_bf16 v[34:37], v[184:187], v[200:203], v[34:37]
	v_mfma_f32_16x16x32_bf16 v[22:25], v[176:179], v[208:211], v[22:25]
	v_mfma_f32_16x16x32_bf16 v[18:21], v[184:187], v[208:211], v[18:21]
	v_mfma_f32_16x16x32_bf16 v[6:9], v[176:179], v[216:219], v[6:9]
	v_mfma_f32_16x16x32_bf16 v[2:5], v[184:187], v[216:219], v[2:5]
	s_barrier
	s_setprio 0
	s_add_i32 s53, 0, 0x18000
	s_add_i32 s54, 0, 0x1c000
	v_add_u32_e32 v168, s53, v150
	v_add_u32_e32 v184, s54, v150
	ds_read_b128 v[152:155], v168
	ds_read_b128 v[156:159], v168 offset:1024
	ds_read_b128 v[160:163], v168 offset:2048
	ds_read_b128 v[168:171], v168 offset:3072
	ds_read_b128 v[172:175], v184
	ds_read_b128 v[176:179], v184 offset:1024
	ds_read_b128 v[180:183], v184 offset:2048
	ds_read_b128 v[184:187], v184 offset:3072
	s_add_u32 s28, s28, 0xb0000
	s_addc_u32 s29, s29, 0
	s_mov_b32 m0, s40
	v_lshl_add_u64 v[226:227], s[28:29], 0, v[130:131]
	ds_read_b128 v[188:191], v151 offset:32768
	ds_read_b128 v[192:195], v151 offset:33792
	ds_read_b128 v[196:199], v151 offset:34816
	ds_read_b128 v[200:203], v151 offset:35840
	ds_read_b128 v[204:207], v151 offset:36864
	ds_read_b128 v[208:211], v151 offset:37888
	ds_read_b128 v[212:215], v151 offset:38912
	ds_read_b128 v[216:219], v151 offset:39936
	global_load_lds_dwordx4 v[226:227], off
	v_lshl_add_u64 v[226:227], s[28:29], 0, v[134:135]
	s_mov_b32 m0, s41
	s_nop 0
	global_load_lds_dwordx4 v[226:227], off
	s_waitcnt vmcnt(8)
	s_waitcnt lgkmcnt(0)
	s_setprio 3
	s_barrier
	v_mfma_f32_16x16x32_bf16 v[102:105], v[152:155], v[188:191], v[102:105]
	v_mfma_f32_16x16x32_bf16 v[106:109], v[160:163], v[188:191], v[106:109]
	v_mfma_f32_16x16x32_bf16 v[114:117], v[152:155], v[196:199], v[114:117]
	v_mfma_f32_16x16x32_bf16 v[118:121], v[160:163], v[196:199], v[118:121]
	v_mfma_f32_16x16x32_bf16 v[126:129], v[152:155], v[204:207], v[126:129]
	v_mfma_f32_16x16x32_bf16 v[122:125], v[160:163], v[204:207], v[122:125]
	v_mfma_f32_16x16x32_bf16 v[78:81], v[152:155], v[212:215], v[78:81]
	v_mfma_f32_16x16x32_bf16 v[74:77], v[160:163], v[212:215], v[74:77]
	v_mfma_f32_16x16x32_bf16 v[102:105], v[156:159], v[192:195], v[102:105]
	v_mfma_f32_16x16x32_bf16 v[106:109], v[168:171], v[192:195], v[106:109]
	v_mfma_f32_16x16x32_bf16 v[114:117], v[156:159], v[200:203], v[114:117]
	v_mfma_f32_16x16x32_bf16 v[118:121], v[168:171], v[200:203], v[118:121]
	v_mfma_f32_16x16x32_bf16 v[126:129], v[156:159], v[208:211], v[126:129]
	v_mfma_f32_16x16x32_bf16 v[122:125], v[168:171], v[208:211], v[122:125]
	v_mfma_f32_16x16x32_bf16 v[78:81], v[156:159], v[216:219], v[78:81]
	v_mfma_f32_16x16x32_bf16 v[74:77], v[168:171], v[216:219], v[74:77]
	v_mfma_f32_16x16x32_bf16 v[86:89], v[172:175], v[188:191], v[86:89]
	v_mfma_f32_16x16x32_bf16 v[82:85], v[180:183], v[188:191], v[82:85]
	v_mfma_f32_16x16x32_bf16 v[94:97], v[172:175], v[196:199], v[94:97]
	v_mfma_f32_16x16x32_bf16 v[90:93], v[180:183], v[196:199], v[90:93]
	v_mfma_f32_16x16x32_bf16 v[110:113], v[172:175], v[204:207], v[110:113]
	v_mfma_f32_16x16x32_bf16 v[98:101], v[180:183], v[204:207], v[98:101]
	v_mfma_f32_16x16x32_bf16 v[70:73], v[172:175], v[212:215], v[70:73]
	v_mfma_f32_16x16x32_bf16 v[66:69], v[180:183], v[212:215], v[66:69]
	v_mfma_f32_16x16x32_bf16 v[86:89], v[176:179], v[192:195], v[86:89]
	v_mfma_f32_16x16x32_bf16 v[82:85], v[184:187], v[192:195], v[82:85]
	v_mfma_f32_16x16x32_bf16 v[94:97], v[176:179], v[200:203], v[94:97]
	v_mfma_f32_16x16x32_bf16 v[90:93], v[184:187], v[200:203], v[90:93]
	v_mfma_f32_16x16x32_bf16 v[110:113], v[176:179], v[208:211], v[110:113]
	v_mfma_f32_16x16x32_bf16 v[98:101], v[184:187], v[208:211], v[98:101]
	v_mfma_f32_16x16x32_bf16 v[70:73], v[176:179], v[216:219], v[70:73]
	v_mfma_f32_16x16x32_bf16 v[66:69], v[184:187], v[216:219], v[66:69]
	s_barrier
; #define PG8_STAGE(bufoff, gbase, voff) do { _Pragma("unroll") for (int _i = 0; _i < 2; ++_i) \
;         __builtin_amdgcn_global_load_lds((const unsigned*)((const char*)(gbase) + (voff)[_i]), (PG8_LAS unsigned*)(lds + (bufoff) + ldsw + _i * 8192), 16, 0, 0); } while (0)
; #define PG8_LDA(dst, b, h) do { _Pragma("unroll") for (int m = 0; m < 4; ++m) _Pragma("unroll") for (int k = 0; k < 2; ++k) dst[m][k] = *(const PG8_LAS bf16x8*)(lds + PG8_SA(b, h) + aoff + m * 2048 + k * 1024); } while (0)
; #define PG8_LDB(dst, b, h) do { _Pragma("unroll") for (int n = 0; n < 2; ++n) _Pragma("unroll") for (int k = 0; k < 2; ++k) dst[n][k] = *(const PG8_LAS bf16x8*)(lds + PG8_SB(b, h) + boff + n * 2048 + k * 1024); } while (0)
; #define PG8_BAR __builtin_amdgcn_s_barrier()
; template <class Epi, class Sched, bool ALIGN_EPI = false, bool SP2 = false, bool PAIR_ACC = false>
; __device__ __forceinline__ void gemm_phase(PG8_LAS unsigned char* lds, const Gemm g, const Sched& S, const Epi& E) {
;     ...
;             if constexpr (SP2) {
;             PG8_LDB(B0, 0, 0); PG8_LDB(B1, 0, 1); PG8_SCHED; PG8_LDA(At, 0, 0); PG8_STAGE(PG8_SA(1, 1), a1 + hstep, voffA);
;             PG8_WAIT_V(8); PG8_WAIT_L(0); PG8_BAR; PG8_MMA(0, 0, At, B0); PG8_MMA(0, 1, At, B1); PG8_BAR; PG8_SCHED;
;             PG8_LDA(At, 0, 1); PG8_STAGE(PG8_SB(0, 0), b2, voffB); PG8_STAGE(PG8_SB(0, 1), b2 + hstep, voffB); PG8_STAGE(PG8_SA(0, 0), a2, voffA);
;             PG8_WAIT_V(8); PG8_WAIT_L(0); PG8_BAR; PG8_MMA(1, 0, At, B0); PG8_MMA(1, 1, At, B1); PG8_BAR; PG8_SCHED;
;             PG8_LDB(B0, 1, 0); PG8_LDB(B1, 1, 1); PG8_SCHED; PG8_LDA(At, 1, 0); PG8_STAGE(PG8_SA(0, 1), a2 + hstep, voffA);
;             PG8_WAIT_V(8); PG8_WAIT_L(0); PG8_BAR; PG8_MMA(0, 0, At, B0); PG8_MMA(0, 1, At, B1); PG8_BAR; PG8_SCHED;
;             PG8_LDA(At, 1, 1); PG8_STAGE(PG8_SB(1, 0), b3, voffB); PG8_STAGE(PG8_SB(1, 1), b3 + hstep, voffB); PG8_STAGE(PG8_SA(1, 0), a3, voffA);
;             PG8_WAIT_V(8); PG8_WAIT_L(0); PG8_BAR; PG8_MMA(1, 0, At, B0); PG8_MMA(1, 1, At, B1); PG8_BAR; PG8_SCHED;
;     ...
;         if (!(PAIR_ACC && cur.pn < 4)) {
; #pragma unroll
;         for (int a = 0; a < 2; ++a)
; #pragma unroll
;             for (int b = 0; b < 2; ++b)
; #pragma unroll
;                 for (int m = 0; m < 4; ++m)
; #pragma unroll
;                     for (int n = 0; n < 2; ++n) acc[a][b][m][n] = (f32x4){0.f, 0.f, 0.f, 0.f};
	s_setprio 0
	s_add_i32 s28, s53, s37
	v_lshl_add_u64 v[164:165], v[164:165], 0, s[20:21]
	s_mov_b32 m0, s28
	ds_read_b128 v[188:191], v151 offset:49152
	ds_read_b128 v[192:195], v151 offset:50176
	ds_read_b128 v[196:199], v151 offset:51200
	ds_read_b128 v[200:203], v151 offset:52224
	ds_read_b128 v[204:207], v151 offset:53248
	ds_read_b128 v[208:211], v151 offset:54272
	ds_read_b128 v[212:215], v151 offset:55296
	ds_read_b128 v[216:219], v151 offset:56320
	global_load_lds_dwordx4 v[164:165], off
	s_add_i32 m0, s28, 0x2000
	s_add_u32 s26, s26, 0xb0080
	v_lshl_add_u64 v[164:165], v[220:221], 0, s[20:21]
	s_addc_u32 s27, s27, 0
	s_add_i32 s28, s54, s37
	global_load_lds_dwordx4 v[164:165], off
	v_lshl_add_u64 v[164:165], s[26:27], 0, v[132:133]
	s_mov_b32 m0, s28
	s_nop 0
	global_load_lds_dwordx4 v[164:165], off
	v_lshl_add_u64 v[164:165], s[26:27], 0, v[136:137]
	s_add_i32 m0, s28, 0x2000
	s_nop 0
	global_load_lds_dwordx4 v[164:165], off
	v_lshl_add_u64 v[164:165], v[222:223], 0, s[20:21]
	s_mov_b32 m0, s43
	s_nop 0
	global_load_lds_dwordx4 v[164:165], off
	v_lshl_add_u64 v[164:165], v[224:225], 0, s[20:21]
	s_mov_b32 m0, s44
	s_nop 0
	global_load_lds_dwordx4 v[164:165], off
	s_waitcnt vmcnt(8)
	s_waitcnt lgkmcnt(0)
	s_setprio 3
	s_barrier
	v_mfma_f32_16x16x32_bf16 v[62:65], v[152:155], v[188:191], v[62:65]
	v_mfma_f32_16x16x32_bf16 v[58:61], v[160:163], v[188:191], v[58:61]
	v_mfma_f32_16x16x32_bf16 v[46:49], v[152:155], v[196:199], v[46:49]
	v_mfma_f32_16x16x32_bf16 v[42:45], v[160:163], v[196:199], v[42:45]
	v_mfma_f32_16x16x32_bf16 v[30:33], v[152:155], v[204:207], v[30:33]
	v_mfma_f32_16x16x32_bf16 v[26:29], v[160:163], v[204:207], v[26:29]
	v_mfma_f32_16x16x32_bf16 v[14:17], v[152:155], v[212:215], v[14:17]
	v_mfma_f32_16x16x32_bf16 v[10:13], v[160:163], v[212:215], v[10:13]
	v_mfma_f32_16x16x32_bf16 v[62:65], v[156:159], v[192:195], v[62:65]
	v_mfma_f32_16x16x32_bf16 v[58:61], v[168:171], v[192:195], v[58:61]
	v_mfma_f32_16x16x32_bf16 v[46:49], v[156:159], v[200:203], v[46:49]
	v_mfma_f32_16x16x32_bf16 v[42:45], v[168:171], v[200:203], v[42:45]
	v_mfma_f32_16x16x32_bf16 v[30:33], v[156:159], v[208:211], v[30:33]
	v_mfma_f32_16x16x32_bf16 v[26:29], v[168:171], v[208:211], v[26:29]
	v_mfma_f32_16x16x32_bf16 v[14:17], v[156:159], v[216:219], v[14:17]
	v_mfma_f32_16x16x32_bf16 v[10:13], v[168:171], v[216:219], v[10:13]
	v_mfma_f32_16x16x32_bf16 v[54:57], v[172:175], v[188:191], v[54:57]
	v_mfma_f32_16x16x32_bf16 v[50:53], v[180:183], v[188:191], v[50:53]
	v_mfma_f32_16x16x32_bf16 v[38:41], v[172:175], v[196:199], v[38:41]
	v_mfma_f32_16x16x32_bf16 v[34:37], v[180:183], v[196:199], v[34:37]
	v_mfma_f32_16x16x32_bf16 v[22:25], v[172:175], v[204:207], v[22:25]
	v_mfma_f32_16x16x32_bf16 v[18:21], v[180:183], v[204:207], v[18:21]
	v_mfma_f32_16x16x32_bf16 v[6:9], v[172:175], v[212:215], v[6:9]
	v_mfma_f32_16x16x32_bf16 v[2:5], v[180:183], v[212:215], v[2:5]
	v_mfma_f32_16x16x32_bf16 v[54:57], v[176:179], v[192:195], v[54:57]
	v_mfma_f32_16x16x32_bf16 v[50:53], v[184:187], v[192:195], v[50:53]
	v_mfma_f32_16x16x32_bf16 v[38:41], v[176:179], v[200:203], v[38:41]
	v_mfma_f32_16x16x32_bf16 v[34:37], v[184:187], v[200:203], v[34:37]
	v_mfma_f32_16x16x32_bf16 v[22:25], v[176:179], v[208:211], v[22:25]
	v_mfma_f32_16x16x32_bf16 v[18:21], v[184:187], v[208:211], v[18:21]
	v_mfma_f32_16x16x32_bf16 v[6:9], v[176:179], v[216:219], v[6:9]
	v_mfma_f32_16x16x32_bf16 v[2:5], v[184:187], v[216:219], v[2:5]
	s_barrier
	s_setprio 0
	s_add_i32 s52, s52, 2
	s_add_u32 s24, s24, 0x100
	s_addc_u32 s25, s25, 0
	s_cmp_gt_u32 s52, 41
	s_cbranch_scc0 .LBB0_1840
	s_add_u32 s24, s50, 0xffffff00
	s_addc_u32 s25, s51, -1
	s_and_b64 vcc, exec, s[6:7]
	s_cbranch_vccnz .LBB0_1827
	v_mov_b32_e32 v2, 0
	s_mov_b32 s14, s47
	s_mov_b32 s31, s48
	s_mov_b64 s[18:19], s[22:23]
	s_mov_b32 s42, s49
	v_mov_b32_e32 v3, v2
	v_mov_b32_e32 v4, v2
	v_mov_b32_e32 v5, v2
	v_mov_b32_e32 v6, v2
	v_mov_b32_e32 v7, v2
	v_mov_b32_e32 v8, v2
	v_mov_b32_e32 v9, v2
	v_mov_b32_e32 v18, v2
	v_mov_b32_e32 v19, v2
	v_mov_b32_e32 v20, v2
	v_mov_b32_e32 v21, v2
	v_mov_b32_e32 v22, v2
	v_mov_b32_e32 v23, v2
	v_mov_b32_e32 v24, v2
	v_mov_b32_e32 v25, v2
	v_mov_b32_e32 v34, v2
	v_mov_b32_e32 v35, v2
	v_mov_b32_e32 v36, v2
	v_mov_b32_e32 v37, v2
	v_mov_b32_e32 v38, v2
	v_mov_b32_e32 v39, v2
	v_mov_b32_e32 v40, v2
	v_mov_b32_e32 v41, v2
	v_mov_b32_e32 v50, v2
	v_mov_b32_e32 v51, v2
	v_mov_b32_e32 v52, v2
	v_mov_b32_e32 v53, v2
	v_mov_b32_e32 v54, v2
	v_mov_b32_e32 v55, v2
	v_mov_b32_e32 v56, v2
	v_mov_b32_e32 v57, v2
	v_mov_b32_e32 v10, v2
	v_mov_b32_e32 v11, v2
	v_mov_b32_e32 v12, v2
	v_mov_b32_e32 v13, v2
	v_mov_b32_e32 v14, v2
	v_mov_b32_e32 v15, v2
	v_mov_b32_e32 v16, v2
	v_mov_b32_e32 v17, v2
	v_mov_b32_e32 v26, v2
	v_mov_b32_e32 v27, v2
	v_mov_b32_e32 v28, v2
	v_mov_b32_e32 v29, v2
	v_mov_b32_e32 v30, v2
	v_mov_b32_e32 v31, v2
	v_mov_b32_e32 v32, v2
	v_mov_b32_e32 v33, v2
	v_mov_b32_e32 v42, v2
	v_mov_b32_e32 v43, v2
	v_mov_b32_e32 v44, v2
	v_mov_b32_e32 v45, v2
	v_mov_b32_e32 v46, v2
	v_mov_b32_e32 v47, v2
	v_mov_b32_e32 v48, v2
	v_mov_b32_e32 v49, v2
	v_mov_b32_e32 v58, v2
	v_mov_b32_e32 v59, v2
	v_mov_b32_e32 v60, v2
	v_mov_b32_e32 v61, v2
	v_mov_b32_e32 v62, v2
	v_mov_b32_e32 v63, v2
	v_mov_b32_e32 v64, v2
	v_mov_b32_e32 v65, v2
	v_mov_b32_e32 v66, v2
	v_mov_b32_e32 v67, v2
	v_mov_b32_e32 v68, v2
	v_mov_b32_e32 v69, v2
	v_mov_b32_e32 v70, v2
	v_mov_b32_e32 v71, v2
	v_mov_b32_e32 v72, v2
	v_mov_b32_e32 v73, v2
	v_mov_b32_e32 v98, v2
	v_mov_b32_e32 v99, v2
	v_mov_b32_e32 v100, v2
	v_mov_b32_e32 v101, v2
	v_mov_b32_e32 v110, v2
	v_mov_b32_e32 v111, v2
	v_mov_b32_e32 v112, v2
	v_mov_b32_e32 v113, v2
	v_mov_b32_e32 v90, v2
	v_mov_b32_e32 v91, v2
	v_mov_b32_e32 v92, v2
	v_mov_b32_e32 v93, v2
	v_mov_b32_e32 v94, v2
	v_mov_b32_e32 v95, v2
	v_mov_b32_e32 v96, v2
	v_mov_b32_e32 v97, v2
	v_mov_b32_e32 v82, v2
	v_mov_b32_e32 v83, v2
	v_mov_b32_e32 v84, v2
	v_mov_b32_e32 v85, v2
	v_mov_b32_e32 v86, v2
	v_mov_b32_e32 v87, v2
	v_mov_b32_e32 v88, v2
	v_mov_b32_e32 v89, v2
	v_mov_b32_e32 v74, v2
	v_mov_b32_e32 v75, v2
	v_mov_b32_e32 v76, v2
	v_mov_b32_e32 v77, v2
	v_mov_b32_e32 v78, v2
	v_mov_b32_e32 v79, v2
	v_mov_b32_e32 v80, v2
	v_mov_b32_e32 v81, v2
	v_mov_b32_e32 v122, v2
	v_mov_b32_e32 v123, v2
	v_mov_b32_e32 v124, v2
	v_mov_b32_e32 v125, v2
	v_mov_b32_e32 v126, v2
	v_mov_b32_e32 v127, v2
	v_mov_b32_e32 v128, v2
	v_mov_b32_e32 v129, v2
	v_mov_b32_e32 v118, v2
	v_mov_b32_e32 v119, v2
	v_mov_b32_e32 v120, v2
	v_mov_b32_e32 v121, v2
	v_mov_b32_e32 v114, v2
	v_mov_b32_e32 v115, v2
	v_mov_b32_e32 v116, v2
	v_mov_b32_e32 v117, v2
	v_mov_b32_e32 v106, v2
	v_mov_b32_e32 v107, v2
	v_mov_b32_e32 v108, v2
	v_mov_b32_e32 v109, v2
	v_mov_b32_e32 v102, v2
	v_mov_b32_e32 v103, v2
	v_mov_b32_e32 v104, v2
	v_mov_b32_e32 v105, v2
	s_andn2_b64 vcc, exec, s[0:1]
	s_cbranch_vccnz .LBB0_1828
